# stack6 with inverted GEMM K-loop priority: load/staging phase at prio 1, MFMA phase at prio 0 (instead of waves 4-7 statically high)
# baseline (speedup 1.0000x reference)
; #define PG8_STAGE(bufoff, gbase, voff) do { _Pragma("unroll") for (int _i = 0; _i < 2; ++_i) \
;         __builtin_amdgcn_global_load_lds((const unsigned*)((const char*)(gbase) + (voff)[_i]), (PG8_LAS unsigned*)(lds + (bufoff) + ldsw + _i * 8192), 16, 0, 0); } while (0)
; #define PG8_LDA(dst, b, h) do { _Pragma("unroll") for (int m = 0; m < 4; ++m) _Pragma("unroll") for (int k = 0; k < 2; ++k) dst[m][k] = *(const PG8_LAS bf16x8*)(lds + PG8_SA(b, h) + aoff + m * 2048 + k * 1024); } while (0)
; #define PG8_LDB(dst, b, h) do { _Pragma("unroll") for (int n = 0; n < 2; ++n) _Pragma("unroll") for (int k = 0; k < 2; ++k) dst[n][k] = *(const PG8_LAS bf16x8*)(lds + PG8_SB(b, h) + boff + n * 2048 + k * 1024); } while (0)
; #define PG8_WAIT_V(n) asm volatile("s_waitcnt vmcnt(" #n ")" ::: "memory")
; #define PG8_WAIT_L(n) asm volatile("s_waitcnt lgkmcnt(" #n ")" ::: "memory")
; template <class Epi, class Sched, bool ALIGN_EPI = false, bool SP2 = false>
; __device__ __forceinline__ void gemm_phase(PG8_LAS unsigned char* lds, const Gemm g, const Sched& S, const Epi& E, int wid_in) {
;     ...
;     for (;;) {
;         const bool has_next = S.next(ui + 1, nxt);
;         const char* nA = has_next ? (const char*)g.A + (size_t)nxt.pm * tstep + (size_t)nxt.kt0 * kstep : cA; const char* nB = has_next ? (const char*)g.Bt + (size_t)nxt.pn * tstep + (size_t)nxt.kt0 * kstep : cB;
;         const int nt = cur.nkt;
;         for (int t = 0; t < nt; t += 2) {
;             const bool last = (t == nt - 2);
;             const char* a1 = cA + (size_t)(t + 1) * kstep;
;             const char* a2 = last ? nA : cA + (size_t)(t + 2) * kstep; const char* b2 = last ? nB : cB + (size_t)(t + 2) * kstep;
;             const char* a3 = a2 + kstep; const char* b3 = b2 + kstep;
;             if (last && has_next) S.a_ready(nxt);
;             if constexpr (SP2) {
;             PG8_LDB(B0, 0, 0); PG8_LDB(B1, 0, 1); PG8_SCHED; PG8_LDA(At, 0, 0); PG8_STAGE(PG8_SA(1, 1), a1 + hstep, voffA);
;             PG8_WAIT_V(8); PG8_WAIT_L(0); PG8_BAR; PG8_MMA(0, 0, At, B0); PG8_MMA(0, 1, At, B1); PG8_BAR; PG8_SCHED;
;     ...
; #pragma unroll
;         for (int a = 0; a < 2; ++a)
; #pragma unroll
;             for (int b = 0; b < 2; ++b)
; #pragma unroll
;                 for (int m = 0; m < 4; ++m)
; #pragma unroll
;                     for (int n = 0; n < 2; ++n) acc[a][b][m][n] = (f32x4){0.f, 0.f, 0.f, 0.f};
.LBB0_277:
	s_ashr_i32 s19, s18, 31
	s_lshl_b64 s[22:23], s[18:19], 20
	s_add_u32 s22, s0, s22
	s_addc_u32 s23, s1, s23
	s_and_b64 s[24:25], s[20:21], exec
	s_cselect_b32 s11, s23, s27
	s_cselect_b32 s19, s22, s26
	s_ashr_i32 s17, s16, 31
	s_lshl_b64 s[24:25], s[16:17], 20
	s_add_u32 s24, s34, s24
	s_addc_u32 s25, s35, s25
	s_and_b64 s[30:31], s[20:21], exec
	s_cselect_b32 s17, s25, s29
	s_cselect_b32 s62, s24, s28
	s_add_u32 s64, s28, 0x100
	s_addc_u32 s65, s29, 0
	s_add_u32 s26, s26, 0x80080
	v_mov_b32_e32 v2, 0
	s_addc_u32 s27, s27, 0
	s_mov_b32 s63, -2
	v_mov_b32_e32 v3, v2
	v_mov_b32_e32 v4, v2
	v_mov_b32_e32 v5, v2
	v_mov_b32_e32 v6, v2
	v_mov_b32_e32 v7, v2
	v_mov_b32_e32 v8, v2
	v_mov_b32_e32 v9, v2
	v_mov_b32_e32 v10, v2
	v_mov_b32_e32 v11, v2
	v_mov_b32_e32 v12, v2
	v_mov_b32_e32 v13, v2
	v_mov_b32_e32 v14, v2
	v_mov_b32_e32 v15, v2
	v_mov_b32_e32 v16, v2
	v_mov_b32_e32 v17, v2
	v_mov_b32_e32 v26, v2
	v_mov_b32_e32 v27, v2
	v_mov_b32_e32 v28, v2
	v_mov_b32_e32 v29, v2
	v_mov_b32_e32 v30, v2
	v_mov_b32_e32 v31, v2
	v_mov_b32_e32 v32, v2
	v_mov_b32_e32 v33, v2
	v_mov_b32_e32 v42, v2
	v_mov_b32_e32 v43, v2
	v_mov_b32_e32 v44, v2
	v_mov_b32_e32 v45, v2
	v_mov_b32_e32 v46, v2
	v_mov_b32_e32 v47, v2
	v_mov_b32_e32 v48, v2
	v_mov_b32_e32 v49, v2
	v_mov_b32_e32 v18, v2
	v_mov_b32_e32 v19, v2
	v_mov_b32_e32 v20, v2
	v_mov_b32_e32 v21, v2
	v_mov_b32_e32 v22, v2
	v_mov_b32_e32 v23, v2
	v_mov_b32_e32 v24, v2
	v_mov_b32_e32 v25, v2
	v_mov_b32_e32 v34, v2
	v_mov_b32_e32 v35, v2
	v_mov_b32_e32 v36, v2
	v_mov_b32_e32 v37, v2
	v_mov_b32_e32 v38, v2
	v_mov_b32_e32 v39, v2
	v_mov_b32_e32 v40, v2
	v_mov_b32_e32 v41, v2
	v_mov_b32_e32 v50, v2
	v_mov_b32_e32 v51, v2
	v_mov_b32_e32 v52, v2
	v_mov_b32_e32 v53, v2
	v_mov_b32_e32 v54, v2
	v_mov_b32_e32 v55, v2
	v_mov_b32_e32 v56, v2
	v_mov_b32_e32 v57, v2
	v_mov_b32_e32 v58, v2
	v_mov_b32_e32 v59, v2
	v_mov_b32_e32 v60, v2
	v_mov_b32_e32 v61, v2
	v_mov_b32_e32 v62, v2
	v_mov_b32_e32 v63, v2
	v_mov_b32_e32 v64, v2
	v_mov_b32_e32 v65, v2
	v_mov_b32_e32 v66, v2
	v_mov_b32_e32 v67, v2
	v_mov_b32_e32 v68, v2
	v_mov_b32_e32 v69, v2
	v_mov_b32_e32 v70, v2
	v_mov_b32_e32 v71, v2
	v_mov_b32_e32 v72, v2
	v_mov_b32_e32 v73, v2
	v_mov_b32_e32 v74, v2
	v_mov_b32_e32 v75, v2
	v_mov_b32_e32 v76, v2
	v_mov_b32_e32 v77, v2
	v_mov_b32_e32 v78, v2
	v_mov_b32_e32 v79, v2
	v_mov_b32_e32 v80, v2
	v_mov_b32_e32 v81, v2
	v_mov_b32_e32 v90, v2
	v_mov_b32_e32 v91, v2
	v_mov_b32_e32 v92, v2
	v_mov_b32_e32 v93, v2
	v_mov_b32_e32 v94, v2
	v_mov_b32_e32 v95, v2
	v_mov_b32_e32 v96, v2
	v_mov_b32_e32 v97, v2
	v_mov_b32_e32 v106, v2
	v_mov_b32_e32 v107, v2
	v_mov_b32_e32 v108, v2
	v_mov_b32_e32 v109, v2
	v_mov_b32_e32 v110, v2
	v_mov_b32_e32 v111, v2
	v_mov_b32_e32 v112, v2
	v_mov_b32_e32 v113, v2
	v_mov_b32_e32 v82, v2
	v_mov_b32_e32 v83, v2
	v_mov_b32_e32 v84, v2
	v_mov_b32_e32 v85, v2
	v_mov_b32_e32 v86, v2
	v_mov_b32_e32 v87, v2
	v_mov_b32_e32 v88, v2
	v_mov_b32_e32 v89, v2
	v_mov_b32_e32 v98, v2
	v_mov_b32_e32 v99, v2
	v_mov_b32_e32 v100, v2
	v_mov_b32_e32 v101, v2
	v_mov_b32_e32 v102, v2
	v_mov_b32_e32 v103, v2
	v_mov_b32_e32 v104, v2
	v_mov_b32_e32 v105, v2
	v_mov_b32_e32 v114, v2
	v_mov_b32_e32 v115, v2
	v_mov_b32_e32 v116, v2
	v_mov_b32_e32 v117, v2
	v_mov_b32_e32 v118, v2
	v_mov_b32_e32 v119, v2
	v_mov_b32_e32 v120, v2
	v_mov_b32_e32 v121, v2
	v_mov_b32_e32 v122, v2
	v_mov_b32_e32 v123, v2
	v_mov_b32_e32 v124, v2
	v_mov_b32_e32 v125, v2
	v_mov_b32_e32 v126, v2
	v_mov_b32_e32 v127, v2
	v_mov_b32_e32 v128, v2
	v_mov_b32_e32 v129, v2
	s_setprio 1
.Lprio_skip_0:
.LBB0_278:
	s_add_u32 s28, s26, 0xfff80080
	s_addc_u32 s29, s27, -1
	s_add_i32 s40, 0, 0x10000
	s_cmp_eq_u32 s63, 28
	s_cselect_b32 s31, s11, s29
	s_cselect_b32 s30, s19, s28
	s_cselect_b32 s29, s17, s65
	s_cselect_b32 s28, s62, s64
	s_add_i32 s41, 0, 0x14000
	v_add_u32_e32 v154, s40, v140
	v_add_u32_e32 v170, s41, v140
	ds_read_b128 v[142:145], v154
	ds_read_b128 v[146:149], v154 offset:1024
	ds_read_b128 v[150:153], v154 offset:2048
	ds_read_b128 v[154:157], v154 offset:3072
	ds_read_b128 v[158:161], v170
	ds_read_b128 v[162:165], v170 offset:1024
	ds_read_b128 v[166:169], v170 offset:2048
	ds_read_b128 v[170:173], v170 offset:3072
	v_lshl_add_u64 v[220:221], s[26:27], 0, v[138:139]
	s_add_i32 m0, s13, 0xc000
	ds_read_b128 v[174:177], v141
	ds_read_b128 v[178:181], v141 offset:1024
	ds_read_b128 v[182:185], v141 offset:2048
	ds_read_b128 v[186:189], v141 offset:3072
	ds_read_b128 v[190:193], v141 offset:4096
	ds_read_b128 v[208:211], v141 offset:5120
	ds_read_b128 v[212:215], v141 offset:6144
	ds_read_b128 v[216:219], v141 offset:7168
	global_load_lds_dwordx4 v[220:221], off
	v_lshl_add_u64 v[220:221], s[26:27], 0, v[136:137]
	s_add_i32 m0, s13, 0xe000
	s_nop 0
	global_load_lds_dwordx4 v[220:221], off
	s_waitcnt vmcnt(8)
	s_waitcnt lgkmcnt(0)
	s_barrier
; #define PG8_STAGE(bufoff, gbase, voff) do { _Pragma("unroll") for (int _i = 0; _i < 2; ++_i) \
;         __builtin_amdgcn_global_load_lds((const unsigned*)((const char*)(gbase) + (voff)[_i]), (PG8_LAS unsigned*)(lds + (bufoff) + ldsw + _i * 8192), 16, 0, 0); } while (0)
; #define PG8_LDA(dst, b, h) do { _Pragma("unroll") for (int m = 0; m < 4; ++m) _Pragma("unroll") for (int k = 0; k < 2; ++k) dst[m][k] = *(const PG8_LAS bf16x8*)(lds + PG8_SA(b, h) + aoff + m * 2048 + k * 1024); } while (0)
; #define PG8_MMA(ai, bj, At, Bt) do { __builtin_amdgcn_s_setprio(1); _Pragma("unroll") for (int m = 0; m < 4; ++m) _Pragma("unroll") for (int n = 0; n < 2; ++n) _Pragma("unroll") for (int k = 0; k < 2; ++k) \
;         acc[ai][bj][m][n] = __builtin_amdgcn_mfma_f32_16x16x32_bf16(Bt[n][k], At[m][k], acc[ai][bj][m][n], 0, 0, 0); __builtin_amdgcn_s_setprio(0); } while (0)
; #define PG8_WAIT_V(n) asm volatile("s_waitcnt vmcnt(" #n ")" ::: "memory")
; #define PG8_WAIT_L(n) asm volatile("s_waitcnt lgkmcnt(" #n ")" ::: "memory")
; #define PG8_BAR __builtin_amdgcn_s_barrier()
; #define PG8_SCHED __builtin_amdgcn_sched_barrier(0)
; template <class Epi, class Sched, bool ALIGN_EPI = false, bool SP2 = false>
; __device__ __forceinline__ void gemm_phase(PG8_LAS unsigned char* lds, const Gemm g, const Sched& S, const Epi& E, int wid_in) {
;     ...
;             PG8_WAIT_V(8); PG8_WAIT_L(0); PG8_BAR; PG8_MMA(0, 0, At, B0); PG8_MMA(0, 1, At, B1); PG8_BAR; PG8_SCHED;
;             PG8_LDA(At, 0, 1); PG8_STAGE(PG8_SB(0, 0), b2, voffB); PG8_STAGE(PG8_SB(0, 1), b2 + hstep, voffB); PG8_STAGE(PG8_SA(0, 0), a2, voffA);
;             PG8_WAIT_V(8); PG8_WAIT_L(0); PG8_BAR; PG8_MMA(1, 0, At, B0); PG8_MMA(1, 1, At, B1); PG8_BAR; PG8_SCHED;
	s_setprio 0
	s_waitcnt lgkmcnt(0)
	v_mfma_f32_16x16x32_bf16 v[126:129], v[142:145], v[174:177], v[126:129]
	v_mfma_f32_16x16x32_bf16 v[122:125], v[150:153], v[174:177], v[122:125]
	v_mfma_f32_16x16x32_bf16 v[118:121], v[142:145], v[182:185], v[118:121]
	v_mfma_f32_16x16x32_bf16 v[114:117], v[150:153], v[182:185], v[114:117]
	v_mfma_f32_16x16x32_bf16 v[102:105], v[142:145], v[190:193], v[102:105]
	v_mfma_f32_16x16x32_bf16 v[98:101], v[150:153], v[190:193], v[98:101]
	v_mfma_f32_16x16x32_bf16 v[86:89], v[142:145], v[212:215], v[86:89]
	v_mfma_f32_16x16x32_bf16 v[82:85], v[150:153], v[212:215], v[82:85]
	v_mfma_f32_16x16x32_bf16 v[126:129], v[146:149], v[178:181], v[126:129]
	v_mfma_f32_16x16x32_bf16 v[122:125], v[154:157], v[178:181], v[122:125]
	v_mfma_f32_16x16x32_bf16 v[118:121], v[146:149], v[186:189], v[118:121]
	v_mfma_f32_16x16x32_bf16 v[114:117], v[154:157], v[186:189], v[114:117]
	v_mfma_f32_16x16x32_bf16 v[102:105], v[146:149], v[208:211], v[102:105]
	v_mfma_f32_16x16x32_bf16 v[98:101], v[154:157], v[208:211], v[98:101]
	v_mfma_f32_16x16x32_bf16 v[86:89], v[146:149], v[216:219], v[86:89]
	v_mfma_f32_16x16x32_bf16 v[82:85], v[154:157], v[216:219], v[82:85]
	v_mfma_f32_16x16x32_bf16 v[110:113], v[158:161], v[174:177], v[110:113]
	v_mfma_f32_16x16x32_bf16 v[106:109], v[166:169], v[174:177], v[106:109]
	v_mfma_f32_16x16x32_bf16 v[94:97], v[158:161], v[182:185], v[94:97]
	v_mfma_f32_16x16x32_bf16 v[90:93], v[166:169], v[182:185], v[90:93]
	v_mfma_f32_16x16x32_bf16 v[78:81], v[158:161], v[190:193], v[78:81]
	v_mfma_f32_16x16x32_bf16 v[74:77], v[166:169], v[190:193], v[74:77]
	v_mfma_f32_16x16x32_bf16 v[70:73], v[158:161], v[212:215], v[70:73]
	v_mfma_f32_16x16x32_bf16 v[66:69], v[166:169], v[212:215], v[66:69]
	v_mfma_f32_16x16x32_bf16 v[110:113], v[162:165], v[178:181], v[110:113]
	v_mfma_f32_16x16x32_bf16 v[106:109], v[170:173], v[178:181], v[106:109]
	v_mfma_f32_16x16x32_bf16 v[94:97], v[162:165], v[186:189], v[94:97]
	v_mfma_f32_16x16x32_bf16 v[90:93], v[170:173], v[186:189], v[90:93]
	v_mfma_f32_16x16x32_bf16 v[78:81], v[162:165], v[208:211], v[78:81]
	v_mfma_f32_16x16x32_bf16 v[74:77], v[170:173], v[208:211], v[74:77]
	v_mfma_f32_16x16x32_bf16 v[70:73], v[162:165], v[216:219], v[70:73]
	v_mfma_f32_16x16x32_bf16 v[66:69], v[170:173], v[216:219], v[66:69]
	s_barrier
	s_setprio 1
	s_add_i32 s40, s40, s59
	v_lshl_add_u64 v[220:221], s[28:29], 0, v[0:1]
	s_mov_b32 m0, s40
	ds_read_b128 v[174:177], v141 offset:16384
	ds_read_b128 v[178:181], v141 offset:17408
	ds_read_b128 v[182:185], v141 offset:18432
	ds_read_b128 v[186:189], v141 offset:19456
	ds_read_b128 v[190:193], v141 offset:20480
	ds_read_b128 v[208:211], v141 offset:21504
	ds_read_b128 v[212:215], v141 offset:22528
	ds_read_b128 v[216:219], v141 offset:23552
	global_load_lds_dwordx4 v[220:221], off
	s_add_i32 m0, s40, 0x2000
	s_add_u32 s72, s28, 0x80000
	v_lshl_add_u64 v[222:223], s[28:29], 0, v[134:135]
	s_addc_u32 s73, s29, 0
	s_add_i32 s40, s41, s59
	global_load_lds_dwordx4 v[222:223], off
	v_lshl_add_u64 v[224:225], s[72:73], 0, v[0:1]
	s_mov_b32 m0, s40
	v_lshl_add_u64 v[226:227], s[30:31], 0, v[132:133]
	global_load_lds_dwordx4 v[224:225], off
	v_lshl_add_u64 v[224:225], s[72:73], 0, v[134:135]
	s_add_i32 m0, s40, 0x2000
	s_nop 0
	global_load_lds_dwordx4 v[224:225], off
	v_lshl_add_u64 v[224:225], s[30:31], 0, v[130:131]
	s_mov_b32 m0, s13
	s_nop 0
	global_load_lds_dwordx4 v[224:225], off
	s_mov_b32 m0, s36
	s_nop 0
	global_load_lds_dwordx4 v[226:227], off
	s_waitcnt vmcnt(8)
	s_waitcnt lgkmcnt(0)
	s_barrier
	s_setprio 0
	s_waitcnt lgkmcnt(0)
	v_mfma_f32_16x16x32_bf16 v[62:65], v[142:145], v[174:177], v[62:65]
	v_mfma_f32_16x16x32_bf16 v[58:61], v[150:153], v[174:177], v[58:61]
	v_mfma_f32_16x16x32_bf16 v[54:57], v[142:145], v[182:185], v[54:57]
	v_mfma_f32_16x16x32_bf16 v[50:53], v[150:153], v[182:185], v[50:53]
	v_mfma_f32_16x16x32_bf16 v[38:41], v[142:145], v[190:193], v[38:41]
	v_mfma_f32_16x16x32_bf16 v[34:37], v[150:153], v[190:193], v[34:37]
	v_mfma_f32_16x16x32_bf16 v[22:25], v[142:145], v[212:215], v[22:25]
	v_mfma_f32_16x16x32_bf16 v[18:21], v[150:153], v[212:215], v[18:21]
	v_mfma_f32_16x16x32_bf16 v[62:65], v[146:149], v[178:181], v[62:65]
	v_mfma_f32_16x16x32_bf16 v[58:61], v[154:157], v[178:181], v[58:61]
	v_mfma_f32_16x16x32_bf16 v[54:57], v[146:149], v[186:189], v[54:57]
	v_mfma_f32_16x16x32_bf16 v[50:53], v[154:157], v[186:189], v[50:53]
	v_mfma_f32_16x16x32_bf16 v[38:41], v[146:149], v[208:211], v[38:41]
	v_mfma_f32_16x16x32_bf16 v[34:37], v[154:157], v[208:211], v[34:37]
	v_mfma_f32_16x16x32_bf16 v[22:25], v[146:149], v[216:219], v[22:25]
	v_mfma_f32_16x16x32_bf16 v[18:21], v[154:157], v[216:219], v[18:21]
	v_mfma_f32_16x16x32_bf16 v[46:49], v[158:161], v[174:177], v[46:49]
	v_mfma_f32_16x16x32_bf16 v[42:45], v[166:169], v[174:177], v[42:45]
	v_mfma_f32_16x16x32_bf16 v[30:33], v[158:161], v[182:185], v[30:33]
	v_mfma_f32_16x16x32_bf16 v[26:29], v[166:169], v[182:185], v[26:29]
	v_mfma_f32_16x16x32_bf16 v[14:17], v[158:161], v[190:193], v[14:17]
	v_mfma_f32_16x16x32_bf16 v[10:13], v[166:169], v[190:193], v[10:13]
	v_mfma_f32_16x16x32_bf16 v[6:9], v[158:161], v[212:215], v[6:9]
	v_mfma_f32_16x16x32_bf16 v[2:5], v[166:169], v[212:215], v[2:5]
	v_mfma_f32_16x16x32_bf16 v[46:49], v[162:165], v[178:181], v[46:49]
	v_mfma_f32_16x16x32_bf16 v[42:45], v[170:173], v[178:181], v[42:45]
	v_mfma_f32_16x16x32_bf16 v[30:33], v[162:165], v[186:189], v[30:33]
	v_mfma_f32_16x16x32_bf16 v[26:29], v[170:173], v[186:189], v[26:29]
	v_mfma_f32_16x16x32_bf16 v[14:17], v[162:165], v[208:211], v[14:17]
	v_mfma_f32_16x16x32_bf16 v[10:13], v[170:173], v[208:211], v[10:13]
	v_mfma_f32_16x16x32_bf16 v[6:9], v[162:165], v[216:219], v[6:9]
	v_mfma_f32_16x16x32_bf16 v[2:5], v[170:173], v[216:219], v[2:5]
	s_barrier
; #define PG8_STAGE(bufoff, gbase, voff) do { _Pragma("unroll") for (int _i = 0; _i < 2; ++_i) \
;         __builtin_amdgcn_global_load_lds((const unsigned*)((const char*)(gbase) + (voff)[_i]), (PG8_LAS unsigned*)(lds + (bufoff) + ldsw + _i * 8192), 16, 0, 0); } while (0)
; #define PG8_LDA(dst, b, h) do { _Pragma("unroll") for (int m = 0; m < 4; ++m) _Pragma("unroll") for (int k = 0; k < 2; ++k) dst[m][k] = *(const PG8_LAS bf16x8*)(lds + PG8_SA(b, h) + aoff + m * 2048 + k * 1024); } while (0)
; #define PG8_LDB(dst, b, h) do { _Pragma("unroll") for (int n = 0; n < 2; ++n) _Pragma("unroll") for (int k = 0; k < 2; ++k) dst[n][k] = *(const PG8_LAS bf16x8*)(lds + PG8_SB(b, h) + boff + n * 2048 + k * 1024); } while (0)
; #define PG8_MMA(ai, bj, At, Bt) do { __builtin_amdgcn_s_setprio(1); _Pragma("unroll") for (int m = 0; m < 4; ++m) _Pragma("unroll") for (int n = 0; n < 2; ++n) _Pragma("unroll") for (int k = 0; k < 2; ++k) \
;         acc[ai][bj][m][n] = __builtin_amdgcn_mfma_f32_16x16x32_bf16(Bt[n][k], At[m][k], acc[ai][bj][m][n], 0, 0, 0); __builtin_amdgcn_s_setprio(0); } while (0)
; #define PG8_WAIT_V(n) asm volatile("s_waitcnt vmcnt(" #n ")" ::: "memory")
; #define PG8_WAIT_L(n) asm volatile("s_waitcnt lgkmcnt(" #n ")" ::: "memory")
; #define PG8_BAR __builtin_amdgcn_s_barrier()
; #define PG8_SCHED __builtin_amdgcn_sched_barrier(0)
; template <class Epi, class Sched, bool ALIGN_EPI = false, bool SP2 = false>
; __device__ __forceinline__ void gemm_phase(PG8_LAS unsigned char* lds, const Gemm g, const Sched& S, const Epi& E, int wid_in) {
;     ...
;             PG8_LDB(B0, 1, 0); PG8_LDB(B1, 1, 1); PG8_SCHED; PG8_LDA(At, 1, 0); PG8_STAGE(PG8_SA(0, 1), a2 + hstep, voffA);
;             PG8_WAIT_V(8); PG8_WAIT_L(0); PG8_BAR; PG8_MMA(0, 0, At, B0); PG8_MMA(0, 1, At, B1); PG8_BAR; PG8_SCHED;
	s_setprio 1
	s_add_i32 s40, 0, 0x18000
	s_add_i32 s41, 0, 0x1c000
	v_add_u32_e32 v154, s40, v140
	v_add_u32_e32 v170, s41, v140
	ds_read_b128 v[142:145], v154
	ds_read_b128 v[146:149], v154 offset:1024
	ds_read_b128 v[150:153], v154 offset:2048
	ds_read_b128 v[154:157], v154 offset:3072
	ds_read_b128 v[158:161], v170
	ds_read_b128 v[162:165], v170 offset:1024
	ds_read_b128 v[166:169], v170 offset:2048
	ds_read_b128 v[170:173], v170 offset:3072
	s_add_u32 s30, s30, 0x80000
	s_addc_u32 s31, s31, 0
	s_mov_b32 m0, s37
	v_lshl_add_u64 v[228:229], s[30:31], 0, v[130:131]
	ds_read_b128 v[174:177], v141 offset:32768
	ds_read_b128 v[178:181], v141 offset:33792
	ds_read_b128 v[182:185], v141 offset:34816
	ds_read_b128 v[186:189], v141 offset:35840
	ds_read_b128 v[190:193], v141 offset:36864
	ds_read_b128 v[208:211], v141 offset:37888
	ds_read_b128 v[212:215], v141 offset:38912
	ds_read_b128 v[216:219], v141 offset:39936
	global_load_lds_dwordx4 v[228:229], off
	v_lshl_add_u64 v[228:229], s[30:31], 0, v[132:133]
	s_mov_b32 m0, s38
	s_nop 0
	global_load_lds_dwordx4 v[228:229], off
	s_waitcnt vmcnt(8)
	s_waitcnt lgkmcnt(0)
	s_barrier
	s_setprio 0
	s_waitcnt lgkmcnt(0)
	v_mfma_f32_16x16x32_bf16 v[126:129], v[142:145], v[174:177], v[126:129]
	v_mfma_f32_16x16x32_bf16 v[122:125], v[150:153], v[174:177], v[122:125]
	v_mfma_f32_16x16x32_bf16 v[118:121], v[142:145], v[182:185], v[118:121]
	v_mfma_f32_16x16x32_bf16 v[114:117], v[150:153], v[182:185], v[114:117]
	v_mfma_f32_16x16x32_bf16 v[102:105], v[142:145], v[190:193], v[102:105]
	v_mfma_f32_16x16x32_bf16 v[98:101], v[150:153], v[190:193], v[98:101]
	v_mfma_f32_16x16x32_bf16 v[86:89], v[142:145], v[212:215], v[86:89]
	v_mfma_f32_16x16x32_bf16 v[82:85], v[150:153], v[212:215], v[82:85]
	v_mfma_f32_16x16x32_bf16 v[126:129], v[146:149], v[178:181], v[126:129]
	v_mfma_f32_16x16x32_bf16 v[122:125], v[154:157], v[178:181], v[122:125]
	v_mfma_f32_16x16x32_bf16 v[118:121], v[146:149], v[186:189], v[118:121]
	v_mfma_f32_16x16x32_bf16 v[114:117], v[154:157], v[186:189], v[114:117]
	v_mfma_f32_16x16x32_bf16 v[102:105], v[146:149], v[208:211], v[102:105]
	v_mfma_f32_16x16x32_bf16 v[98:101], v[154:157], v[208:211], v[98:101]
	v_mfma_f32_16x16x32_bf16 v[86:89], v[146:149], v[216:219], v[86:89]
	v_mfma_f32_16x16x32_bf16 v[82:85], v[154:157], v[216:219], v[82:85]
	v_mfma_f32_16x16x32_bf16 v[110:113], v[158:161], v[174:177], v[110:113]
	v_mfma_f32_16x16x32_bf16 v[106:109], v[166:169], v[174:177], v[106:109]
	v_mfma_f32_16x16x32_bf16 v[94:97], v[158:161], v[182:185], v[94:97]
	v_mfma_f32_16x16x32_bf16 v[90:93], v[166:169], v[182:185], v[90:93]
	v_mfma_f32_16x16x32_bf16 v[78:81], v[158:161], v[190:193], v[78:81]
	v_mfma_f32_16x16x32_bf16 v[74:77], v[166:169], v[190:193], v[74:77]
	v_mfma_f32_16x16x32_bf16 v[70:73], v[158:161], v[212:215], v[70:73]
	v_mfma_f32_16x16x32_bf16 v[66:69], v[166:169], v[212:215], v[66:69]
	v_mfma_f32_16x16x32_bf16 v[110:113], v[162:165], v[178:181], v[110:113]
	v_mfma_f32_16x16x32_bf16 v[106:109], v[170:173], v[178:181], v[106:109]
	v_mfma_f32_16x16x32_bf16 v[94:97], v[162:165], v[186:189], v[94:97]
	v_mfma_f32_16x16x32_bf16 v[90:93], v[170:173], v[186:189], v[90:93]
	v_mfma_f32_16x16x32_bf16 v[78:81], v[162:165], v[208:211], v[78:81]
	v_mfma_f32_16x16x32_bf16 v[74:77], v[170:173], v[208:211], v[74:77]
	v_mfma_f32_16x16x32_bf16 v[70:73], v[162:165], v[216:219], v[70:73]
	v_mfma_f32_16x16x32_bf16 v[66:69], v[170:173], v[216:219], v[66:69]
	s_barrier
; #define PG8_STAGE(bufoff, gbase, voff) do { _Pragma("unroll") for (int _i = 0; _i < 2; ++_i) \
;         __builtin_amdgcn_global_load_lds((const unsigned*)((const char*)(gbase) + (voff)[_i]), (PG8_LAS unsigned*)(lds + (bufoff) + ldsw + _i * 8192), 16, 0, 0); } while (0)
; #define PG8_LDA(dst, b, h) do { _Pragma("unroll") for (int m = 0; m < 4; ++m) _Pragma("unroll") for (int k = 0; k < 2; ++k) dst[m][k] = *(const PG8_LAS bf16x8*)(lds + PG8_SA(b, h) + aoff + m * 2048 + k * 1024); } while (0)
; #define PG8_MMA(ai, bj, At, Bt) do { __builtin_amdgcn_s_setprio(1); _Pragma("unroll") for (int m = 0; m < 4; ++m) _Pragma("unroll") for (int n = 0; n < 2; ++n) _Pragma("unroll") for (int k = 0; k < 2; ++k) \
;         acc[ai][bj][m][n] = __builtin_amdgcn_mfma_f32_16x16x32_bf16(Bt[n][k], At[m][k], acc[ai][bj][m][n], 0, 0, 0); __builtin_amdgcn_s_setprio(0); } while (0)
; #define PG8_WAIT_V(n) asm volatile("s_waitcnt vmcnt(" #n ")" ::: "memory")
; #define PG8_WAIT_L(n) asm volatile("s_waitcnt lgkmcnt(" #n ")" ::: "memory")
; #define PG8_BAR __builtin_amdgcn_s_barrier()
; #define PG8_SCHED __builtin_amdgcn_sched_barrier(0)
; template <class Epi, class Sched, bool ALIGN_EPI = false, bool SP2 = false>
; __device__ __forceinline__ void gemm_phase(PG8_LAS unsigned char* lds, const Gemm g, const Sched& S, const Epi& E, int wid_in) {
;     ...
;             PG8_LDA(At, 1, 1); PG8_STAGE(PG8_SB(1, 0), b3, voffB); PG8_STAGE(PG8_SB(1, 1), b3 + hstep, voffB); PG8_STAGE(PG8_SA(1, 0), a3, voffA);
;             PG8_WAIT_V(8); PG8_WAIT_L(0); PG8_BAR; PG8_MMA(1, 0, At, B0); PG8_MMA(1, 1, At, B1); PG8_BAR; PG8_SCHED;
;     ...
;         if constexpr (ALIGN_EPI) { if (wr == 0) PG8_BAR; }
	s_setprio 1
	s_add_i32 s30, s40, s59
	v_lshl_add_u64 v[220:221], v[220:221], 0, s[94:95]
	s_mov_b32 m0, s30
	ds_read_b128 v[174:177], v141 offset:49152
	ds_read_b128 v[178:181], v141 offset:50176
	ds_read_b128 v[182:185], v141 offset:51200
	ds_read_b128 v[186:189], v141 offset:52224
	ds_read_b128 v[190:193], v141 offset:53248
	ds_read_b128 v[208:211], v141 offset:54272
	ds_read_b128 v[212:215], v141 offset:55296
	ds_read_b128 v[216:219], v141 offset:56320
	global_load_lds_dwordx4 v[220:221], off
	s_add_i32 m0, s30, 0x2000
	s_add_u32 s28, s28, 0x80080
	v_lshl_add_u64 v[220:221], v[222:223], 0, s[94:95]
	s_addc_u32 s29, s29, 0
	s_add_i32 s30, s41, s59
	global_load_lds_dwordx4 v[220:221], off
	v_lshl_add_u64 v[220:221], s[28:29], 0, v[0:1]
	s_mov_b32 m0, s30
	s_nop 0
	global_load_lds_dwordx4 v[220:221], off
	v_lshl_add_u64 v[220:221], s[28:29], 0, v[134:135]
	s_add_i32 m0, s30, 0x2000
	s_nop 0
	global_load_lds_dwordx4 v[220:221], off
	v_lshl_add_u64 v[220:221], v[224:225], 0, s[94:95]
	s_mov_b32 m0, s52
	s_nop 0
	global_load_lds_dwordx4 v[220:221], off
	v_lshl_add_u64 v[220:221], v[226:227], 0, s[94:95]
	s_mov_b32 m0, s53
	s_nop 0
	global_load_lds_dwordx4 v[220:221], off
	s_waitcnt vmcnt(8)
	s_waitcnt lgkmcnt(0)
	s_barrier
	s_setprio 0
	s_waitcnt lgkmcnt(0)
	v_mfma_f32_16x16x32_bf16 v[62:65], v[142:145], v[174:177], v[62:65]
	v_mfma_f32_16x16x32_bf16 v[58:61], v[150:153], v[174:177], v[58:61]
	v_mfma_f32_16x16x32_bf16 v[54:57], v[142:145], v[182:185], v[54:57]
	v_mfma_f32_16x16x32_bf16 v[50:53], v[150:153], v[182:185], v[50:53]
	v_mfma_f32_16x16x32_bf16 v[38:41], v[142:145], v[190:193], v[38:41]
	v_mfma_f32_16x16x32_bf16 v[34:37], v[150:153], v[190:193], v[34:37]
	v_mfma_f32_16x16x32_bf16 v[22:25], v[142:145], v[212:215], v[22:25]
	v_mfma_f32_16x16x32_bf16 v[18:21], v[150:153], v[212:215], v[18:21]
	v_mfma_f32_16x16x32_bf16 v[62:65], v[146:149], v[178:181], v[62:65]
	v_mfma_f32_16x16x32_bf16 v[58:61], v[154:157], v[178:181], v[58:61]
	v_mfma_f32_16x16x32_bf16 v[54:57], v[146:149], v[186:189], v[54:57]
	v_mfma_f32_16x16x32_bf16 v[50:53], v[154:157], v[186:189], v[50:53]
	v_mfma_f32_16x16x32_bf16 v[38:41], v[146:149], v[208:211], v[38:41]
	v_mfma_f32_16x16x32_bf16 v[34:37], v[154:157], v[208:211], v[34:37]
	v_mfma_f32_16x16x32_bf16 v[22:25], v[146:149], v[216:219], v[22:25]
	v_mfma_f32_16x16x32_bf16 v[18:21], v[154:157], v[216:219], v[18:21]
	v_mfma_f32_16x16x32_bf16 v[46:49], v[158:161], v[174:177], v[46:49]
	v_mfma_f32_16x16x32_bf16 v[42:45], v[166:169], v[174:177], v[42:45]
	v_mfma_f32_16x16x32_bf16 v[30:33], v[158:161], v[182:185], v[30:33]
	v_mfma_f32_16x16x32_bf16 v[26:29], v[166:169], v[182:185], v[26:29]
	v_mfma_f32_16x16x32_bf16 v[14:17], v[158:161], v[190:193], v[14:17]
	v_mfma_f32_16x16x32_bf16 v[10:13], v[166:169], v[190:193], v[10:13]
	v_mfma_f32_16x16x32_bf16 v[6:9], v[158:161], v[212:215], v[6:9]
	v_mfma_f32_16x16x32_bf16 v[2:5], v[166:169], v[212:215], v[2:5]
	v_mfma_f32_16x16x32_bf16 v[46:49], v[162:165], v[178:181], v[46:49]
	v_mfma_f32_16x16x32_bf16 v[42:45], v[170:173], v[178:181], v[42:45]
	v_mfma_f32_16x16x32_bf16 v[30:33], v[162:165], v[186:189], v[30:33]
	v_mfma_f32_16x16x32_bf16 v[26:29], v[170:173], v[186:189], v[26:29]
	v_mfma_f32_16x16x32_bf16 v[14:17], v[162:165], v[208:211], v[14:17]
	v_mfma_f32_16x16x32_bf16 v[10:13], v[170:173], v[208:211], v[10:13]
	v_mfma_f32_16x16x32_bf16 v[6:9], v[162:165], v[216:219], v[6:9]
	v_mfma_f32_16x16x32_bf16 v[2:5], v[170:173], v[216:219], v[2:5]
	s_barrier
	s_setprio 1
	s_add_i32 s63, s63, 2
	s_add_u32 s64, s64, 0x100
	s_addc_u32 s65, s65, 0
	s_add_u32 s26, s26, 0x100
	s_addc_u32 s27, s27, 0
	s_cmp_gt_u32 s63, 29
	s_cbranch_scc0 .LBB0_278
	s_setprio 0
	s_and_b64 vcc, exec, s[14:15]
	s_cbranch_vccz .LBB0_281
	s_barrier

; #define PG8_STAGE(bufoff, gbase, voff) do { _Pragma("unroll") for (int _i = 0; _i < 2; ++_i) \
;         __builtin_amdgcn_global_load_lds((const unsigned*)((const char*)(gbase) + (voff)[_i]), (PG8_LAS unsigned*)(lds + (bufoff) + ldsw + _i * 8192), 16, 0, 0); } while (0)
; #define PG8_LDA(dst, b, h) do { _Pragma("unroll") for (int m = 0; m < 4; ++m) _Pragma("unroll") for (int k = 0; k < 2; ++k) dst[m][k] = *(const PG8_LAS bf16x8*)(lds + PG8_SA(b, h) + aoff + m * 2048 + k * 1024); } while (0)
; #define PG8_LDB(dst, b, h) do { _Pragma("unroll") for (int n = 0; n < 2; ++n) _Pragma("unroll") for (int k = 0; k < 2; ++k) dst[n][k] = *(const PG8_LAS bf16x8*)(lds + PG8_SB(b, h) + boff + n * 2048 + k * 1024); } while (0)
; #define PG8_WAIT_V(n) asm volatile("s_waitcnt vmcnt(" #n ")" ::: "memory")
; #define PG8_WAIT_L(n) asm volatile("s_waitcnt lgkmcnt(" #n ")" ::: "memory")
; template <class Epi, class Sched, bool ALIGN_EPI = false, bool SP2 = false>
; __device__ __forceinline__ void gemm_phase(PG8_LAS unsigned char* lds, const Gemm g, const Sched& S, const Epi& E, int wid_in) {
;     ...
;     for (;;) {
;         const bool has_next = S.next(ui + 1, nxt);
;         const char* nA = has_next ? (const char*)g.A + (size_t)nxt.pm * tstep + (size_t)nxt.kt0 * kstep : cA; const char* nB = has_next ? (const char*)g.Bt + (size_t)nxt.pn * tstep + (size_t)nxt.kt0 * kstep : cB;
;         const int nt = cur.nkt;
;         for (int t = 0; t < nt; t += 2) {
;             const bool last = (t == nt - 2);
;             const char* a1 = cA + (size_t)(t + 1) * kstep;
;             const char* a2 = last ? nA : cA + (size_t)(t + 2) * kstep; const char* b2 = last ? nB : cB + (size_t)(t + 2) * kstep;
;             const char* a3 = a2 + kstep; const char* b3 = b2 + kstep;
;             if (last && has_next) S.a_ready(nxt);
;             if constexpr (SP2) {
;             PG8_LDB(B0, 0, 0); PG8_LDB(B1, 0, 1); PG8_SCHED; PG8_LDA(At, 0, 0); PG8_STAGE(PG8_SA(1, 1), a1 + hstep, voffA);
;             PG8_WAIT_V(8); PG8_WAIT_L(0); PG8_BAR; PG8_MMA(0, 0, At, B0); PG8_MMA(0, 1, At, B1); PG8_BAR; PG8_SCHED;
;     ...
; #pragma unroll
;         for (int a = 0; a < 2; ++a)
; #pragma unroll
;             for (int b = 0; b < 2; ++b)
; #pragma unroll
;                 for (int m = 0; m < 4; ++m)
; #pragma unroll
;                     for (int n = 0; n < 2; ++n) acc[a][b][m][n] = (f32x4){0.f, 0.f, 0.f, 0.f};
.LBB0_847:
	s_ashr_i32 s19, s18, 31
	s_lshl_b64 s[22:23], s[18:19], 19
	s_add_u32 s17, s38, s22
	s_addc_u32 s19, s39, s23
	s_ashr_i32 s15, s14, 31
	s_lshl_b64 s[24:25], s[14:15], 7
	s_add_u32 s22, s17, s24
	s_addc_u32 s23, s19, s25
	s_and_b64 s[36:37], s[20:21], exec
	s_cselect_b32 s15, s23, s35
	s_cselect_b32 s19, s22, s34
	s_ashr_i32 s17, s16, 31
	s_lshl_b64 s[36:37], s[16:17], 19
	s_add_u32 s17, s52, s36
	s_addc_u32 s27, s53, s37
	s_add_u32 s24, s17, s24
	s_addc_u32 s25, s27, s25
	s_and_b64 s[36:37], s[20:21], exec
	s_cselect_b32 s17, s25, s31
	s_cselect_b32 s27, s24, s30
	s_add_i32 vcc_lo, s1, -2
	s_add_u32 vcc_hi, s30, 0x100
	s_addc_u32 s63, s31, 0
	s_add_u32 s30, s34, 0x40080
	v_mov_b32_e32 v2, 0
	s_addc_u32 s31, s35, 0
	s_mov_b32 s34, 0
	v_mov_b32_e32 v3, v2
	v_mov_b32_e32 v4, v2
	v_mov_b32_e32 v5, v2
	v_mov_b32_e32 v6, v2
	v_mov_b32_e32 v7, v2
	v_mov_b32_e32 v8, v2
	v_mov_b32_e32 v9, v2
	v_mov_b32_e32 v10, v2
	v_mov_b32_e32 v11, v2
	v_mov_b32_e32 v12, v2
	v_mov_b32_e32 v13, v2
	v_mov_b32_e32 v14, v2
	v_mov_b32_e32 v15, v2
	v_mov_b32_e32 v16, v2
	v_mov_b32_e32 v17, v2
	v_mov_b32_e32 v26, v2
	v_mov_b32_e32 v27, v2
	v_mov_b32_e32 v28, v2
	v_mov_b32_e32 v29, v2
	v_mov_b32_e32 v30, v2
	v_mov_b32_e32 v31, v2
	v_mov_b32_e32 v32, v2
	v_mov_b32_e32 v33, v2
	v_mov_b32_e32 v42, v2
	v_mov_b32_e32 v43, v2
	v_mov_b32_e32 v44, v2
	v_mov_b32_e32 v45, v2
	v_mov_b32_e32 v46, v2
	v_mov_b32_e32 v47, v2
	v_mov_b32_e32 v48, v2
	v_mov_b32_e32 v49, v2
	v_mov_b32_e32 v18, v2
	v_mov_b32_e32 v19, v2
	v_mov_b32_e32 v20, v2
	v_mov_b32_e32 v21, v2
	v_mov_b32_e32 v22, v2
	v_mov_b32_e32 v23, v2
	v_mov_b32_e32 v24, v2
	v_mov_b32_e32 v25, v2
	v_mov_b32_e32 v34, v2
	v_mov_b32_e32 v35, v2
	v_mov_b32_e32 v36, v2
	v_mov_b32_e32 v37, v2
	v_mov_b32_e32 v38, v2
	v_mov_b32_e32 v39, v2
	v_mov_b32_e32 v40, v2
	v_mov_b32_e32 v41, v2
	v_mov_b32_e32 v50, v2
	v_mov_b32_e32 v51, v2
	v_mov_b32_e32 v52, v2
	v_mov_b32_e32 v53, v2
	v_mov_b32_e32 v54, v2
	v_mov_b32_e32 v55, v2
	v_mov_b32_e32 v56, v2
	v_mov_b32_e32 v57, v2
	v_mov_b32_e32 v58, v2
	v_mov_b32_e32 v59, v2
	v_mov_b32_e32 v60, v2
	v_mov_b32_e32 v61, v2
	v_mov_b32_e32 v62, v2
	v_mov_b32_e32 v63, v2
	v_mov_b32_e32 v64, v2
	v_mov_b32_e32 v65, v2
	v_mov_b32_e32 v66, v2
	v_mov_b32_e32 v67, v2
	v_mov_b32_e32 v68, v2
	v_mov_b32_e32 v69, v2
	v_mov_b32_e32 v70, v2
	v_mov_b32_e32 v71, v2
	v_mov_b32_e32 v72, v2
	v_mov_b32_e32 v73, v2
	v_mov_b32_e32 v74, v2
	v_mov_b32_e32 v75, v2
	v_mov_b32_e32 v76, v2
	v_mov_b32_e32 v77, v2
	v_mov_b32_e32 v78, v2
	v_mov_b32_e32 v79, v2
	v_mov_b32_e32 v80, v2
	v_mov_b32_e32 v81, v2
	v_mov_b32_e32 v90, v2
	v_mov_b32_e32 v91, v2
	v_mov_b32_e32 v92, v2
	v_mov_b32_e32 v93, v2
	v_mov_b32_e32 v94, v2
	v_mov_b32_e32 v95, v2
	v_mov_b32_e32 v96, v2
	v_mov_b32_e32 v97, v2
	v_mov_b32_e32 v106, v2
	v_mov_b32_e32 v107, v2
	v_mov_b32_e32 v108, v2
	v_mov_b32_e32 v109, v2
	v_mov_b32_e32 v110, v2
	v_mov_b32_e32 v111, v2
	v_mov_b32_e32 v112, v2
	v_mov_b32_e32 v113, v2
	v_mov_b32_e32 v82, v2
	v_mov_b32_e32 v83, v2
	v_mov_b32_e32 v84, v2
	v_mov_b32_e32 v85, v2
	v_mov_b32_e32 v86, v2
	v_mov_b32_e32 v87, v2
	v_mov_b32_e32 v88, v2
	v_mov_b32_e32 v89, v2
	v_mov_b32_e32 v98, v2
	v_mov_b32_e32 v99, v2
	v_mov_b32_e32 v100, v2
	v_mov_b32_e32 v101, v2
	v_mov_b32_e32 v102, v2
	v_mov_b32_e32 v103, v2
	v_mov_b32_e32 v104, v2
	v_mov_b32_e32 v105, v2
	v_mov_b32_e32 v114, v2
	v_mov_b32_e32 v115, v2
	v_mov_b32_e32 v116, v2
	v_mov_b32_e32 v117, v2
	v_mov_b32_e32 v118, v2
	v_mov_b32_e32 v119, v2
	v_mov_b32_e32 v120, v2
	v_mov_b32_e32 v121, v2
	v_mov_b32_e32 v122, v2
	v_mov_b32_e32 v123, v2
	v_mov_b32_e32 v124, v2
	v_mov_b32_e32 v125, v2
	v_mov_b32_e32 v126, v2
	v_mov_b32_e32 v127, v2
	v_mov_b32_e32 v128, v2
	v_mov_b32_e32 v129, v2
	s_setprio 1
.Lprio_skip_1:
.LBB0_848:
	s_add_i32 s56, s34, 2
	s_add_u32 s35, s30, 0xfffc0080
	s_addc_u32 s36, s31, -1
	s_add_i32 s40, 0, 0x10000
	s_cmp_eq_u32 vcc_lo, s34
	s_cselect_b32 s37, s15, s36
	s_cselect_b32 s36, s19, s35
	s_cselect_b32 s35, s17, s63
	s_cselect_b32 s34, s27, vcc_hi
	s_add_i32 s42, 0, 0x14000
	v_add_u32_e32 v142, s40, v188
	v_add_u32_e32 v158, s42, v188
	ds_read_b128 v[130:133], v142
	ds_read_b128 v[134:137], v142 offset:1024
	ds_read_b128 v[138:141], v142 offset:2048
	ds_read_b128 v[142:145], v142 offset:3072
	ds_read_b128 v[146:149], v158
	ds_read_b128 v[150:153], v158 offset:1024
	ds_read_b128 v[154:157], v158 offset:2048
	ds_read_b128 v[158:161], v158 offset:3072
	v_lshl_add_u64 v[220:221], s[30:31], 0, v[170:171]
	s_add_i32 m0, s29, 0xc000
	ds_read_b128 v[172:175], v189
	ds_read_b128 v[176:179], v189 offset:1024
	ds_read_b128 v[180:183], v189 offset:2048
	ds_read_b128 v[184:187], v189 offset:3072
	ds_read_b128 v[190:193], v189 offset:4096
	ds_read_b128 v[208:211], v189 offset:5120
	ds_read_b128 v[212:215], v189 offset:6144
	ds_read_b128 v[216:219], v189 offset:7168
	global_load_lds_dwordx4 v[220:221], off
	v_lshl_add_u64 v[220:221], s[30:31], 0, v[168:169]
	s_add_i32 m0, s29, 0xe000
	s_nop 0
	global_load_lds_dwordx4 v[220:221], off
	s_waitcnt vmcnt(8)
	s_waitcnt lgkmcnt(0)
	s_barrier
; #define PG8_STAGE(bufoff, gbase, voff) do { _Pragma("unroll") for (int _i = 0; _i < 2; ++_i) \
;         __builtin_amdgcn_global_load_lds((const unsigned*)((const char*)(gbase) + (voff)[_i]), (PG8_LAS unsigned*)(lds + (bufoff) + ldsw + _i * 8192), 16, 0, 0); } while (0)
; #define PG8_LDA(dst, b, h) do { _Pragma("unroll") for (int m = 0; m < 4; ++m) _Pragma("unroll") for (int k = 0; k < 2; ++k) dst[m][k] = *(const PG8_LAS bf16x8*)(lds + PG8_SA(b, h) + aoff + m * 2048 + k * 1024); } while (0)
; #define PG8_MMA(ai, bj, At, Bt) do { __builtin_amdgcn_s_setprio(1); _Pragma("unroll") for (int m = 0; m < 4; ++m) _Pragma("unroll") for (int n = 0; n < 2; ++n) _Pragma("unroll") for (int k = 0; k < 2; ++k) \
;         acc[ai][bj][m][n] = __builtin_amdgcn_mfma_f32_16x16x32_bf16(Bt[n][k], At[m][k], acc[ai][bj][m][n], 0, 0, 0); __builtin_amdgcn_s_setprio(0); } while (0)
; #define PG8_WAIT_V(n) asm volatile("s_waitcnt vmcnt(" #n ")" ::: "memory")
; #define PG8_WAIT_L(n) asm volatile("s_waitcnt lgkmcnt(" #n ")" ::: "memory")
; #define PG8_BAR __builtin_amdgcn_s_barrier()
; #define PG8_SCHED __builtin_amdgcn_sched_barrier(0)
; template <class Epi, class Sched, bool ALIGN_EPI = false, bool SP2 = false>
; __device__ __forceinline__ void gemm_phase(PG8_LAS unsigned char* lds, const Gemm g, const Sched& S, const Epi& E, int wid_in) {
;     ...
;             PG8_WAIT_V(8); PG8_WAIT_L(0); PG8_BAR; PG8_MMA(0, 0, At, B0); PG8_MMA(0, 1, At, B1); PG8_BAR; PG8_SCHED;
;             PG8_LDA(At, 0, 1); PG8_STAGE(PG8_SB(0, 0), b2, voffB); PG8_STAGE(PG8_SB(0, 1), b2 + hstep, voffB); PG8_STAGE(PG8_SA(0, 0), a2, voffA);
;             PG8_WAIT_V(8); PG8_WAIT_L(0); PG8_BAR; PG8_MMA(1, 0, At, B0); PG8_MMA(1, 1, At, B1); PG8_BAR; PG8_SCHED;
	s_setprio 0
	s_waitcnt lgkmcnt(0)
	v_mfma_f32_16x16x32_bf16 v[126:129], v[130:133], v[172:175], v[126:129]
	v_mfma_f32_16x16x32_bf16 v[122:125], v[138:141], v[172:175], v[122:125]
	v_mfma_f32_16x16x32_bf16 v[118:121], v[130:133], v[180:183], v[118:121]
	v_mfma_f32_16x16x32_bf16 v[114:117], v[138:141], v[180:183], v[114:117]
	v_mfma_f32_16x16x32_bf16 v[102:105], v[130:133], v[190:193], v[102:105]
	v_mfma_f32_16x16x32_bf16 v[98:101], v[138:141], v[190:193], v[98:101]
	v_mfma_f32_16x16x32_bf16 v[86:89], v[130:133], v[212:215], v[86:89]
	v_mfma_f32_16x16x32_bf16 v[82:85], v[138:141], v[212:215], v[82:85]
	v_mfma_f32_16x16x32_bf16 v[126:129], v[134:137], v[176:179], v[126:129]
	v_mfma_f32_16x16x32_bf16 v[122:125], v[142:145], v[176:179], v[122:125]
	v_mfma_f32_16x16x32_bf16 v[118:121], v[134:137], v[184:187], v[118:121]
	v_mfma_f32_16x16x32_bf16 v[114:117], v[142:145], v[184:187], v[114:117]
	v_mfma_f32_16x16x32_bf16 v[102:105], v[134:137], v[208:211], v[102:105]
	v_mfma_f32_16x16x32_bf16 v[98:101], v[142:145], v[208:211], v[98:101]
	v_mfma_f32_16x16x32_bf16 v[86:89], v[134:137], v[216:219], v[86:89]
	v_mfma_f32_16x16x32_bf16 v[82:85], v[142:145], v[216:219], v[82:85]
	v_mfma_f32_16x16x32_bf16 v[110:113], v[146:149], v[172:175], v[110:113]
	v_mfma_f32_16x16x32_bf16 v[106:109], v[154:157], v[172:175], v[106:109]
	v_mfma_f32_16x16x32_bf16 v[94:97], v[146:149], v[180:183], v[94:97]
	v_mfma_f32_16x16x32_bf16 v[90:93], v[154:157], v[180:183], v[90:93]
	v_mfma_f32_16x16x32_bf16 v[78:81], v[146:149], v[190:193], v[78:81]
	v_mfma_f32_16x16x32_bf16 v[74:77], v[154:157], v[190:193], v[74:77]
	v_mfma_f32_16x16x32_bf16 v[70:73], v[146:149], v[212:215], v[70:73]
	v_mfma_f32_16x16x32_bf16 v[66:69], v[154:157], v[212:215], v[66:69]
	v_mfma_f32_16x16x32_bf16 v[110:113], v[150:153], v[176:179], v[110:113]
	v_mfma_f32_16x16x32_bf16 v[106:109], v[158:161], v[176:179], v[106:109]
	v_mfma_f32_16x16x32_bf16 v[94:97], v[150:153], v[184:187], v[94:97]
	v_mfma_f32_16x16x32_bf16 v[90:93], v[158:161], v[184:187], v[90:93]
	v_mfma_f32_16x16x32_bf16 v[78:81], v[150:153], v[208:211], v[78:81]
	v_mfma_f32_16x16x32_bf16 v[74:77], v[158:161], v[208:211], v[74:77]
	v_mfma_f32_16x16x32_bf16 v[70:73], v[150:153], v[216:219], v[70:73]
	v_mfma_f32_16x16x32_bf16 v[66:69], v[158:161], v[216:219], v[66:69]
	s_barrier
	s_setprio 1
	s_add_i32 s40, s40, s59
	v_lshl_add_u64 v[220:221], s[34:35], 0, v[0:1]
	s_mov_b32 m0, s40
	ds_read_b128 v[172:175], v189 offset:16384
	ds_read_b128 v[176:179], v189 offset:17408
	ds_read_b128 v[180:183], v189 offset:18432
	ds_read_b128 v[184:187], v189 offset:19456
	ds_read_b128 v[190:193], v189 offset:20480
	ds_read_b128 v[208:211], v189 offset:21504
	ds_read_b128 v[212:215], v189 offset:22528
	ds_read_b128 v[216:219], v189 offset:23552
	global_load_lds_dwordx4 v[220:221], off
	s_add_i32 m0, s40, 0x2000
	s_add_u32 s40, s34, 0x40000
	v_lshl_add_u64 v[222:223], s[34:35], 0, v[166:167]
	s_addc_u32 s41, s35, 0
	s_add_i32 s42, s42, s59
	global_load_lds_dwordx4 v[222:223], off
	v_lshl_add_u64 v[224:225], s[40:41], 0, v[0:1]
	s_mov_b32 m0, s42
	v_lshl_add_u64 v[226:227], s[36:37], 0, v[164:165]
	global_load_lds_dwordx4 v[224:225], off
	v_lshl_add_u64 v[224:225], s[40:41], 0, v[166:167]
	s_add_i32 m0, s42, 0x2000
	s_nop 0
	global_load_lds_dwordx4 v[224:225], off
	v_lshl_add_u64 v[224:225], s[36:37], 0, v[162:163]
	s_mov_b32 m0, s29
	s_nop 0
	global_load_lds_dwordx4 v[224:225], off
	s_mov_b32 m0, s64
	s_nop 0
	global_load_lds_dwordx4 v[226:227], off
	s_waitcnt vmcnt(8)
	s_waitcnt lgkmcnt(0)
	s_barrier
	s_setprio 0
	s_waitcnt lgkmcnt(0)
	v_mfma_f32_16x16x32_bf16 v[62:65], v[130:133], v[172:175], v[62:65]
	v_mfma_f32_16x16x32_bf16 v[58:61], v[138:141], v[172:175], v[58:61]
	v_mfma_f32_16x16x32_bf16 v[54:57], v[130:133], v[180:183], v[54:57]
	v_mfma_f32_16x16x32_bf16 v[50:53], v[138:141], v[180:183], v[50:53]
	v_mfma_f32_16x16x32_bf16 v[38:41], v[130:133], v[190:193], v[38:41]
	v_mfma_f32_16x16x32_bf16 v[34:37], v[138:141], v[190:193], v[34:37]
	v_mfma_f32_16x16x32_bf16 v[22:25], v[130:133], v[212:215], v[22:25]
	v_mfma_f32_16x16x32_bf16 v[18:21], v[138:141], v[212:215], v[18:21]
	v_mfma_f32_16x16x32_bf16 v[62:65], v[134:137], v[176:179], v[62:65]
	v_mfma_f32_16x16x32_bf16 v[58:61], v[142:145], v[176:179], v[58:61]
	v_mfma_f32_16x16x32_bf16 v[54:57], v[134:137], v[184:187], v[54:57]
	v_mfma_f32_16x16x32_bf16 v[50:53], v[142:145], v[184:187], v[50:53]
	v_mfma_f32_16x16x32_bf16 v[38:41], v[134:137], v[208:211], v[38:41]
	v_mfma_f32_16x16x32_bf16 v[34:37], v[142:145], v[208:211], v[34:37]
	v_mfma_f32_16x16x32_bf16 v[22:25], v[134:137], v[216:219], v[22:25]
	v_mfma_f32_16x16x32_bf16 v[18:21], v[142:145], v[216:219], v[18:21]
	v_mfma_f32_16x16x32_bf16 v[46:49], v[146:149], v[172:175], v[46:49]
	v_mfma_f32_16x16x32_bf16 v[42:45], v[154:157], v[172:175], v[42:45]
	v_mfma_f32_16x16x32_bf16 v[30:33], v[146:149], v[180:183], v[30:33]
	v_mfma_f32_16x16x32_bf16 v[26:29], v[154:157], v[180:183], v[26:29]
	v_mfma_f32_16x16x32_bf16 v[14:17], v[146:149], v[190:193], v[14:17]
	v_mfma_f32_16x16x32_bf16 v[10:13], v[154:157], v[190:193], v[10:13]
	v_mfma_f32_16x16x32_bf16 v[6:9], v[146:149], v[212:215], v[6:9]
	v_mfma_f32_16x16x32_bf16 v[2:5], v[154:157], v[212:215], v[2:5]
	v_mfma_f32_16x16x32_bf16 v[46:49], v[150:153], v[176:179], v[46:49]
	v_mfma_f32_16x16x32_bf16 v[42:45], v[158:161], v[176:179], v[42:45]
	v_mfma_f32_16x16x32_bf16 v[30:33], v[150:153], v[184:187], v[30:33]
	v_mfma_f32_16x16x32_bf16 v[26:29], v[158:161], v[184:187], v[26:29]
	v_mfma_f32_16x16x32_bf16 v[14:17], v[150:153], v[208:211], v[14:17]
	v_mfma_f32_16x16x32_bf16 v[10:13], v[158:161], v[208:211], v[10:13]
	v_mfma_f32_16x16x32_bf16 v[6:9], v[150:153], v[216:219], v[6:9]
	v_mfma_f32_16x16x32_bf16 v[2:5], v[158:161], v[216:219], v[2:5]
	s_barrier
; #define PG8_STAGE(bufoff, gbase, voff) do { _Pragma("unroll") for (int _i = 0; _i < 2; ++_i) \
;         __builtin_amdgcn_global_load_lds((const unsigned*)((const char*)(gbase) + (voff)[_i]), (PG8_LAS unsigned*)(lds + (bufoff) + ldsw + _i * 8192), 16, 0, 0); } while (0)
; #define PG8_LDA(dst, b, h) do { _Pragma("unroll") for (int m = 0; m < 4; ++m) _Pragma("unroll") for (int k = 0; k < 2; ++k) dst[m][k] = *(const PG8_LAS bf16x8*)(lds + PG8_SA(b, h) + aoff + m * 2048 + k * 1024); } while (0)
; #define PG8_LDB(dst, b, h) do { _Pragma("unroll") for (int n = 0; n < 2; ++n) _Pragma("unroll") for (int k = 0; k < 2; ++k) dst[n][k] = *(const PG8_LAS bf16x8*)(lds + PG8_SB(b, h) + boff + n * 2048 + k * 1024); } while (0)
; #define PG8_MMA(ai, bj, At, Bt) do { __builtin_amdgcn_s_setprio(1); _Pragma("unroll") for (int m = 0; m < 4; ++m) _Pragma("unroll") for (int n = 0; n < 2; ++n) _Pragma("unroll") for (int k = 0; k < 2; ++k) \
;         acc[ai][bj][m][n] = __builtin_amdgcn_mfma_f32_16x16x32_bf16(Bt[n][k], At[m][k], acc[ai][bj][m][n], 0, 0, 0); __builtin_amdgcn_s_setprio(0); } while (0)
; #define PG8_WAIT_V(n) asm volatile("s_waitcnt vmcnt(" #n ")" ::: "memory")
; #define PG8_WAIT_L(n) asm volatile("s_waitcnt lgkmcnt(" #n ")" ::: "memory")
; #define PG8_BAR __builtin_amdgcn_s_barrier()
; #define PG8_SCHED __builtin_amdgcn_sched_barrier(0)
; template <class Epi, class Sched, bool ALIGN_EPI = false, bool SP2 = false>
; __device__ __forceinline__ void gemm_phase(PG8_LAS unsigned char* lds, const Gemm g, const Sched& S, const Epi& E, int wid_in) {
;     ...
;             PG8_LDB(B0, 1, 0); PG8_LDB(B1, 1, 1); PG8_SCHED; PG8_LDA(At, 1, 0); PG8_STAGE(PG8_SA(0, 1), a2 + hstep, voffA);
;             PG8_WAIT_V(8); PG8_WAIT_L(0); PG8_BAR; PG8_MMA(0, 0, At, B0); PG8_MMA(0, 1, At, B1); PG8_BAR; PG8_SCHED;
	s_setprio 1
	s_add_i32 s40, 0, 0x18000
	s_add_i32 s41, 0, 0x1c000
	v_add_u32_e32 v142, s40, v188
	v_add_u32_e32 v158, s41, v188
	ds_read_b128 v[130:133], v142
	ds_read_b128 v[134:137], v142 offset:1024
	ds_read_b128 v[138:141], v142 offset:2048
	ds_read_b128 v[142:145], v142 offset:3072
	ds_read_b128 v[146:149], v158
	ds_read_b128 v[150:153], v158 offset:1024
	ds_read_b128 v[154:157], v158 offset:2048
	ds_read_b128 v[158:161], v158 offset:3072
	s_add_u32 s36, s36, 0x40000
	s_addc_u32 s37, s37, 0
	s_mov_b32 m0, s65
	v_lshl_add_u64 v[228:229], s[36:37], 0, v[162:163]
	ds_read_b128 v[172:175], v189 offset:32768
	ds_read_b128 v[176:179], v189 offset:33792
	ds_read_b128 v[180:183], v189 offset:34816
	ds_read_b128 v[184:187], v189 offset:35840
	ds_read_b128 v[190:193], v189 offset:36864
	ds_read_b128 v[208:211], v189 offset:37888
	ds_read_b128 v[212:215], v189 offset:38912
	ds_read_b128 v[216:219], v189 offset:39936
	global_load_lds_dwordx4 v[228:229], off
	v_lshl_add_u64 v[228:229], s[36:37], 0, v[164:165]
	s_mov_b32 m0, s62
	s_nop 0
	global_load_lds_dwordx4 v[228:229], off
	s_waitcnt vmcnt(8)
	s_waitcnt lgkmcnt(0)
	s_barrier
	s_setprio 0
	s_waitcnt lgkmcnt(0)
	v_mfma_f32_16x16x32_bf16 v[126:129], v[130:133], v[172:175], v[126:129]
	v_mfma_f32_16x16x32_bf16 v[122:125], v[138:141], v[172:175], v[122:125]
	v_mfma_f32_16x16x32_bf16 v[118:121], v[130:133], v[180:183], v[118:121]
	v_mfma_f32_16x16x32_bf16 v[114:117], v[138:141], v[180:183], v[114:117]
	v_mfma_f32_16x16x32_bf16 v[102:105], v[130:133], v[190:193], v[102:105]
	v_mfma_f32_16x16x32_bf16 v[98:101], v[138:141], v[190:193], v[98:101]
	v_mfma_f32_16x16x32_bf16 v[86:89], v[130:133], v[212:215], v[86:89]
	v_mfma_f32_16x16x32_bf16 v[82:85], v[138:141], v[212:215], v[82:85]
	v_mfma_f32_16x16x32_bf16 v[126:129], v[134:137], v[176:179], v[126:129]
	v_mfma_f32_16x16x32_bf16 v[122:125], v[142:145], v[176:179], v[122:125]
	v_mfma_f32_16x16x32_bf16 v[118:121], v[134:137], v[184:187], v[118:121]
	v_mfma_f32_16x16x32_bf16 v[114:117], v[142:145], v[184:187], v[114:117]
	v_mfma_f32_16x16x32_bf16 v[102:105], v[134:137], v[208:211], v[102:105]
	v_mfma_f32_16x16x32_bf16 v[98:101], v[142:145], v[208:211], v[98:101]
	v_mfma_f32_16x16x32_bf16 v[86:89], v[134:137], v[216:219], v[86:89]
	v_mfma_f32_16x16x32_bf16 v[82:85], v[142:145], v[216:219], v[82:85]
	v_mfma_f32_16x16x32_bf16 v[110:113], v[146:149], v[172:175], v[110:113]
	v_mfma_f32_16x16x32_bf16 v[106:109], v[154:157], v[172:175], v[106:109]
	v_mfma_f32_16x16x32_bf16 v[94:97], v[146:149], v[180:183], v[94:97]
	v_mfma_f32_16x16x32_bf16 v[90:93], v[154:157], v[180:183], v[90:93]
	v_mfma_f32_16x16x32_bf16 v[78:81], v[146:149], v[190:193], v[78:81]
	v_mfma_f32_16x16x32_bf16 v[74:77], v[154:157], v[190:193], v[74:77]
	v_mfma_f32_16x16x32_bf16 v[70:73], v[146:149], v[212:215], v[70:73]
	v_mfma_f32_16x16x32_bf16 v[66:69], v[154:157], v[212:215], v[66:69]
	v_mfma_f32_16x16x32_bf16 v[110:113], v[150:153], v[176:179], v[110:113]
	v_mfma_f32_16x16x32_bf16 v[106:109], v[158:161], v[176:179], v[106:109]
	v_mfma_f32_16x16x32_bf16 v[94:97], v[150:153], v[184:187], v[94:97]
	v_mfma_f32_16x16x32_bf16 v[90:93], v[158:161], v[184:187], v[90:93]
	v_mfma_f32_16x16x32_bf16 v[78:81], v[150:153], v[208:211], v[78:81]
	v_mfma_f32_16x16x32_bf16 v[74:77], v[158:161], v[208:211], v[74:77]
	v_mfma_f32_16x16x32_bf16 v[70:73], v[150:153], v[216:219], v[70:73]
	v_mfma_f32_16x16x32_bf16 v[66:69], v[158:161], v[216:219], v[66:69]
	s_barrier
; #define PG8_STAGE(bufoff, gbase, voff) do { _Pragma("unroll") for (int _i = 0; _i < 2; ++_i) \
;         __builtin_amdgcn_global_load_lds((const unsigned*)((const char*)(gbase) + (voff)[_i]), (PG8_LAS unsigned*)(lds + (bufoff) + ldsw + _i * 8192), 16, 0, 0); } while (0)
; #define PG8_LDA(dst, b, h) do { _Pragma("unroll") for (int m = 0; m < 4; ++m) _Pragma("unroll") for (int k = 0; k < 2; ++k) dst[m][k] = *(const PG8_LAS bf16x8*)(lds + PG8_SA(b, h) + aoff + m * 2048 + k * 1024); } while (0)
; #define PG8_MMA(ai, bj, At, Bt) do { __builtin_amdgcn_s_setprio(1); _Pragma("unroll") for (int m = 0; m < 4; ++m) _Pragma("unroll") for (int n = 0; n < 2; ++n) _Pragma("unroll") for (int k = 0; k < 2; ++k) \
;         acc[ai][bj][m][n] = __builtin_amdgcn_mfma_f32_16x16x32_bf16(Bt[n][k], At[m][k], acc[ai][bj][m][n], 0, 0, 0); __builtin_amdgcn_s_setprio(0); } while (0)
; #define PG8_WAIT_V(n) asm volatile("s_waitcnt vmcnt(" #n ")" ::: "memory")
; #define PG8_WAIT_L(n) asm volatile("s_waitcnt lgkmcnt(" #n ")" ::: "memory")
; #define PG8_BAR __builtin_amdgcn_s_barrier()
; #define PG8_SCHED __builtin_amdgcn_sched_barrier(0)
; template <class Epi, class Sched, bool ALIGN_EPI = false, bool SP2 = false>
; __device__ __forceinline__ void gemm_phase(PG8_LAS unsigned char* lds, const Gemm g, const Sched& S, const Epi& E, int wid_in) {
;     ...
;             PG8_LDA(At, 1, 1); PG8_STAGE(PG8_SB(1, 0), b3, voffB); PG8_STAGE(PG8_SB(1, 1), b3 + hstep, voffB); PG8_STAGE(PG8_SA(1, 0), a3, voffA);
;             PG8_WAIT_V(8); PG8_WAIT_L(0); PG8_BAR; PG8_MMA(1, 0, At, B0); PG8_MMA(1, 1, At, B1); PG8_BAR; PG8_SCHED;
;     ...
;         if constexpr (ALIGN_EPI) { if (wr == 0) PG8_BAR; }
	s_setprio 1
	s_add_i32 s36, s40, s59
	v_lshl_add_u64 v[220:221], v[220:221], 0, s[94:95]
	s_mov_b32 m0, s36
	ds_read_b128 v[172:175], v189 offset:49152
	ds_read_b128 v[176:179], v189 offset:50176
	ds_read_b128 v[180:183], v189 offset:51200
	ds_read_b128 v[184:187], v189 offset:52224
	ds_read_b128 v[190:193], v189 offset:53248
	ds_read_b128 v[208:211], v189 offset:54272
	ds_read_b128 v[212:215], v189 offset:55296
	ds_read_b128 v[216:219], v189 offset:56320
	global_load_lds_dwordx4 v[220:221], off
	s_add_i32 m0, s36, 0x2000
	s_add_u32 s34, s34, 0x40080
	v_lshl_add_u64 v[220:221], v[222:223], 0, s[94:95]
	s_addc_u32 s35, s35, 0
	s_add_i32 s36, s41, s59
	global_load_lds_dwordx4 v[220:221], off
	v_lshl_add_u64 v[220:221], s[34:35], 0, v[0:1]
	s_mov_b32 m0, s36
	s_nop 0
	global_load_lds_dwordx4 v[220:221], off
	v_lshl_add_u64 v[220:221], s[34:35], 0, v[166:167]
	s_add_i32 m0, s36, 0x2000
	s_nop 0
	global_load_lds_dwordx4 v[220:221], off
	v_lshl_add_u64 v[220:221], v[224:225], 0, s[94:95]
	s_mov_b32 m0, s88
	s_nop 0
	global_load_lds_dwordx4 v[220:221], off
	v_lshl_add_u64 v[220:221], v[226:227], 0, s[94:95]
	s_mov_b32 m0, s89
	s_nop 0
	global_load_lds_dwordx4 v[220:221], off
	s_waitcnt vmcnt(8)
	s_waitcnt lgkmcnt(0)
	s_barrier
	s_setprio 0
	s_waitcnt lgkmcnt(0)
	v_mfma_f32_16x16x32_bf16 v[62:65], v[130:133], v[172:175], v[62:65]
	v_mfma_f32_16x16x32_bf16 v[58:61], v[138:141], v[172:175], v[58:61]
	v_mfma_f32_16x16x32_bf16 v[54:57], v[130:133], v[180:183], v[54:57]
	v_mfma_f32_16x16x32_bf16 v[50:53], v[138:141], v[180:183], v[50:53]
	v_mfma_f32_16x16x32_bf16 v[38:41], v[130:133], v[190:193], v[38:41]
	v_mfma_f32_16x16x32_bf16 v[34:37], v[138:141], v[190:193], v[34:37]
	v_mfma_f32_16x16x32_bf16 v[22:25], v[130:133], v[212:215], v[22:25]
	v_mfma_f32_16x16x32_bf16 v[18:21], v[138:141], v[212:215], v[18:21]
	v_mfma_f32_16x16x32_bf16 v[62:65], v[134:137], v[176:179], v[62:65]
	v_mfma_f32_16x16x32_bf16 v[58:61], v[142:145], v[176:179], v[58:61]
	v_mfma_f32_16x16x32_bf16 v[54:57], v[134:137], v[184:187], v[54:57]
	v_mfma_f32_16x16x32_bf16 v[50:53], v[142:145], v[184:187], v[50:53]
	v_mfma_f32_16x16x32_bf16 v[38:41], v[134:137], v[208:211], v[38:41]
	v_mfma_f32_16x16x32_bf16 v[34:37], v[142:145], v[208:211], v[34:37]
	v_mfma_f32_16x16x32_bf16 v[22:25], v[134:137], v[216:219], v[22:25]
	v_mfma_f32_16x16x32_bf16 v[18:21], v[142:145], v[216:219], v[18:21]
	v_mfma_f32_16x16x32_bf16 v[46:49], v[146:149], v[172:175], v[46:49]
	v_mfma_f32_16x16x32_bf16 v[42:45], v[154:157], v[172:175], v[42:45]
	v_mfma_f32_16x16x32_bf16 v[30:33], v[146:149], v[180:183], v[30:33]
	v_mfma_f32_16x16x32_bf16 v[26:29], v[154:157], v[180:183], v[26:29]
	v_mfma_f32_16x16x32_bf16 v[14:17], v[146:149], v[190:193], v[14:17]
	v_mfma_f32_16x16x32_bf16 v[10:13], v[154:157], v[190:193], v[10:13]
	v_mfma_f32_16x16x32_bf16 v[6:9], v[146:149], v[212:215], v[6:9]
	v_mfma_f32_16x16x32_bf16 v[2:5], v[154:157], v[212:215], v[2:5]
	v_mfma_f32_16x16x32_bf16 v[46:49], v[150:153], v[176:179], v[46:49]
	v_mfma_f32_16x16x32_bf16 v[42:45], v[158:161], v[176:179], v[42:45]
	v_mfma_f32_16x16x32_bf16 v[30:33], v[150:153], v[184:187], v[30:33]
	v_mfma_f32_16x16x32_bf16 v[26:29], v[158:161], v[184:187], v[26:29]
	v_mfma_f32_16x16x32_bf16 v[14:17], v[150:153], v[208:211], v[14:17]
	v_mfma_f32_16x16x32_bf16 v[10:13], v[158:161], v[208:211], v[10:13]
	v_mfma_f32_16x16x32_bf16 v[6:9], v[150:153], v[216:219], v[6:9]
	v_mfma_f32_16x16x32_bf16 v[2:5], v[158:161], v[216:219], v[2:5]
	s_barrier
	s_setprio 1
	s_add_u32 vcc_hi, vcc_hi, 0x100
	s_addc_u32 s63, s63, 0
	s_add_u32 s30, s30, 0x100
	s_addc_u32 s31, s31, 0
	s_cmp_ge_i32 s56, s1
	s_mov_b32 s34, s56
	s_cbranch_scc0 .LBB0_848
	s_setprio 0
	s_and_b64 vcc, exec, s[12:13]
	s_cbranch_vccz .LBB0_851
	s_barrier

; #define PG8_STAGE(bufoff, gbase, voff) do { _Pragma("unroll") for (int _i = 0; _i < 2; ++_i) \
;         __builtin_amdgcn_global_load_lds((const unsigned*)((const char*)(gbase) + (voff)[_i]), (PG8_LAS unsigned*)(lds + (bufoff) + ldsw + _i * 8192), 16, 0, 0); } while (0)
; #define PG8_LDA(dst, b, h) do { _Pragma("unroll") for (int m = 0; m < 4; ++m) _Pragma("unroll") for (int k = 0; k < 2; ++k) dst[m][k] = *(const PG8_LAS bf16x8*)(lds + PG8_SA(b, h) + aoff + m * 2048 + k * 1024); } while (0)
; #define PG8_LDB(dst, b, h) do { _Pragma("unroll") for (int n = 0; n < 2; ++n) _Pragma("unroll") for (int k = 0; k < 2; ++k) dst[n][k] = *(const PG8_LAS bf16x8*)(lds + PG8_SB(b, h) + boff + n * 2048 + k * 1024); } while (0)
; #define PG8_MMA(ai, bj, At, Bt) do { __builtin_amdgcn_s_setprio(1); _Pragma("unroll") for (int m = 0; m < 4; ++m) _Pragma("unroll") for (int n = 0; n < 2; ++n) _Pragma("unroll") for (int k = 0; k < 2; ++k) \
;         acc[ai][bj][m][n] = __builtin_amdgcn_mfma_f32_16x16x32_bf16(Bt[n][k], At[m][k], acc[ai][bj][m][n], 0, 0, 0); __builtin_amdgcn_s_setprio(0); } while (0)
; #define PG8_WAIT_V(n) asm volatile("s_waitcnt vmcnt(" #n ")" ::: "memory")
; #define PG8_BAR __builtin_amdgcn_s_barrier()
; template <class Epi, class Sched, bool ALIGN_EPI = false, bool SP2 = false>
; __device__ __forceinline__ void gemm_phase(PG8_LAS unsigned char* lds, const Gemm g, const Sched& S, const Epi& E, int wid_in) {
;     ...
;         for (int t = 0; t < nt; t += 2) {
;             const bool last = (t == nt - 2);
;             const char* a1 = cA + (size_t)(t + 1) * kstep;
;             const char* a2 = last ? nA : cA + (size_t)(t + 2) * kstep; const char* b2 = last ? nB : cB + (size_t)(t + 2) * kstep;
;             const char* a3 = a2 + kstep; const char* b3 = b2 + kstep;
;             if (last && has_next) S.a_ready(nxt);
;             if constexpr (SP2) {
;             PG8_LDB(B0, 0, 0); PG8_LDB(B1, 0, 1); PG8_SCHED; PG8_LDA(At, 0, 0); PG8_STAGE(PG8_SA(1, 1), a1 + hstep, voffA);
;             PG8_WAIT_V(8); PG8_WAIT_L(0); PG8_BAR; PG8_MMA(0, 0, At, B0); PG8_MMA(0, 1, At, B1); PG8_BAR; PG8_SCHED;
;             PG8_LDA(At, 0, 1); PG8_STAGE(PG8_SB(0, 0), b2, voffB); PG8_STAGE(PG8_SB(0, 1), b2 + hstep, voffB); PG8_STAGE(PG8_SA(0, 0), a2, voffA);
;             PG8_WAIT_V(8); PG8_WAIT_L(0); PG8_BAR; PG8_MMA(1, 0, At, B0); PG8_MMA(1, 1, At, B1); PG8_BAR; PG8_SCHED;
.Lprio_skip_2:
.LBB0_880:
	s_add_i32 s56, s34, 2
	s_add_u32 s35, s30, 0xfffc0080
	s_addc_u32 s36, s31, -1
	s_add_i32 s40, 0, 0x10000
	s_cmp_eq_u32 vcc_lo, s34
	s_cselect_b32 s37, s15, s36
	s_cselect_b32 s36, s19, s35
	s_cselect_b32 s35, s17, s63
	s_cselect_b32 s34, s27, vcc_hi
	s_add_i32 s42, 0, 0x14000
	v_add_u32_e32 v142, s40, v195
	v_add_u32_e32 v158, s42, v195
	ds_read_b128 v[130:133], v142
	ds_read_b128 v[134:137], v142 offset:1024
	ds_read_b128 v[138:141], v142 offset:2048
	ds_read_b128 v[142:145], v142 offset:3072
	ds_read_b128 v[146:149], v158
	ds_read_b128 v[150:153], v158 offset:1024
	ds_read_b128 v[154:157], v158 offset:2048
	ds_read_b128 v[158:161], v158 offset:3072
	v_lshl_add_u64 v[218:219], s[30:31], 0, v[216:217]
	s_add_i32 m0, s29, 0xc000
	ds_read_b128 v[162:165], v251
	ds_read_b128 v[166:169], v251 offset:1024
	ds_read_b128 v[170:173], v251 offset:2048
	ds_read_b128 v[174:177], v251 offset:3072
	ds_read_b128 v[178:181], v251 offset:4096
	ds_read_b128 v[182:185], v251 offset:5120
	ds_read_b128 v[186:189], v251 offset:6144
	ds_read_b128 v[190:193], v251 offset:7168
	global_load_lds_dwordx4 v[218:219], off
	v_lshl_add_u64 v[218:219], s[30:31], 0, v[214:215]
	s_add_i32 m0, s29, 0xe000
	s_nop 0
	global_load_lds_dwordx4 v[218:219], off
	s_waitcnt vmcnt(8)
	s_waitcnt lgkmcnt(0)
	s_barrier
	s_setprio 0
	s_waitcnt lgkmcnt(0)
	v_mfma_f32_16x16x32_bf16 v[126:129], v[130:133], v[162:165], v[126:129]
	v_mfma_f32_16x16x32_bf16 v[122:125], v[138:141], v[162:165], v[122:125]
	v_mfma_f32_16x16x32_bf16 v[118:121], v[130:133], v[170:173], v[118:121]
	v_mfma_f32_16x16x32_bf16 v[114:117], v[138:141], v[170:173], v[114:117]
	v_mfma_f32_16x16x32_bf16 v[102:105], v[130:133], v[178:181], v[102:105]
	v_mfma_f32_16x16x32_bf16 v[98:101], v[138:141], v[178:181], v[98:101]
	v_mfma_f32_16x16x32_bf16 v[86:89], v[130:133], v[186:189], v[86:89]
	v_mfma_f32_16x16x32_bf16 v[82:85], v[138:141], v[186:189], v[82:85]
	v_mfma_f32_16x16x32_bf16 v[126:129], v[134:137], v[166:169], v[126:129]
	v_mfma_f32_16x16x32_bf16 v[122:125], v[142:145], v[166:169], v[122:125]
	v_mfma_f32_16x16x32_bf16 v[118:121], v[134:137], v[174:177], v[118:121]
	v_mfma_f32_16x16x32_bf16 v[114:117], v[142:145], v[174:177], v[114:117]
	v_mfma_f32_16x16x32_bf16 v[102:105], v[134:137], v[182:185], v[102:105]
	v_mfma_f32_16x16x32_bf16 v[98:101], v[142:145], v[182:185], v[98:101]
	v_mfma_f32_16x16x32_bf16 v[86:89], v[134:137], v[190:193], v[86:89]
	v_mfma_f32_16x16x32_bf16 v[82:85], v[142:145], v[190:193], v[82:85]
	v_mfma_f32_16x16x32_bf16 v[110:113], v[146:149], v[162:165], v[110:113]
	v_mfma_f32_16x16x32_bf16 v[106:109], v[154:157], v[162:165], v[106:109]
	v_mfma_f32_16x16x32_bf16 v[94:97], v[146:149], v[170:173], v[94:97]
	v_mfma_f32_16x16x32_bf16 v[90:93], v[154:157], v[170:173], v[90:93]
	v_mfma_f32_16x16x32_bf16 v[78:81], v[146:149], v[178:181], v[78:81]
	v_mfma_f32_16x16x32_bf16 v[74:77], v[154:157], v[178:181], v[74:77]
	v_mfma_f32_16x16x32_bf16 v[70:73], v[146:149], v[186:189], v[70:73]
	v_mfma_f32_16x16x32_bf16 v[66:69], v[154:157], v[186:189], v[66:69]
	v_mfma_f32_16x16x32_bf16 v[110:113], v[150:153], v[166:169], v[110:113]
	v_mfma_f32_16x16x32_bf16 v[106:109], v[158:161], v[166:169], v[106:109]
	v_mfma_f32_16x16x32_bf16 v[94:97], v[150:153], v[174:177], v[94:97]
	v_mfma_f32_16x16x32_bf16 v[90:93], v[158:161], v[174:177], v[90:93]
	v_mfma_f32_16x16x32_bf16 v[78:81], v[150:153], v[182:185], v[78:81]
	v_mfma_f32_16x16x32_bf16 v[74:77], v[158:161], v[182:185], v[74:77]
	v_mfma_f32_16x16x32_bf16 v[70:73], v[150:153], v[190:193], v[70:73]
	v_mfma_f32_16x16x32_bf16 v[66:69], v[158:161], v[190:193], v[66:69]
	s_barrier
	s_setprio 1
	s_add_i32 s40, s40, s59
	v_lshl_add_u64 v[218:219], s[34:35], 0, v[0:1]
	s_mov_b32 m0, s40
	ds_read_b128 v[162:165], v251 offset:16384
	ds_read_b128 v[166:169], v251 offset:17408
	ds_read_b128 v[170:173], v251 offset:18432
	ds_read_b128 v[174:177], v251 offset:19456
	ds_read_b128 v[178:181], v251 offset:20480
	ds_read_b128 v[182:185], v251 offset:21504
	ds_read_b128 v[186:189], v251 offset:22528
	ds_read_b128 v[190:193], v251 offset:23552
	global_load_lds_dwordx4 v[218:219], off
	s_add_i32 m0, s40, 0x2000
	s_add_u32 s40, s34, 0x40000
	v_lshl_add_u64 v[220:221], s[34:35], 0, v[212:213]
	s_addc_u32 s41, s35, 0
	s_add_i32 s42, s42, s59
	global_load_lds_dwordx4 v[220:221], off
	v_lshl_add_u64 v[222:223], s[40:41], 0, v[0:1]
	s_mov_b32 m0, s42
	v_lshl_add_u64 v[224:225], s[36:37], 0, v[210:211]
	global_load_lds_dwordx4 v[222:223], off
	v_lshl_add_u64 v[222:223], s[40:41], 0, v[212:213]
	s_add_i32 m0, s42, 0x2000
	s_nop 0
	global_load_lds_dwordx4 v[222:223], off
	v_lshl_add_u64 v[222:223], s[36:37], 0, v[208:209]
	s_mov_b32 m0, s29
	s_nop 0
	global_load_lds_dwordx4 v[222:223], off
	s_mov_b32 m0, s48
	s_nop 0
	global_load_lds_dwordx4 v[224:225], off
	s_waitcnt vmcnt(8)
	s_waitcnt lgkmcnt(0)
	s_barrier
; #define PG8_STAGE(bufoff, gbase, voff) do { _Pragma("unroll") for (int _i = 0; _i < 2; ++_i) \
;         __builtin_amdgcn_global_load_lds((const unsigned*)((const char*)(gbase) + (voff)[_i]), (PG8_LAS unsigned*)(lds + (bufoff) + ldsw + _i * 8192), 16, 0, 0); } while (0)
; #define PG8_LDA(dst, b, h) do { _Pragma("unroll") for (int m = 0; m < 4; ++m) _Pragma("unroll") for (int k = 0; k < 2; ++k) dst[m][k] = *(const PG8_LAS bf16x8*)(lds + PG8_SA(b, h) + aoff + m * 2048 + k * 1024); } while (0)
; #define PG8_LDB(dst, b, h) do { _Pragma("unroll") for (int n = 0; n < 2; ++n) _Pragma("unroll") for (int k = 0; k < 2; ++k) dst[n][k] = *(const PG8_LAS bf16x8*)(lds + PG8_SB(b, h) + boff + n * 2048 + k * 1024); } while (0)
; #define PG8_MMA(ai, bj, At, Bt) do { __builtin_amdgcn_s_setprio(1); _Pragma("unroll") for (int m = 0; m < 4; ++m) _Pragma("unroll") for (int n = 0; n < 2; ++n) _Pragma("unroll") for (int k = 0; k < 2; ++k) \
;         acc[ai][bj][m][n] = __builtin_amdgcn_mfma_f32_16x16x32_bf16(Bt[n][k], At[m][k], acc[ai][bj][m][n], 0, 0, 0); __builtin_amdgcn_s_setprio(0); } while (0)
; #define PG8_WAIT_V(n) asm volatile("s_waitcnt vmcnt(" #n ")" ::: "memory")
; #define PG8_WAIT_L(n) asm volatile("s_waitcnt lgkmcnt(" #n ")" ::: "memory")
; #define PG8_BAR __builtin_amdgcn_s_barrier()
; #define PG8_SCHED __builtin_amdgcn_sched_barrier(0)
; template <class Epi, class Sched, bool ALIGN_EPI = false, bool SP2 = false>
; __device__ __forceinline__ void gemm_phase(PG8_LAS unsigned char* lds, const Gemm g, const Sched& S, const Epi& E, int wid_in) {
;     ...
;             PG8_WAIT_V(8); PG8_WAIT_L(0); PG8_BAR; PG8_MMA(1, 0, At, B0); PG8_MMA(1, 1, At, B1); PG8_BAR; PG8_SCHED;
;             PG8_LDB(B0, 1, 0); PG8_LDB(B1, 1, 1); PG8_SCHED; PG8_LDA(At, 1, 0); PG8_STAGE(PG8_SA(0, 1), a2 + hstep, voffA);
;             PG8_WAIT_V(8); PG8_WAIT_L(0); PG8_BAR; PG8_MMA(0, 0, At, B0); PG8_MMA(0, 1, At, B1); PG8_BAR; PG8_SCHED;
	s_setprio 0
	s_waitcnt lgkmcnt(0)
	v_mfma_f32_16x16x32_bf16 v[62:65], v[130:133], v[162:165], v[62:65]
	v_mfma_f32_16x16x32_bf16 v[58:61], v[138:141], v[162:165], v[58:61]
	v_mfma_f32_16x16x32_bf16 v[54:57], v[130:133], v[170:173], v[54:57]
	v_mfma_f32_16x16x32_bf16 v[50:53], v[138:141], v[170:173], v[50:53]
	v_mfma_f32_16x16x32_bf16 v[38:41], v[130:133], v[178:181], v[38:41]
	v_mfma_f32_16x16x32_bf16 v[34:37], v[138:141], v[178:181], v[34:37]
	v_mfma_f32_16x16x32_bf16 v[22:25], v[130:133], v[186:189], v[22:25]
	v_mfma_f32_16x16x32_bf16 v[18:21], v[138:141], v[186:189], v[18:21]
	v_mfma_f32_16x16x32_bf16 v[62:65], v[134:137], v[166:169], v[62:65]
	v_mfma_f32_16x16x32_bf16 v[58:61], v[142:145], v[166:169], v[58:61]
	v_mfma_f32_16x16x32_bf16 v[54:57], v[134:137], v[174:177], v[54:57]
	v_mfma_f32_16x16x32_bf16 v[50:53], v[142:145], v[174:177], v[50:53]
	v_mfma_f32_16x16x32_bf16 v[38:41], v[134:137], v[182:185], v[38:41]
	v_mfma_f32_16x16x32_bf16 v[34:37], v[142:145], v[182:185], v[34:37]
	v_mfma_f32_16x16x32_bf16 v[22:25], v[134:137], v[190:193], v[22:25]
	v_mfma_f32_16x16x32_bf16 v[18:21], v[142:145], v[190:193], v[18:21]
	v_mfma_f32_16x16x32_bf16 v[46:49], v[146:149], v[162:165], v[46:49]
	v_mfma_f32_16x16x32_bf16 v[42:45], v[154:157], v[162:165], v[42:45]
	v_mfma_f32_16x16x32_bf16 v[30:33], v[146:149], v[170:173], v[30:33]
	v_mfma_f32_16x16x32_bf16 v[26:29], v[154:157], v[170:173], v[26:29]
	v_mfma_f32_16x16x32_bf16 v[14:17], v[146:149], v[178:181], v[14:17]
	v_mfma_f32_16x16x32_bf16 v[10:13], v[154:157], v[178:181], v[10:13]
	v_mfma_f32_16x16x32_bf16 v[6:9], v[146:149], v[186:189], v[6:9]
	v_mfma_f32_16x16x32_bf16 v[2:5], v[154:157], v[186:189], v[2:5]
	v_mfma_f32_16x16x32_bf16 v[46:49], v[150:153], v[166:169], v[46:49]
	v_mfma_f32_16x16x32_bf16 v[42:45], v[158:161], v[166:169], v[42:45]
	v_mfma_f32_16x16x32_bf16 v[30:33], v[150:153], v[174:177], v[30:33]
	v_mfma_f32_16x16x32_bf16 v[26:29], v[158:161], v[174:177], v[26:29]
	v_mfma_f32_16x16x32_bf16 v[14:17], v[150:153], v[182:185], v[14:17]
	v_mfma_f32_16x16x32_bf16 v[10:13], v[158:161], v[182:185], v[10:13]
	v_mfma_f32_16x16x32_bf16 v[6:9], v[150:153], v[190:193], v[6:9]
	v_mfma_f32_16x16x32_bf16 v[2:5], v[158:161], v[190:193], v[2:5]
	s_barrier
	s_setprio 1
	s_add_i32 s40, 0, 0x18000
	s_add_i32 s41, 0, 0x1c000
	v_add_u32_e32 v142, s40, v195
	v_add_u32_e32 v158, s41, v195
	ds_read_b128 v[130:133], v142
	ds_read_b128 v[134:137], v142 offset:1024
	ds_read_b128 v[138:141], v142 offset:2048
	ds_read_b128 v[142:145], v142 offset:3072
	ds_read_b128 v[146:149], v158
	ds_read_b128 v[150:153], v158 offset:1024
	ds_read_b128 v[154:157], v158 offset:2048
	ds_read_b128 v[158:161], v158 offset:3072
	s_add_u32 s36, s36, 0x40000
	s_addc_u32 s37, s37, 0
	s_mov_b32 m0, s61
	v_lshl_add_u64 v[226:227], s[36:37], 0, v[208:209]
	ds_read_b128 v[162:165], v251 offset:32768
	ds_read_b128 v[166:169], v251 offset:33792
	ds_read_b128 v[170:173], v251 offset:34816
	ds_read_b128 v[174:177], v251 offset:35840
	ds_read_b128 v[178:181], v251 offset:36864
	ds_read_b128 v[182:185], v251 offset:37888
	ds_read_b128 v[186:189], v251 offset:38912
	ds_read_b128 v[190:193], v251 offset:39936
	global_load_lds_dwordx4 v[226:227], off
	v_lshl_add_u64 v[226:227], s[36:37], 0, v[210:211]
	s_mov_b32 m0, s62
	s_nop 0
	global_load_lds_dwordx4 v[226:227], off
	s_waitcnt vmcnt(8)
	s_waitcnt lgkmcnt(0)
	s_barrier
	s_setprio 0
	s_waitcnt lgkmcnt(0)
	v_mfma_f32_16x16x32_bf16 v[126:129], v[130:133], v[162:165], v[126:129]
	v_mfma_f32_16x16x32_bf16 v[122:125], v[138:141], v[162:165], v[122:125]
	v_mfma_f32_16x16x32_bf16 v[118:121], v[130:133], v[170:173], v[118:121]
	v_mfma_f32_16x16x32_bf16 v[114:117], v[138:141], v[170:173], v[114:117]
	v_mfma_f32_16x16x32_bf16 v[102:105], v[130:133], v[178:181], v[102:105]
	v_mfma_f32_16x16x32_bf16 v[98:101], v[138:141], v[178:181], v[98:101]
	v_mfma_f32_16x16x32_bf16 v[86:89], v[130:133], v[186:189], v[86:89]
	v_mfma_f32_16x16x32_bf16 v[82:85], v[138:141], v[186:189], v[82:85]
	v_mfma_f32_16x16x32_bf16 v[126:129], v[134:137], v[166:169], v[126:129]
	v_mfma_f32_16x16x32_bf16 v[122:125], v[142:145], v[166:169], v[122:125]
	v_mfma_f32_16x16x32_bf16 v[118:121], v[134:137], v[174:177], v[118:121]
	v_mfma_f32_16x16x32_bf16 v[114:117], v[142:145], v[174:177], v[114:117]
	v_mfma_f32_16x16x32_bf16 v[102:105], v[134:137], v[182:185], v[102:105]
	v_mfma_f32_16x16x32_bf16 v[98:101], v[142:145], v[182:185], v[98:101]
	v_mfma_f32_16x16x32_bf16 v[86:89], v[134:137], v[190:193], v[86:89]
	v_mfma_f32_16x16x32_bf16 v[82:85], v[142:145], v[190:193], v[82:85]
	v_mfma_f32_16x16x32_bf16 v[110:113], v[146:149], v[162:165], v[110:113]
	v_mfma_f32_16x16x32_bf16 v[106:109], v[154:157], v[162:165], v[106:109]
	v_mfma_f32_16x16x32_bf16 v[94:97], v[146:149], v[170:173], v[94:97]
	v_mfma_f32_16x16x32_bf16 v[90:93], v[154:157], v[170:173], v[90:93]
	v_mfma_f32_16x16x32_bf16 v[78:81], v[146:149], v[178:181], v[78:81]
	v_mfma_f32_16x16x32_bf16 v[74:77], v[154:157], v[178:181], v[74:77]
	v_mfma_f32_16x16x32_bf16 v[70:73], v[146:149], v[186:189], v[70:73]
	v_mfma_f32_16x16x32_bf16 v[66:69], v[154:157], v[186:189], v[66:69]
	v_mfma_f32_16x16x32_bf16 v[110:113], v[150:153], v[166:169], v[110:113]
	v_mfma_f32_16x16x32_bf16 v[106:109], v[158:161], v[166:169], v[106:109]
	v_mfma_f32_16x16x32_bf16 v[94:97], v[150:153], v[174:177], v[94:97]
	v_mfma_f32_16x16x32_bf16 v[90:93], v[158:161], v[174:177], v[90:93]
	v_mfma_f32_16x16x32_bf16 v[78:81], v[150:153], v[182:185], v[78:81]
	v_mfma_f32_16x16x32_bf16 v[74:77], v[158:161], v[182:185], v[74:77]
	v_mfma_f32_16x16x32_bf16 v[70:73], v[150:153], v[190:193], v[70:73]
	v_mfma_f32_16x16x32_bf16 v[66:69], v[158:161], v[190:193], v[66:69]
	s_barrier
; #define PG8_STAGE(bufoff, gbase, voff) do { _Pragma("unroll") for (int _i = 0; _i < 2; ++_i) \
;         __builtin_amdgcn_global_load_lds((const unsigned*)((const char*)(gbase) + (voff)[_i]), (PG8_LAS unsigned*)(lds + (bufoff) + ldsw + _i * 8192), 16, 0, 0); } while (0)
; #define PG8_LDA(dst, b, h) do { _Pragma("unroll") for (int m = 0; m < 4; ++m) _Pragma("unroll") for (int k = 0; k < 2; ++k) dst[m][k] = *(const PG8_LAS bf16x8*)(lds + PG8_SA(b, h) + aoff + m * 2048 + k * 1024); } while (0)
; #define PG8_MMA(ai, bj, At, Bt) do { __builtin_amdgcn_s_setprio(1); _Pragma("unroll") for (int m = 0; m < 4; ++m) _Pragma("unroll") for (int n = 0; n < 2; ++n) _Pragma("unroll") for (int k = 0; k < 2; ++k) \
;         acc[ai][bj][m][n] = __builtin_amdgcn_mfma_f32_16x16x32_bf16(Bt[n][k], At[m][k], acc[ai][bj][m][n], 0, 0, 0); __builtin_amdgcn_s_setprio(0); } while (0)
; #define PG8_WAIT_V(n) asm volatile("s_waitcnt vmcnt(" #n ")" ::: "memory")
; #define PG8_WAIT_L(n) asm volatile("s_waitcnt lgkmcnt(" #n ")" ::: "memory")
; #define PG8_BAR __builtin_amdgcn_s_barrier()
; #define PG8_SCHED __builtin_amdgcn_sched_barrier(0)
; template <class Epi, class Sched, bool ALIGN_EPI = false, bool SP2 = false>
; __device__ __forceinline__ void gemm_phase(PG8_LAS unsigned char* lds, const Gemm g, const Sched& S, const Epi& E, int wid_in) {
;     ...
;             PG8_LDA(At, 1, 1); PG8_STAGE(PG8_SB(1, 0), b3, voffB); PG8_STAGE(PG8_SB(1, 1), b3 + hstep, voffB); PG8_STAGE(PG8_SA(1, 0), a3, voffA);
;             PG8_WAIT_V(8); PG8_WAIT_L(0); PG8_BAR; PG8_MMA(1, 0, At, B0); PG8_MMA(1, 1, At, B1); PG8_BAR; PG8_SCHED;
;     ...
;         if constexpr (ALIGN_EPI) { if (wr == 0) PG8_BAR; }
	s_setprio 1
	s_add_i32 s36, s40, s59
	v_lshl_add_u64 v[218:219], v[218:219], 0, s[94:95]
	s_mov_b32 m0, s36
	ds_read_b128 v[162:165], v251 offset:49152
	ds_read_b128 v[166:169], v251 offset:50176
	ds_read_b128 v[170:173], v251 offset:51200
	ds_read_b128 v[174:177], v251 offset:52224
	ds_read_b128 v[178:181], v251 offset:53248
	ds_read_b128 v[182:185], v251 offset:54272
	ds_read_b128 v[186:189], v251 offset:55296
	ds_read_b128 v[190:193], v251 offset:56320
	global_load_lds_dwordx4 v[218:219], off
	s_add_i32 m0, s36, 0x2000
	s_add_u32 s34, s34, 0x40080
	v_lshl_add_u64 v[218:219], v[220:221], 0, s[94:95]
	s_addc_u32 s35, s35, 0
	s_add_i32 s36, s41, s59
	global_load_lds_dwordx4 v[218:219], off
	v_lshl_add_u64 v[218:219], s[34:35], 0, v[0:1]
	s_mov_b32 m0, s36
	s_nop 0
	global_load_lds_dwordx4 v[218:219], off
	v_lshl_add_u64 v[218:219], s[34:35], 0, v[212:213]
	s_add_i32 m0, s36, 0x2000
	s_nop 0
	global_load_lds_dwordx4 v[218:219], off
	v_lshl_add_u64 v[218:219], v[222:223], 0, s[94:95]
	s_mov_b32 m0, s89
	s_nop 0
	global_load_lds_dwordx4 v[218:219], off
	v_lshl_add_u64 v[218:219], v[224:225], 0, s[94:95]
	s_mov_b32 m0, s90
	s_nop 0
	global_load_lds_dwordx4 v[218:219], off
	s_waitcnt vmcnt(8)
	s_waitcnt lgkmcnt(0)
	s_barrier
	s_setprio 0
	s_waitcnt lgkmcnt(0)
	v_mfma_f32_16x16x32_bf16 v[62:65], v[130:133], v[162:165], v[62:65]
	v_mfma_f32_16x16x32_bf16 v[58:61], v[138:141], v[162:165], v[58:61]
	v_mfma_f32_16x16x32_bf16 v[54:57], v[130:133], v[170:173], v[54:57]
	v_mfma_f32_16x16x32_bf16 v[50:53], v[138:141], v[170:173], v[50:53]
	v_mfma_f32_16x16x32_bf16 v[38:41], v[130:133], v[178:181], v[38:41]
	v_mfma_f32_16x16x32_bf16 v[34:37], v[138:141], v[178:181], v[34:37]
	v_mfma_f32_16x16x32_bf16 v[22:25], v[130:133], v[186:189], v[22:25]
	v_mfma_f32_16x16x32_bf16 v[18:21], v[138:141], v[186:189], v[18:21]
	v_mfma_f32_16x16x32_bf16 v[62:65], v[134:137], v[166:169], v[62:65]
	v_mfma_f32_16x16x32_bf16 v[58:61], v[142:145], v[166:169], v[58:61]
	v_mfma_f32_16x16x32_bf16 v[54:57], v[134:137], v[174:177], v[54:57]
	v_mfma_f32_16x16x32_bf16 v[50:53], v[142:145], v[174:177], v[50:53]
	v_mfma_f32_16x16x32_bf16 v[38:41], v[134:137], v[182:185], v[38:41]
	v_mfma_f32_16x16x32_bf16 v[34:37], v[142:145], v[182:185], v[34:37]
	v_mfma_f32_16x16x32_bf16 v[22:25], v[134:137], v[190:193], v[22:25]
	v_mfma_f32_16x16x32_bf16 v[18:21], v[142:145], v[190:193], v[18:21]
	v_mfma_f32_16x16x32_bf16 v[46:49], v[146:149], v[162:165], v[46:49]
	v_mfma_f32_16x16x32_bf16 v[42:45], v[154:157], v[162:165], v[42:45]
	v_mfma_f32_16x16x32_bf16 v[30:33], v[146:149], v[170:173], v[30:33]
	v_mfma_f32_16x16x32_bf16 v[26:29], v[154:157], v[170:173], v[26:29]
	v_mfma_f32_16x16x32_bf16 v[14:17], v[146:149], v[178:181], v[14:17]
	v_mfma_f32_16x16x32_bf16 v[10:13], v[154:157], v[178:181], v[10:13]
	v_mfma_f32_16x16x32_bf16 v[6:9], v[146:149], v[186:189], v[6:9]
	v_mfma_f32_16x16x32_bf16 v[2:5], v[154:157], v[186:189], v[2:5]
	v_mfma_f32_16x16x32_bf16 v[46:49], v[150:153], v[166:169], v[46:49]
	v_mfma_f32_16x16x32_bf16 v[42:45], v[158:161], v[166:169], v[42:45]
	v_mfma_f32_16x16x32_bf16 v[30:33], v[150:153], v[174:177], v[30:33]
	v_mfma_f32_16x16x32_bf16 v[26:29], v[158:161], v[174:177], v[26:29]
	v_mfma_f32_16x16x32_bf16 v[14:17], v[150:153], v[182:185], v[14:17]
	v_mfma_f32_16x16x32_bf16 v[10:13], v[158:161], v[182:185], v[10:13]
	v_mfma_f32_16x16x32_bf16 v[6:9], v[150:153], v[190:193], v[6:9]
	v_mfma_f32_16x16x32_bf16 v[2:5], v[158:161], v[190:193], v[2:5]
	s_barrier
	s_setprio 1
	s_add_u32 vcc_hi, vcc_hi, 0x100
	s_addc_u32 s63, s63, 0
	s_add_u32 s30, s30, 0x100
	s_addc_u32 s31, s31, 0
	s_cmp_ge_i32 s56, s1
	s_mov_b32 s34, s56
	s_cbranch_scc0 .LBB0_880
	s_setprio 0
	s_and_b64 vcc, exec, s[12:13]
	s_cbranch_vccz .LBB0_883
	s_barrier

; #define PG8_STAGE(bufoff, gbase, voff) do { _Pragma("unroll") for (int _i = 0; _i < 2; ++_i) \
;         __builtin_amdgcn_global_load_lds((const unsigned*)((const char*)(gbase) + (voff)[_i]), (PG8_LAS unsigned*)(lds + (bufoff) + ldsw + _i * 8192), 16, 0, 0); } while (0)
; #define PG8_LDA(dst, b, h) do { _Pragma("unroll") for (int m = 0; m < 4; ++m) _Pragma("unroll") for (int k = 0; k < 2; ++k) dst[m][k] = *(const PG8_LAS bf16x8*)(lds + PG8_SA(b, h) + aoff + m * 2048 + k * 1024); } while (0)
; #define PG8_LDB(dst, b, h) do { _Pragma("unroll") for (int n = 0; n < 2; ++n) _Pragma("unroll") for (int k = 0; k < 2; ++k) dst[n][k] = *(const PG8_LAS bf16x8*)(lds + PG8_SB(b, h) + boff + n * 2048 + k * 1024); } while (0)
; #define PG8_WAIT_V(n) asm volatile("s_waitcnt vmcnt(" #n ")" ::: "memory")
; #define PG8_WAIT_L(n) asm volatile("s_waitcnt lgkmcnt(" #n ")" ::: "memory")
; template <class Epi, class Sched, bool ALIGN_EPI = false, bool SP2 = false>
; __device__ __forceinline__ void gemm_phase(PG8_LAS unsigned char* lds, const Gemm g, const Sched& S, const Epi& E, int wid_in) {
;     ...
;     for (;;) {
;         const bool has_next = S.next(ui + 1, nxt);
;         const char* nA = has_next ? (const char*)g.A + (size_t)nxt.pm * tstep + (size_t)nxt.kt0 * kstep : cA; const char* nB = has_next ? (const char*)g.Bt + (size_t)nxt.pn * tstep + (size_t)nxt.kt0 * kstep : cB;
;         const int nt = cur.nkt;
;         for (int t = 0; t < nt; t += 2) {
;             const bool last = (t == nt - 2);
;             const char* a1 = cA + (size_t)(t + 1) * kstep;
;             const char* a2 = last ? nA : cA + (size_t)(t + 2) * kstep; const char* b2 = last ? nB : cB + (size_t)(t + 2) * kstep;
;             const char* a3 = a2 + kstep; const char* b3 = b2 + kstep;
;             if (last && has_next) S.a_ready(nxt);
;             if constexpr (SP2) {
;             PG8_LDB(B0, 0, 0); PG8_LDB(B1, 0, 1); PG8_SCHED; PG8_LDA(At, 0, 0); PG8_STAGE(PG8_SA(1, 1), a1 + hstep, voffA);
;             PG8_WAIT_V(8); PG8_WAIT_L(0); PG8_BAR; PG8_MMA(0, 0, At, B0); PG8_MMA(0, 1, At, B1); PG8_BAR; PG8_SCHED;
;     ...
; #pragma unroll
;         for (int a = 0; a < 2; ++a)
; #pragma unroll
;             for (int b = 0; b < 2; ++b)
; #pragma unroll
;                 for (int m = 0; m < 4; ++m)
; #pragma unroll
;                     for (int n = 0; n < 2; ++n) acc[a][b][m][n] = (f32x4){0.f, 0.f, 0.f, 0.f};
.LBB0_1020:
	s_add_i32 s17, s90, -2
	s_add_u32 s19, s30, 0x100
	s_addc_u32 s21, s31, 0
	s_add_u32 s30, s34, 0x80080
	v_mov_b32_e32 v2, 0
	s_addc_u32 s31, s35, 0
	s_mov_b32 s27, 0
	v_mov_b32_e32 v3, v2
	v_mov_b32_e32 v4, v2
	v_mov_b32_e32 v5, v2
	v_mov_b32_e32 v6, v2
	v_mov_b32_e32 v7, v2
	v_mov_b32_e32 v8, v2
	v_mov_b32_e32 v9, v2
	v_mov_b32_e32 v10, v2
	v_mov_b32_e32 v11, v2
	v_mov_b32_e32 v12, v2
	v_mov_b32_e32 v13, v2
	v_mov_b32_e32 v14, v2
	v_mov_b32_e32 v15, v2
	v_mov_b32_e32 v16, v2
	v_mov_b32_e32 v17, v2
	v_mov_b32_e32 v26, v2
	v_mov_b32_e32 v27, v2
	v_mov_b32_e32 v28, v2
	v_mov_b32_e32 v29, v2
	v_mov_b32_e32 v30, v2
	v_mov_b32_e32 v31, v2
	v_mov_b32_e32 v32, v2
	v_mov_b32_e32 v33, v2
	v_mov_b32_e32 v42, v2
	v_mov_b32_e32 v43, v2
	v_mov_b32_e32 v44, v2
	v_mov_b32_e32 v45, v2
	v_mov_b32_e32 v46, v2
	v_mov_b32_e32 v47, v2
	v_mov_b32_e32 v48, v2
	v_mov_b32_e32 v49, v2
	v_mov_b32_e32 v18, v2
	v_mov_b32_e32 v19, v2
	v_mov_b32_e32 v20, v2
	v_mov_b32_e32 v21, v2
	v_mov_b32_e32 v22, v2
	v_mov_b32_e32 v23, v2
	v_mov_b32_e32 v24, v2
	v_mov_b32_e32 v25, v2
	v_mov_b32_e32 v34, v2
	v_mov_b32_e32 v35, v2
	v_mov_b32_e32 v36, v2
	v_mov_b32_e32 v37, v2
	v_mov_b32_e32 v38, v2
	v_mov_b32_e32 v39, v2
	v_mov_b32_e32 v40, v2
	v_mov_b32_e32 v41, v2
	v_mov_b32_e32 v50, v2
	v_mov_b32_e32 v51, v2
	v_mov_b32_e32 v52, v2
	v_mov_b32_e32 v53, v2
	v_mov_b32_e32 v54, v2
	v_mov_b32_e32 v55, v2
	v_mov_b32_e32 v56, v2
	v_mov_b32_e32 v57, v2
	v_mov_b32_e32 v58, v2
	v_mov_b32_e32 v59, v2
	v_mov_b32_e32 v60, v2
	v_mov_b32_e32 v61, v2
	v_mov_b32_e32 v62, v2
	v_mov_b32_e32 v63, v2
	v_mov_b32_e32 v64, v2
	v_mov_b32_e32 v65, v2
	v_mov_b32_e32 v66, v2
	v_mov_b32_e32 v67, v2
	v_mov_b32_e32 v68, v2
	v_mov_b32_e32 v69, v2
	v_mov_b32_e32 v70, v2
	v_mov_b32_e32 v71, v2
	v_mov_b32_e32 v72, v2
	v_mov_b32_e32 v73, v2
	v_mov_b32_e32 v74, v2
	v_mov_b32_e32 v75, v2
	v_mov_b32_e32 v76, v2
	v_mov_b32_e32 v77, v2
	v_mov_b32_e32 v78, v2
	v_mov_b32_e32 v79, v2
	v_mov_b32_e32 v80, v2
	v_mov_b32_e32 v81, v2
	v_mov_b32_e32 v90, v2
	v_mov_b32_e32 v91, v2
	v_mov_b32_e32 v92, v2
	v_mov_b32_e32 v93, v2
	v_mov_b32_e32 v94, v2
	v_mov_b32_e32 v95, v2
	v_mov_b32_e32 v96, v2
	v_mov_b32_e32 v97, v2
	v_mov_b32_e32 v106, v2
	v_mov_b32_e32 v107, v2
	v_mov_b32_e32 v108, v2
	v_mov_b32_e32 v109, v2
	v_mov_b32_e32 v110, v2
	v_mov_b32_e32 v111, v2
	v_mov_b32_e32 v112, v2
	v_mov_b32_e32 v113, v2
	v_mov_b32_e32 v82, v2
	v_mov_b32_e32 v83, v2
	v_mov_b32_e32 v84, v2
	v_mov_b32_e32 v85, v2
	v_mov_b32_e32 v86, v2
	v_mov_b32_e32 v87, v2
	v_mov_b32_e32 v88, v2
	v_mov_b32_e32 v89, v2
	v_mov_b32_e32 v98, v2
	v_mov_b32_e32 v99, v2
	v_mov_b32_e32 v100, v2
	v_mov_b32_e32 v101, v2
	v_mov_b32_e32 v102, v2
	v_mov_b32_e32 v103, v2
	v_mov_b32_e32 v104, v2
	v_mov_b32_e32 v105, v2
	v_mov_b32_e32 v114, v2
	v_mov_b32_e32 v115, v2
	v_mov_b32_e32 v116, v2
	v_mov_b32_e32 v117, v2
	v_mov_b32_e32 v118, v2
	v_mov_b32_e32 v119, v2
	v_mov_b32_e32 v120, v2
	v_mov_b32_e32 v121, v2
	v_mov_b32_e32 v122, v2
	v_mov_b32_e32 v123, v2
	v_mov_b32_e32 v124, v2
	v_mov_b32_e32 v125, v2
	v_mov_b32_e32 v126, v2
	v_mov_b32_e32 v127, v2
	v_mov_b32_e32 v128, v2
	v_mov_b32_e32 v129, v2
	s_setprio 1
.Lprio_skip_3:
.LBB0_1021:
	s_add_i32 s56, s27, 2
	s_add_u32 s34, s30, 0xfff80080
	s_addc_u32 s35, s31, -1
	s_add_i32 s40, 0, 0x10000
	s_cmp_eq_u32 s17, s27
	s_cselect_b32 s37, s23, s35
	s_cselect_b32 s36, s22, s34
	s_cselect_b32 s35, s25, s21
	s_cselect_b32 s34, s24, s19
	s_add_i32 s27, 0, 0x14000
	v_add_u32_e32 v142, s40, v176
	v_add_u32_e32 v168, s27, v176
	ds_read_b128 v[130:133], v142
	ds_read_b128 v[134:137], v142 offset:1024
	ds_read_b128 v[138:141], v142 offset:2048
	ds_read_b128 v[142:145], v142 offset:3072
	ds_read_b128 v[146:149], v168
	ds_read_b128 v[160:163], v168 offset:1024
	ds_read_b128 v[164:167], v168 offset:2048
	ds_read_b128 v[168:171], v168 offset:3072
	v_lshl_add_u64 v[220:221], s[30:31], 0, v[158:159]
	s_add_i32 m0, s29, 0xc000
	ds_read_b128 v[172:175], v177
	ds_read_b128 v[178:181], v177 offset:1024
	ds_read_b128 v[182:185], v177 offset:2048
	ds_read_b128 v[186:189], v177 offset:3072
	ds_read_b128 v[190:193], v177 offset:4096
	ds_read_b128 v[208:211], v177 offset:5120
	ds_read_b128 v[212:215], v177 offset:6144
	ds_read_b128 v[216:219], v177 offset:7168
	global_load_lds_dwordx4 v[220:221], off
	v_lshl_add_u64 v[220:221], s[30:31], 0, v[156:157]
	s_add_i32 m0, s29, 0xe000
	s_nop 0
	global_load_lds_dwordx4 v[220:221], off
	s_waitcnt vmcnt(8)
	s_waitcnt lgkmcnt(0)
	s_barrier
	s_setprio 0
	s_waitcnt lgkmcnt(0)
	v_mfma_f32_16x16x32_bf16 v[126:129], v[130:133], v[172:175], v[126:129]
	v_mfma_f32_16x16x32_bf16 v[122:125], v[138:141], v[172:175], v[122:125]
	v_mfma_f32_16x16x32_bf16 v[118:121], v[130:133], v[182:185], v[118:121]
	v_mfma_f32_16x16x32_bf16 v[114:117], v[138:141], v[182:185], v[114:117]
	v_mfma_f32_16x16x32_bf16 v[102:105], v[130:133], v[190:193], v[102:105]
	v_mfma_f32_16x16x32_bf16 v[98:101], v[138:141], v[190:193], v[98:101]
	v_mfma_f32_16x16x32_bf16 v[86:89], v[130:133], v[212:215], v[86:89]
	v_mfma_f32_16x16x32_bf16 v[82:85], v[138:141], v[212:215], v[82:85]
	v_mfma_f32_16x16x32_bf16 v[126:129], v[134:137], v[178:181], v[126:129]
	v_mfma_f32_16x16x32_bf16 v[122:125], v[142:145], v[178:181], v[122:125]
	v_mfma_f32_16x16x32_bf16 v[118:121], v[134:137], v[186:189], v[118:121]
	v_mfma_f32_16x16x32_bf16 v[114:117], v[142:145], v[186:189], v[114:117]
	v_mfma_f32_16x16x32_bf16 v[102:105], v[134:137], v[208:211], v[102:105]
	v_mfma_f32_16x16x32_bf16 v[98:101], v[142:145], v[208:211], v[98:101]
	v_mfma_f32_16x16x32_bf16 v[86:89], v[134:137], v[216:219], v[86:89]
	v_mfma_f32_16x16x32_bf16 v[82:85], v[142:145], v[216:219], v[82:85]
	v_mfma_f32_16x16x32_bf16 v[110:113], v[146:149], v[172:175], v[110:113]
	v_mfma_f32_16x16x32_bf16 v[106:109], v[164:167], v[172:175], v[106:109]
	v_mfma_f32_16x16x32_bf16 v[94:97], v[146:149], v[182:185], v[94:97]
	v_mfma_f32_16x16x32_bf16 v[90:93], v[164:167], v[182:185], v[90:93]
	v_mfma_f32_16x16x32_bf16 v[78:81], v[146:149], v[190:193], v[78:81]
	v_mfma_f32_16x16x32_bf16 v[74:77], v[164:167], v[190:193], v[74:77]
	v_mfma_f32_16x16x32_bf16 v[70:73], v[146:149], v[212:215], v[70:73]
	v_mfma_f32_16x16x32_bf16 v[66:69], v[164:167], v[212:215], v[66:69]
	v_mfma_f32_16x16x32_bf16 v[110:113], v[160:163], v[178:181], v[110:113]
	v_mfma_f32_16x16x32_bf16 v[106:109], v[168:171], v[178:181], v[106:109]
	v_mfma_f32_16x16x32_bf16 v[94:97], v[160:163], v[186:189], v[94:97]
	v_mfma_f32_16x16x32_bf16 v[90:93], v[168:171], v[186:189], v[90:93]
	v_mfma_f32_16x16x32_bf16 v[78:81], v[160:163], v[208:211], v[78:81]
	v_mfma_f32_16x16x32_bf16 v[74:77], v[168:171], v[208:211], v[74:77]
	v_mfma_f32_16x16x32_bf16 v[70:73], v[160:163], v[216:219], v[70:73]
	v_mfma_f32_16x16x32_bf16 v[66:69], v[168:171], v[216:219], v[66:69]
	s_barrier
; #define PG8_STAGE(bufoff, gbase, voff) do { _Pragma("unroll") for (int _i = 0; _i < 2; ++_i) \
;         __builtin_amdgcn_global_load_lds((const unsigned*)((const char*)(gbase) + (voff)[_i]), (PG8_LAS unsigned*)(lds + (bufoff) + ldsw + _i * 8192), 16, 0, 0); } while (0)
; #define PG8_LDA(dst, b, h) do { _Pragma("unroll") for (int m = 0; m < 4; ++m) _Pragma("unroll") for (int k = 0; k < 2; ++k) dst[m][k] = *(const PG8_LAS bf16x8*)(lds + PG8_SA(b, h) + aoff + m * 2048 + k * 1024); } while (0)
; #define PG8_LDB(dst, b, h) do { _Pragma("unroll") for (int n = 0; n < 2; ++n) _Pragma("unroll") for (int k = 0; k < 2; ++k) dst[n][k] = *(const PG8_LAS bf16x8*)(lds + PG8_SB(b, h) + boff + n * 2048 + k * 1024); } while (0)
; #define PG8_MMA(ai, bj, At, Bt) do { __builtin_amdgcn_s_setprio(1); _Pragma("unroll") for (int m = 0; m < 4; ++m) _Pragma("unroll") for (int n = 0; n < 2; ++n) _Pragma("unroll") for (int k = 0; k < 2; ++k) \
;         acc[ai][bj][m][n] = __builtin_amdgcn_mfma_f32_16x16x32_bf16(Bt[n][k], At[m][k], acc[ai][bj][m][n], 0, 0, 0); __builtin_amdgcn_s_setprio(0); } while (0)
; #define PG8_WAIT_V(n) asm volatile("s_waitcnt vmcnt(" #n ")" ::: "memory")
; #define PG8_WAIT_L(n) asm volatile("s_waitcnt lgkmcnt(" #n ")" ::: "memory")
; #define PG8_BAR __builtin_amdgcn_s_barrier()
; #define PG8_SCHED __builtin_amdgcn_sched_barrier(0)
; template <class Epi, class Sched, bool ALIGN_EPI = false, bool SP2 = false>
; __device__ __forceinline__ void gemm_phase(PG8_LAS unsigned char* lds, const Gemm g, const Sched& S, const Epi& E, int wid_in) {
;     ...
;             PG8_LDA(At, 0, 1); PG8_STAGE(PG8_SB(0, 0), b2, voffB); PG8_STAGE(PG8_SB(0, 1), b2 + hstep, voffB); PG8_STAGE(PG8_SA(0, 0), a2, voffA);
;             PG8_WAIT_V(8); PG8_WAIT_L(0); PG8_BAR; PG8_MMA(1, 0, At, B0); PG8_MMA(1, 1, At, B1); PG8_BAR; PG8_SCHED;
;             PG8_LDB(B0, 1, 0); PG8_LDB(B1, 1, 1); PG8_SCHED; PG8_LDA(At, 1, 0); PG8_STAGE(PG8_SA(0, 1), a2 + hstep, voffA);
	s_setprio 1
	s_add_i32 s40, s40, s59
	v_lshl_add_u64 v[220:221], s[34:35], 0, v[0:1]
	s_mov_b32 m0, s40
	ds_read_b128 v[172:175], v177 offset:16384
	ds_read_b128 v[178:181], v177 offset:17408
	ds_read_b128 v[182:185], v177 offset:18432
	ds_read_b128 v[186:189], v177 offset:19456
	ds_read_b128 v[190:193], v177 offset:20480
	ds_read_b128 v[208:211], v177 offset:21504
	ds_read_b128 v[212:215], v177 offset:22528
	ds_read_b128 v[216:219], v177 offset:23552
	global_load_lds_dwordx4 v[220:221], off
	s_add_i32 m0, s40, 0x2000
	s_add_u32 s40, s34, 0x80000
	v_lshl_add_u64 v[222:223], s[34:35], 0, v[154:155]
	s_addc_u32 s41, s35, 0
	s_add_i32 s27, s27, s59
	global_load_lds_dwordx4 v[222:223], off
	v_lshl_add_u64 v[224:225], s[40:41], 0, v[0:1]
	s_mov_b32 m0, s27
	v_lshl_add_u64 v[226:227], s[36:37], 0, v[152:153]
	global_load_lds_dwordx4 v[224:225], off
	v_lshl_add_u64 v[224:225], s[40:41], 0, v[154:155]
	s_add_i32 m0, s27, 0x2000
	s_nop 0
	global_load_lds_dwordx4 v[224:225], off
	v_lshl_add_u64 v[224:225], s[36:37], 0, v[150:151]
	s_mov_b32 m0, s29
	s_nop 0
	global_load_lds_dwordx4 v[224:225], off
	s_mov_b32 m0, s52
	s_nop 0
	global_load_lds_dwordx4 v[226:227], off
	s_waitcnt vmcnt(8)
	s_waitcnt lgkmcnt(0)
	s_barrier
	s_setprio 0
	s_waitcnt lgkmcnt(0)
	v_mfma_f32_16x16x32_bf16 v[62:65], v[130:133], v[172:175], v[62:65]
	v_mfma_f32_16x16x32_bf16 v[58:61], v[138:141], v[172:175], v[58:61]
	v_mfma_f32_16x16x32_bf16 v[54:57], v[130:133], v[182:185], v[54:57]
	v_mfma_f32_16x16x32_bf16 v[50:53], v[138:141], v[182:185], v[50:53]
	v_mfma_f32_16x16x32_bf16 v[38:41], v[130:133], v[190:193], v[38:41]
	v_mfma_f32_16x16x32_bf16 v[34:37], v[138:141], v[190:193], v[34:37]
	v_mfma_f32_16x16x32_bf16 v[22:25], v[130:133], v[212:215], v[22:25]
	v_mfma_f32_16x16x32_bf16 v[18:21], v[138:141], v[212:215], v[18:21]
	v_mfma_f32_16x16x32_bf16 v[62:65], v[134:137], v[178:181], v[62:65]
	v_mfma_f32_16x16x32_bf16 v[58:61], v[142:145], v[178:181], v[58:61]
	v_mfma_f32_16x16x32_bf16 v[54:57], v[134:137], v[186:189], v[54:57]
	v_mfma_f32_16x16x32_bf16 v[50:53], v[142:145], v[186:189], v[50:53]
	v_mfma_f32_16x16x32_bf16 v[38:41], v[134:137], v[208:211], v[38:41]
	v_mfma_f32_16x16x32_bf16 v[34:37], v[142:145], v[208:211], v[34:37]
	v_mfma_f32_16x16x32_bf16 v[22:25], v[134:137], v[216:219], v[22:25]
	v_mfma_f32_16x16x32_bf16 v[18:21], v[142:145], v[216:219], v[18:21]
	v_mfma_f32_16x16x32_bf16 v[46:49], v[146:149], v[172:175], v[46:49]
	v_mfma_f32_16x16x32_bf16 v[42:45], v[164:167], v[172:175], v[42:45]
	v_mfma_f32_16x16x32_bf16 v[30:33], v[146:149], v[182:185], v[30:33]
	v_mfma_f32_16x16x32_bf16 v[26:29], v[164:167], v[182:185], v[26:29]
	v_mfma_f32_16x16x32_bf16 v[14:17], v[146:149], v[190:193], v[14:17]
	v_mfma_f32_16x16x32_bf16 v[10:13], v[164:167], v[190:193], v[10:13]
	v_mfma_f32_16x16x32_bf16 v[6:9], v[146:149], v[212:215], v[6:9]
	v_mfma_f32_16x16x32_bf16 v[2:5], v[164:167], v[212:215], v[2:5]
	v_mfma_f32_16x16x32_bf16 v[46:49], v[160:163], v[178:181], v[46:49]
	v_mfma_f32_16x16x32_bf16 v[42:45], v[168:171], v[178:181], v[42:45]
	v_mfma_f32_16x16x32_bf16 v[30:33], v[160:163], v[186:189], v[30:33]
	v_mfma_f32_16x16x32_bf16 v[26:29], v[168:171], v[186:189], v[26:29]
	v_mfma_f32_16x16x32_bf16 v[14:17], v[160:163], v[208:211], v[14:17]
	v_mfma_f32_16x16x32_bf16 v[10:13], v[168:171], v[208:211], v[10:13]
	v_mfma_f32_16x16x32_bf16 v[6:9], v[160:163], v[216:219], v[6:9]
	v_mfma_f32_16x16x32_bf16 v[2:5], v[168:171], v[216:219], v[2:5]
	s_barrier
	s_setprio 1
	s_add_i32 s27, 0, 0x18000
	s_add_i32 s40, 0, 0x1c000
	v_add_u32_e32 v142, s27, v176
	v_add_u32_e32 v168, s40, v176
	ds_read_b128 v[130:133], v142
	ds_read_b128 v[134:137], v142 offset:1024
	ds_read_b128 v[138:141], v142 offset:2048
	ds_read_b128 v[142:145], v142 offset:3072
	ds_read_b128 v[146:149], v168
	ds_read_b128 v[160:163], v168 offset:1024
	ds_read_b128 v[164:167], v168 offset:2048
	ds_read_b128 v[168:171], v168 offset:3072
	s_add_u32 s36, s36, 0x80000
	s_addc_u32 s37, s37, 0
	s_mov_b32 m0, s53
	v_lshl_add_u64 v[228:229], s[36:37], 0, v[150:151]
	ds_read_b128 v[172:175], v177 offset:32768
	ds_read_b128 v[178:181], v177 offset:33792
	ds_read_b128 v[182:185], v177 offset:34816
	ds_read_b128 v[186:189], v177 offset:35840
	ds_read_b128 v[190:193], v177 offset:36864
	ds_read_b128 v[208:211], v177 offset:37888
	ds_read_b128 v[212:215], v177 offset:38912
	ds_read_b128 v[216:219], v177 offset:39936
	global_load_lds_dwordx4 v[228:229], off
	v_lshl_add_u64 v[228:229], s[36:37], 0, v[152:153]
	s_mov_b32 m0, s61
	s_nop 0
	global_load_lds_dwordx4 v[228:229], off
	s_waitcnt vmcnt(8)
	s_waitcnt lgkmcnt(0)
	s_barrier
; #define PG8_STAGE(bufoff, gbase, voff) do { _Pragma("unroll") for (int _i = 0; _i < 2; ++_i) \
;         __builtin_amdgcn_global_load_lds((const unsigned*)((const char*)(gbase) + (voff)[_i]), (PG8_LAS unsigned*)(lds + (bufoff) + ldsw + _i * 8192), 16, 0, 0); } while (0)
; #define PG8_LDA(dst, b, h) do { _Pragma("unroll") for (int m = 0; m < 4; ++m) _Pragma("unroll") for (int k = 0; k < 2; ++k) dst[m][k] = *(const PG8_LAS bf16x8*)(lds + PG8_SA(b, h) + aoff + m * 2048 + k * 1024); } while (0)
; #define PG8_MMA(ai, bj, At, Bt) do { __builtin_amdgcn_s_setprio(1); _Pragma("unroll") for (int m = 0; m < 4; ++m) _Pragma("unroll") for (int n = 0; n < 2; ++n) _Pragma("unroll") for (int k = 0; k < 2; ++k) \
;         acc[ai][bj][m][n] = __builtin_amdgcn_mfma_f32_16x16x32_bf16(Bt[n][k], At[m][k], acc[ai][bj][m][n], 0, 0, 0); __builtin_amdgcn_s_setprio(0); } while (0)
; #define PG8_WAIT_V(n) asm volatile("s_waitcnt vmcnt(" #n ")" ::: "memory")
; #define PG8_WAIT_L(n) asm volatile("s_waitcnt lgkmcnt(" #n ")" ::: "memory")
; #define PG8_BAR __builtin_amdgcn_s_barrier()
; #define PG8_SCHED __builtin_amdgcn_sched_barrier(0)
; template <class Epi, class Sched, bool ALIGN_EPI = false, bool SP2 = false>
; __device__ __forceinline__ void gemm_phase(PG8_LAS unsigned char* lds, const Gemm g, const Sched& S, const Epi& E, int wid_in) {
;     ...
;             PG8_WAIT_V(8); PG8_WAIT_L(0); PG8_BAR; PG8_MMA(0, 0, At, B0); PG8_MMA(0, 1, At, B1); PG8_BAR; PG8_SCHED;
;             PG8_LDA(At, 1, 1); PG8_STAGE(PG8_SB(1, 0), b3, voffB); PG8_STAGE(PG8_SB(1, 1), b3 + hstep, voffB); PG8_STAGE(PG8_SA(1, 0), a3, voffA);
;             PG8_WAIT_V(8); PG8_WAIT_L(0); PG8_BAR; PG8_MMA(1, 0, At, B0); PG8_MMA(1, 1, At, B1); PG8_BAR; PG8_SCHED;
;     ...
;         if constexpr (ALIGN_EPI) { if (wr == 0) PG8_BAR; }
	s_setprio 0
	s_waitcnt lgkmcnt(0)
	v_mfma_f32_16x16x32_bf16 v[126:129], v[130:133], v[172:175], v[126:129]
	v_mfma_f32_16x16x32_bf16 v[122:125], v[138:141], v[172:175], v[122:125]
	v_mfma_f32_16x16x32_bf16 v[118:121], v[130:133], v[182:185], v[118:121]
	v_mfma_f32_16x16x32_bf16 v[114:117], v[138:141], v[182:185], v[114:117]
	v_mfma_f32_16x16x32_bf16 v[102:105], v[130:133], v[190:193], v[102:105]
	v_mfma_f32_16x16x32_bf16 v[98:101], v[138:141], v[190:193], v[98:101]
	v_mfma_f32_16x16x32_bf16 v[86:89], v[130:133], v[212:215], v[86:89]
	v_mfma_f32_16x16x32_bf16 v[82:85], v[138:141], v[212:215], v[82:85]
	v_mfma_f32_16x16x32_bf16 v[126:129], v[134:137], v[178:181], v[126:129]
	v_mfma_f32_16x16x32_bf16 v[122:125], v[142:145], v[178:181], v[122:125]
	v_mfma_f32_16x16x32_bf16 v[118:121], v[134:137], v[186:189], v[118:121]
	v_mfma_f32_16x16x32_bf16 v[114:117], v[142:145], v[186:189], v[114:117]
	v_mfma_f32_16x16x32_bf16 v[102:105], v[134:137], v[208:211], v[102:105]
	v_mfma_f32_16x16x32_bf16 v[98:101], v[142:145], v[208:211], v[98:101]
	v_mfma_f32_16x16x32_bf16 v[86:89], v[134:137], v[216:219], v[86:89]
	v_mfma_f32_16x16x32_bf16 v[82:85], v[142:145], v[216:219], v[82:85]
	v_mfma_f32_16x16x32_bf16 v[110:113], v[146:149], v[172:175], v[110:113]
	v_mfma_f32_16x16x32_bf16 v[106:109], v[164:167], v[172:175], v[106:109]
	v_mfma_f32_16x16x32_bf16 v[94:97], v[146:149], v[182:185], v[94:97]
	v_mfma_f32_16x16x32_bf16 v[90:93], v[164:167], v[182:185], v[90:93]
	v_mfma_f32_16x16x32_bf16 v[78:81], v[146:149], v[190:193], v[78:81]
	v_mfma_f32_16x16x32_bf16 v[74:77], v[164:167], v[190:193], v[74:77]
	v_mfma_f32_16x16x32_bf16 v[70:73], v[146:149], v[212:215], v[70:73]
	v_mfma_f32_16x16x32_bf16 v[66:69], v[164:167], v[212:215], v[66:69]
	v_mfma_f32_16x16x32_bf16 v[110:113], v[160:163], v[178:181], v[110:113]
	v_mfma_f32_16x16x32_bf16 v[106:109], v[168:171], v[178:181], v[106:109]
	v_mfma_f32_16x16x32_bf16 v[94:97], v[160:163], v[186:189], v[94:97]
	v_mfma_f32_16x16x32_bf16 v[90:93], v[168:171], v[186:189], v[90:93]
	v_mfma_f32_16x16x32_bf16 v[78:81], v[160:163], v[208:211], v[78:81]
	v_mfma_f32_16x16x32_bf16 v[74:77], v[168:171], v[208:211], v[74:77]
	v_mfma_f32_16x16x32_bf16 v[70:73], v[160:163], v[216:219], v[70:73]
	v_mfma_f32_16x16x32_bf16 v[66:69], v[168:171], v[216:219], v[66:69]
	s_barrier
	s_setprio 1
	s_add_i32 s27, s27, s59
	v_lshl_add_u64 v[220:221], v[220:221], 0, s[94:95]
	s_mov_b32 m0, s27
	ds_read_b128 v[172:175], v177 offset:49152
	ds_read_b128 v[178:181], v177 offset:50176
	ds_read_b128 v[182:185], v177 offset:51200
	ds_read_b128 v[186:189], v177 offset:52224
	ds_read_b128 v[190:193], v177 offset:53248
	ds_read_b128 v[208:211], v177 offset:54272
	ds_read_b128 v[212:215], v177 offset:55296
	ds_read_b128 v[216:219], v177 offset:56320
	global_load_lds_dwordx4 v[220:221], off
	s_add_i32 m0, s27, 0x2000
	s_add_u32 s34, s34, 0x80080
	v_lshl_add_u64 v[220:221], v[222:223], 0, s[94:95]
	s_addc_u32 s35, s35, 0
	s_add_i32 s27, s40, s59
	global_load_lds_dwordx4 v[220:221], off
	v_lshl_add_u64 v[220:221], s[34:35], 0, v[0:1]
	s_mov_b32 m0, s27
	s_nop 0
	global_load_lds_dwordx4 v[220:221], off
	v_lshl_add_u64 v[220:221], s[34:35], 0, v[154:155]
	s_add_i32 m0, s27, 0x2000
	s_nop 0
	global_load_lds_dwordx4 v[220:221], off
	v_lshl_add_u64 v[220:221], v[224:225], 0, s[94:95]
	s_mov_b32 m0, s73
	s_nop 0
	global_load_lds_dwordx4 v[220:221], off
	v_lshl_add_u64 v[220:221], v[226:227], 0, s[94:95]
	s_mov_b32 m0, s80
	s_nop 0
	global_load_lds_dwordx4 v[220:221], off
	s_waitcnt vmcnt(8)
	s_waitcnt lgkmcnt(0)
	s_barrier
	s_setprio 0
	s_waitcnt lgkmcnt(0)
	v_mfma_f32_16x16x32_bf16 v[62:65], v[130:133], v[172:175], v[62:65]
	v_mfma_f32_16x16x32_bf16 v[58:61], v[138:141], v[172:175], v[58:61]
	v_mfma_f32_16x16x32_bf16 v[54:57], v[130:133], v[182:185], v[54:57]
	v_mfma_f32_16x16x32_bf16 v[50:53], v[138:141], v[182:185], v[50:53]
	v_mfma_f32_16x16x32_bf16 v[38:41], v[130:133], v[190:193], v[38:41]
	v_mfma_f32_16x16x32_bf16 v[34:37], v[138:141], v[190:193], v[34:37]
	v_mfma_f32_16x16x32_bf16 v[22:25], v[130:133], v[212:215], v[22:25]
	v_mfma_f32_16x16x32_bf16 v[18:21], v[138:141], v[212:215], v[18:21]
	v_mfma_f32_16x16x32_bf16 v[62:65], v[134:137], v[178:181], v[62:65]
	v_mfma_f32_16x16x32_bf16 v[58:61], v[142:145], v[178:181], v[58:61]
	v_mfma_f32_16x16x32_bf16 v[54:57], v[134:137], v[186:189], v[54:57]
	v_mfma_f32_16x16x32_bf16 v[50:53], v[142:145], v[186:189], v[50:53]
	v_mfma_f32_16x16x32_bf16 v[38:41], v[134:137], v[208:211], v[38:41]
	v_mfma_f32_16x16x32_bf16 v[34:37], v[142:145], v[208:211], v[34:37]
	v_mfma_f32_16x16x32_bf16 v[22:25], v[134:137], v[216:219], v[22:25]
	v_mfma_f32_16x16x32_bf16 v[18:21], v[142:145], v[216:219], v[18:21]
	v_mfma_f32_16x16x32_bf16 v[46:49], v[146:149], v[172:175], v[46:49]
	v_mfma_f32_16x16x32_bf16 v[42:45], v[164:167], v[172:175], v[42:45]
	v_mfma_f32_16x16x32_bf16 v[30:33], v[146:149], v[182:185], v[30:33]
	v_mfma_f32_16x16x32_bf16 v[26:29], v[164:167], v[182:185], v[26:29]
	v_mfma_f32_16x16x32_bf16 v[14:17], v[146:149], v[190:193], v[14:17]
	v_mfma_f32_16x16x32_bf16 v[10:13], v[164:167], v[190:193], v[10:13]
	v_mfma_f32_16x16x32_bf16 v[6:9], v[146:149], v[212:215], v[6:9]
	v_mfma_f32_16x16x32_bf16 v[2:5], v[164:167], v[212:215], v[2:5]
	v_mfma_f32_16x16x32_bf16 v[46:49], v[160:163], v[178:181], v[46:49]
	v_mfma_f32_16x16x32_bf16 v[42:45], v[168:171], v[178:181], v[42:45]
	v_mfma_f32_16x16x32_bf16 v[30:33], v[160:163], v[186:189], v[30:33]
	v_mfma_f32_16x16x32_bf16 v[26:29], v[168:171], v[186:189], v[26:29]
	v_mfma_f32_16x16x32_bf16 v[14:17], v[160:163], v[208:211], v[14:17]
	v_mfma_f32_16x16x32_bf16 v[10:13], v[168:171], v[208:211], v[10:13]
	v_mfma_f32_16x16x32_bf16 v[6:9], v[160:163], v[216:219], v[6:9]
	v_mfma_f32_16x16x32_bf16 v[2:5], v[168:171], v[216:219], v[2:5]
	s_barrier
	s_setprio 1
	s_add_u32 s19, s19, 0x100
	s_addc_u32 s21, s21, 0
	s_add_u32 s30, s30, 0x100
	s_addc_u32 s31, s31, 0
	s_cmp_ge_i32 s56, s90
	s_mov_b32 s27, s56
	s_cbranch_scc0 .LBB0_1021
	s_setprio 0
	s_and_b64 vcc, exec, s[14:15]
	s_cbranch_vccz .LBB0_1024
	s_barrier

; #define PG8_STAGE(bufoff, gbase, voff) do { _Pragma("unroll") for (int _i = 0; _i < 2; ++_i) \
;         __builtin_amdgcn_global_load_lds((const unsigned*)((const char*)(gbase) + (voff)[_i]), (PG8_LAS unsigned*)(lds + (bufoff) + ldsw + _i * 8192), 16, 0, 0); } while (0)
; #define PG8_LDA(dst, b, h) do { _Pragma("unroll") for (int m = 0; m < 4; ++m) _Pragma("unroll") for (int k = 0; k < 2; ++k) dst[m][k] = *(const PG8_LAS bf16x8*)(lds + PG8_SA(b, h) + aoff + m * 2048 + k * 1024); } while (0)
; #define PG8_LDB(dst, b, h) do { _Pragma("unroll") for (int n = 0; n < 2; ++n) _Pragma("unroll") for (int k = 0; k < 2; ++k) dst[n][k] = *(const PG8_LAS bf16x8*)(lds + PG8_SB(b, h) + boff + n * 2048 + k * 1024); } while (0)
; #define PG8_WAIT_V(n) asm volatile("s_waitcnt vmcnt(" #n ")" ::: "memory")
; #define PG8_WAIT_L(n) asm volatile("s_waitcnt lgkmcnt(" #n ")" ::: "memory")
; template <class Epi, class Sched, bool ALIGN_EPI = false, bool SP2 = false>
; __device__ __forceinline__ void gemm_phase(PG8_LAS unsigned char* lds, const Gemm g, const Sched& S, const Epi& E, int wid_in) {
;     ...
;     for (;;) {
;         const bool has_next = S.next(ui + 1, nxt);
;         const char* nA = has_next ? (const char*)g.A + (size_t)nxt.pm * tstep + (size_t)nxt.kt0 * kstep : cA; const char* nB = has_next ? (const char*)g.Bt + (size_t)nxt.pn * tstep + (size_t)nxt.kt0 * kstep : cB;
;         const int nt = cur.nkt;
;         for (int t = 0; t < nt; t += 2) {
;             const bool last = (t == nt - 2);
;             const char* a1 = cA + (size_t)(t + 1) * kstep;
;             const char* a2 = last ? nA : cA + (size_t)(t + 2) * kstep; const char* b2 = last ? nB : cB + (size_t)(t + 2) * kstep;
;             const char* a3 = a2 + kstep; const char* b3 = b2 + kstep;
;             if (last && has_next) S.a_ready(nxt);
;             if constexpr (SP2) {
;             PG8_LDB(B0, 0, 0); PG8_LDB(B1, 0, 1); PG8_SCHED; PG8_LDA(At, 0, 0); PG8_STAGE(PG8_SA(1, 1), a1 + hstep, voffA);
;             PG8_WAIT_V(8); PG8_WAIT_L(0); PG8_BAR; PG8_MMA(0, 0, At, B0); PG8_MMA(0, 1, At, B1); PG8_BAR; PG8_SCHED;
;     ...
; #pragma unroll
;         for (int a = 0; a < 2; ++a)
; #pragma unroll
;             for (int b = 0; b < 2; ++b)
; #pragma unroll
;                 for (int m = 0; m < 4; ++m)
; #pragma unroll
;                     for (int n = 0; n < 2; ++n) acc[a][b][m][n] = (f32x4){0.f, 0.f, 0.f, 0.f};
.LBB0_1152:
	s_ashr_i32 s19, s18, 31
	s_lshl_b64 s[20:21], s[18:19], 20
	s_add_u32 s20, s0, s20
	s_addc_u32 s21, s1, s21
	s_and_b64 s[22:23], s[8:9], exec
	s_cselect_b32 s19, s21, s25
	s_cselect_b32 s64, s20, s24
	s_ashr_i32 s17, s16, 31
	s_lshl_b64 s[22:23], s[16:17], 20
	s_add_u32 s22, s30, s22
	s_addc_u32 s23, s31, s23
	s_and_b64 s[28:29], s[8:9], exec
	s_cselect_b32 s17, s23, s27
	s_cselect_b32 s65, s22, s26
	s_add_u32 s72, s26, 0x100
	s_addc_u32 s63, s27, 0
	s_add_u32 s24, s24, 0x80080
	v_mov_b32_e32 v2, 0
	s_addc_u32 s25, s25, 0
	s_mov_b32 s73, -2
	v_mov_b32_e32 v3, v2
	v_mov_b32_e32 v4, v2
	v_mov_b32_e32 v5, v2
	v_mov_b32_e32 v6, v2
	v_mov_b32_e32 v7, v2
	v_mov_b32_e32 v8, v2
	v_mov_b32_e32 v9, v2
	v_mov_b32_e32 v18, v2
	v_mov_b32_e32 v19, v2
	v_mov_b32_e32 v20, v2
	v_mov_b32_e32 v21, v2
	v_mov_b32_e32 v22, v2
	v_mov_b32_e32 v23, v2
	v_mov_b32_e32 v24, v2
	v_mov_b32_e32 v25, v2
	v_mov_b32_e32 v34, v2
	v_mov_b32_e32 v35, v2
	v_mov_b32_e32 v36, v2
	v_mov_b32_e32 v37, v2
	v_mov_b32_e32 v38, v2
	v_mov_b32_e32 v39, v2
	v_mov_b32_e32 v40, v2
	v_mov_b32_e32 v41, v2
	v_mov_b32_e32 v50, v2
	v_mov_b32_e32 v51, v2
	v_mov_b32_e32 v52, v2
	v_mov_b32_e32 v53, v2
	v_mov_b32_e32 v54, v2
	v_mov_b32_e32 v55, v2
	v_mov_b32_e32 v56, v2
	v_mov_b32_e32 v57, v2
	v_mov_b32_e32 v10, v2
	v_mov_b32_e32 v11, v2
	v_mov_b32_e32 v12, v2
	v_mov_b32_e32 v13, v2
	v_mov_b32_e32 v14, v2
	v_mov_b32_e32 v15, v2
	v_mov_b32_e32 v16, v2
	v_mov_b32_e32 v17, v2
	v_mov_b32_e32 v26, v2
	v_mov_b32_e32 v27, v2
	v_mov_b32_e32 v28, v2
	v_mov_b32_e32 v29, v2
	v_mov_b32_e32 v30, v2
	v_mov_b32_e32 v31, v2
	v_mov_b32_e32 v32, v2
	v_mov_b32_e32 v33, v2
	v_mov_b32_e32 v42, v2
	v_mov_b32_e32 v43, v2
	v_mov_b32_e32 v44, v2
	v_mov_b32_e32 v45, v2
	v_mov_b32_e32 v46, v2
	v_mov_b32_e32 v47, v2
	v_mov_b32_e32 v48, v2
	v_mov_b32_e32 v49, v2
	v_mov_b32_e32 v58, v2
	v_mov_b32_e32 v59, v2
	v_mov_b32_e32 v60, v2
	v_mov_b32_e32 v61, v2
	v_mov_b32_e32 v62, v2
	v_mov_b32_e32 v63, v2
	v_mov_b32_e32 v64, v2
	v_mov_b32_e32 v65, v2
	v_mov_b32_e32 v66, v2
	v_mov_b32_e32 v67, v2
	v_mov_b32_e32 v68, v2
	v_mov_b32_e32 v69, v2
	v_mov_b32_e32 v70, v2
	v_mov_b32_e32 v71, v2
	v_mov_b32_e32 v72, v2
	v_mov_b32_e32 v73, v2
	v_mov_b32_e32 v82, v2
	v_mov_b32_e32 v83, v2
	v_mov_b32_e32 v84, v2
	v_mov_b32_e32 v85, v2
	v_mov_b32_e32 v86, v2
	v_mov_b32_e32 v87, v2
	v_mov_b32_e32 v88, v2
	v_mov_b32_e32 v89, v2
	v_mov_b32_e32 v98, v2
	v_mov_b32_e32 v99, v2
	v_mov_b32_e32 v100, v2
	v_mov_b32_e32 v101, v2
	v_mov_b32_e32 v102, v2
	v_mov_b32_e32 v103, v2
	v_mov_b32_e32 v104, v2
	v_mov_b32_e32 v105, v2
	v_mov_b32_e32 v114, v2
	v_mov_b32_e32 v115, v2
	v_mov_b32_e32 v116, v2
	v_mov_b32_e32 v117, v2
	v_mov_b32_e32 v118, v2
	v_mov_b32_e32 v119, v2
	v_mov_b32_e32 v120, v2
	v_mov_b32_e32 v121, v2
	v_mov_b32_e32 v74, v2
	v_mov_b32_e32 v75, v2
	v_mov_b32_e32 v76, v2
	v_mov_b32_e32 v77, v2
	v_mov_b32_e32 v78, v2
	v_mov_b32_e32 v79, v2
	v_mov_b32_e32 v80, v2
	v_mov_b32_e32 v81, v2
	v_mov_b32_e32 v90, v2
	v_mov_b32_e32 v91, v2
	v_mov_b32_e32 v92, v2
	v_mov_b32_e32 v93, v2
	v_mov_b32_e32 v94, v2
	v_mov_b32_e32 v95, v2
	v_mov_b32_e32 v96, v2
	v_mov_b32_e32 v97, v2
	v_mov_b32_e32 v106, v2
	v_mov_b32_e32 v107, v2
	v_mov_b32_e32 v108, v2
	v_mov_b32_e32 v109, v2
	v_mov_b32_e32 v110, v2
	v_mov_b32_e32 v111, v2
	v_mov_b32_e32 v112, v2
	v_mov_b32_e32 v113, v2
	v_mov_b32_e32 v122, v2
	v_mov_b32_e32 v123, v2
	v_mov_b32_e32 v124, v2
	v_mov_b32_e32 v125, v2
	v_mov_b32_e32 v126, v2
	v_mov_b32_e32 v127, v2
	v_mov_b32_e32 v128, v2
	v_mov_b32_e32 v129, v2
	s_setprio 1
.Lprio_skip_4:
.LBB0_1153:
	s_add_u32 s26, s24, 0xfff80080
	s_addc_u32 s27, s25, -1
	s_add_i32 s40, 0, 0x10000
	s_cmp_eq_u32 s73, 28
	s_cselect_b32 s29, s19, s27
	s_cselect_b32 s28, s64, s26
	v_add_u32_e32 v140, s40, v142
	s_cselect_b32 s27, s17, s63
	s_cselect_b32 s26, s65, s72
	s_add_i32 s42, 0, 0x14000
	ds_read_b128 v[144:147], v140
	ds_read_b128 v[148:151], v140 offset:1024
	ds_read_b128 v[152:155], v140 offset:2048
	ds_read_b128 v[156:159], v140 offset:3072
	v_add_u32_e32 v140, s42, v142
	ds_read_b128 v[160:163], v140
	ds_read_b128 v[164:167], v140 offset:1024
	ds_read_b128 v[168:171], v140 offset:2048
	ds_read_b128 v[172:175], v140 offset:3072
	v_lshl_add_u64 v[140:141], s[24:25], 0, v[138:139]
	s_add_i32 m0, s34, 0xc000
	ds_read_b128 v[176:179], v143
	ds_read_b128 v[180:183], v143 offset:1024
	ds_read_b128 v[184:187], v143 offset:2048
	ds_read_b128 v[188:191], v143 offset:3072
	ds_read_b128 v[208:211], v143 offset:4096
	ds_read_b128 v[212:215], v143 offset:5120
	ds_read_b128 v[216:219], v143 offset:6144
	ds_read_b128 v[220:223], v143 offset:7168
	global_load_lds_dwordx4 v[140:141], off
	v_lshl_add_u64 v[140:141], s[24:25], 0, v[136:137]
	s_add_i32 m0, s34, 0xe000
	s_nop 0
	global_load_lds_dwordx4 v[140:141], off
	s_waitcnt vmcnt(8)
	s_waitcnt lgkmcnt(0)
	s_barrier
; #define PG8_STAGE(bufoff, gbase, voff) do { _Pragma("unroll") for (int _i = 0; _i < 2; ++_i) \
;         __builtin_amdgcn_global_load_lds((const unsigned*)((const char*)(gbase) + (voff)[_i]), (PG8_LAS unsigned*)(lds + (bufoff) + ldsw + _i * 8192), 16, 0, 0); } while (0)
; #define PG8_LDA(dst, b, h) do { _Pragma("unroll") for (int m = 0; m < 4; ++m) _Pragma("unroll") for (int k = 0; k < 2; ++k) dst[m][k] = *(const PG8_LAS bf16x8*)(lds + PG8_SA(b, h) + aoff + m * 2048 + k * 1024); } while (0)
; #define PG8_MMA(ai, bj, At, Bt) do { __builtin_amdgcn_s_setprio(1); _Pragma("unroll") for (int m = 0; m < 4; ++m) _Pragma("unroll") for (int n = 0; n < 2; ++n) _Pragma("unroll") for (int k = 0; k < 2; ++k) \
;         acc[ai][bj][m][n] = __builtin_amdgcn_mfma_f32_16x16x32_bf16(Bt[n][k], At[m][k], acc[ai][bj][m][n], 0, 0, 0); __builtin_amdgcn_s_setprio(0); } while (0)
; #define PG8_WAIT_V(n) asm volatile("s_waitcnt vmcnt(" #n ")" ::: "memory")
; #define PG8_WAIT_L(n) asm volatile("s_waitcnt lgkmcnt(" #n ")" ::: "memory")
; #define PG8_BAR __builtin_amdgcn_s_barrier()
; #define PG8_SCHED __builtin_amdgcn_sched_barrier(0)
; template <class Epi, class Sched, bool ALIGN_EPI = false, bool SP2 = false>
; __device__ __forceinline__ void gemm_phase(PG8_LAS unsigned char* lds, const Gemm g, const Sched& S, const Epi& E, int wid_in) {
;     ...
;             PG8_WAIT_V(8); PG8_WAIT_L(0); PG8_BAR; PG8_MMA(0, 0, At, B0); PG8_MMA(0, 1, At, B1); PG8_BAR; PG8_SCHED;
;             PG8_LDA(At, 0, 1); PG8_STAGE(PG8_SB(0, 0), b2, voffB); PG8_STAGE(PG8_SB(0, 1), b2 + hstep, voffB); PG8_STAGE(PG8_SA(0, 0), a2, voffA);
;             PG8_WAIT_V(8); PG8_WAIT_L(0); PG8_BAR; PG8_MMA(1, 0, At, B0); PG8_MMA(1, 1, At, B1); PG8_BAR; PG8_SCHED;
	s_setprio 0
	s_waitcnt lgkmcnt(0)
	v_mfma_f32_16x16x32_bf16 v[126:129], v[144:147], v[176:179], v[126:129]
	v_mfma_f32_16x16x32_bf16 v[122:125], v[152:155], v[176:179], v[122:125]
	v_mfma_f32_16x16x32_bf16 v[110:113], v[144:147], v[184:187], v[110:113]
	v_mfma_f32_16x16x32_bf16 v[106:109], v[152:155], v[184:187], v[106:109]
	v_mfma_f32_16x16x32_bf16 v[94:97], v[144:147], v[208:211], v[94:97]
	v_mfma_f32_16x16x32_bf16 v[90:93], v[152:155], v[208:211], v[90:93]
	v_mfma_f32_16x16x32_bf16 v[78:81], v[144:147], v[216:219], v[78:81]
	v_mfma_f32_16x16x32_bf16 v[74:77], v[152:155], v[216:219], v[74:77]
	v_mfma_f32_16x16x32_bf16 v[126:129], v[148:151], v[180:183], v[126:129]
	v_mfma_f32_16x16x32_bf16 v[122:125], v[156:159], v[180:183], v[122:125]
	v_mfma_f32_16x16x32_bf16 v[110:113], v[148:151], v[188:191], v[110:113]
	v_mfma_f32_16x16x32_bf16 v[106:109], v[156:159], v[188:191], v[106:109]
	v_mfma_f32_16x16x32_bf16 v[94:97], v[148:151], v[212:215], v[94:97]
	v_mfma_f32_16x16x32_bf16 v[90:93], v[156:159], v[212:215], v[90:93]
	v_mfma_f32_16x16x32_bf16 v[78:81], v[148:151], v[220:223], v[78:81]
	v_mfma_f32_16x16x32_bf16 v[74:77], v[156:159], v[220:223], v[74:77]
	v_mfma_f32_16x16x32_bf16 v[118:121], v[160:163], v[176:179], v[118:121]
	v_mfma_f32_16x16x32_bf16 v[114:117], v[168:171], v[176:179], v[114:117]
	v_mfma_f32_16x16x32_bf16 v[102:105], v[160:163], v[184:187], v[102:105]
	v_mfma_f32_16x16x32_bf16 v[98:101], v[168:171], v[184:187], v[98:101]
	v_mfma_f32_16x16x32_bf16 v[86:89], v[160:163], v[208:211], v[86:89]
	v_mfma_f32_16x16x32_bf16 v[82:85], v[168:171], v[208:211], v[82:85]
	v_mfma_f32_16x16x32_bf16 v[70:73], v[160:163], v[216:219], v[70:73]
	v_mfma_f32_16x16x32_bf16 v[66:69], v[168:171], v[216:219], v[66:69]
	v_mfma_f32_16x16x32_bf16 v[118:121], v[164:167], v[180:183], v[118:121]
	v_mfma_f32_16x16x32_bf16 v[114:117], v[172:175], v[180:183], v[114:117]
	v_mfma_f32_16x16x32_bf16 v[102:105], v[164:167], v[188:191], v[102:105]
	v_mfma_f32_16x16x32_bf16 v[98:101], v[172:175], v[188:191], v[98:101]
	v_mfma_f32_16x16x32_bf16 v[86:89], v[164:167], v[212:215], v[86:89]
	v_mfma_f32_16x16x32_bf16 v[82:85], v[172:175], v[212:215], v[82:85]
	v_mfma_f32_16x16x32_bf16 v[70:73], v[164:167], v[220:223], v[70:73]
	v_mfma_f32_16x16x32_bf16 v[66:69], v[172:175], v[220:223], v[66:69]
	s_barrier
	s_setprio 1
	s_add_i32 s40, s40, s59
	v_lshl_add_u64 v[140:141], s[26:27], 0, v[0:1]
	s_mov_b32 m0, s40
	ds_read_b128 v[176:179], v143 offset:16384
	ds_read_b128 v[180:183], v143 offset:17408
	ds_read_b128 v[184:187], v143 offset:18432
	ds_read_b128 v[188:191], v143 offset:19456
	ds_read_b128 v[208:211], v143 offset:20480
	ds_read_b128 v[212:215], v143 offset:21504
	ds_read_b128 v[216:219], v143 offset:22528
	ds_read_b128 v[220:223], v143 offset:23552
	global_load_lds_dwordx4 v[140:141], off
	s_add_i32 m0, s40, 0x2000
	s_add_u32 s40, s26, 0x80000
	v_lshl_add_u64 v[192:193], s[26:27], 0, v[130:131]
	s_addc_u32 s41, s27, 0
	s_add_i32 s42, s42, s59
	global_load_lds_dwordx4 v[192:193], off
	v_lshl_add_u64 v[224:225], s[40:41], 0, v[0:1]
	s_mov_b32 m0, s42
	v_lshl_add_u64 v[226:227], s[28:29], 0, v[132:133]
	global_load_lds_dwordx4 v[224:225], off
	v_lshl_add_u64 v[224:225], s[40:41], 0, v[130:131]
	s_add_i32 m0, s42, 0x2000
	s_nop 0
	global_load_lds_dwordx4 v[224:225], off
	v_lshl_add_u64 v[224:225], s[28:29], 0, v[134:135]
	s_mov_b32 m0, s34
	s_nop 0
	global_load_lds_dwordx4 v[224:225], off
	s_mov_b32 m0, s35
	s_nop 0
	global_load_lds_dwordx4 v[226:227], off
	s_waitcnt vmcnt(8)
	s_waitcnt lgkmcnt(0)
	s_barrier
	s_setprio 0
	s_waitcnt lgkmcnt(0)
	v_mfma_f32_16x16x32_bf16 v[62:65], v[144:147], v[176:179], v[62:65]
	v_mfma_f32_16x16x32_bf16 v[58:61], v[152:155], v[176:179], v[58:61]
	v_mfma_f32_16x16x32_bf16 v[46:49], v[144:147], v[184:187], v[46:49]
	v_mfma_f32_16x16x32_bf16 v[42:45], v[152:155], v[184:187], v[42:45]
	v_mfma_f32_16x16x32_bf16 v[30:33], v[144:147], v[208:211], v[30:33]
	v_mfma_f32_16x16x32_bf16 v[26:29], v[152:155], v[208:211], v[26:29]
	v_mfma_f32_16x16x32_bf16 v[14:17], v[144:147], v[216:219], v[14:17]
	v_mfma_f32_16x16x32_bf16 v[10:13], v[152:155], v[216:219], v[10:13]
	v_mfma_f32_16x16x32_bf16 v[62:65], v[148:151], v[180:183], v[62:65]
	v_mfma_f32_16x16x32_bf16 v[58:61], v[156:159], v[180:183], v[58:61]
	v_mfma_f32_16x16x32_bf16 v[46:49], v[148:151], v[188:191], v[46:49]
	v_mfma_f32_16x16x32_bf16 v[42:45], v[156:159], v[188:191], v[42:45]
	v_mfma_f32_16x16x32_bf16 v[30:33], v[148:151], v[212:215], v[30:33]
	v_mfma_f32_16x16x32_bf16 v[26:29], v[156:159], v[212:215], v[26:29]
	v_mfma_f32_16x16x32_bf16 v[14:17], v[148:151], v[220:223], v[14:17]
	v_mfma_f32_16x16x32_bf16 v[10:13], v[156:159], v[220:223], v[10:13]
	v_mfma_f32_16x16x32_bf16 v[54:57], v[160:163], v[176:179], v[54:57]
	v_mfma_f32_16x16x32_bf16 v[50:53], v[168:171], v[176:179], v[50:53]
	v_mfma_f32_16x16x32_bf16 v[38:41], v[160:163], v[184:187], v[38:41]
	v_mfma_f32_16x16x32_bf16 v[34:37], v[168:171], v[184:187], v[34:37]
	v_mfma_f32_16x16x32_bf16 v[22:25], v[160:163], v[208:211], v[22:25]
	v_mfma_f32_16x16x32_bf16 v[18:21], v[168:171], v[208:211], v[18:21]
	v_mfma_f32_16x16x32_bf16 v[6:9], v[160:163], v[216:219], v[6:9]
	v_mfma_f32_16x16x32_bf16 v[2:5], v[168:171], v[216:219], v[2:5]
	v_mfma_f32_16x16x32_bf16 v[54:57], v[164:167], v[180:183], v[54:57]
	v_mfma_f32_16x16x32_bf16 v[50:53], v[172:175], v[180:183], v[50:53]
	v_mfma_f32_16x16x32_bf16 v[38:41], v[164:167], v[188:191], v[38:41]
	v_mfma_f32_16x16x32_bf16 v[34:37], v[172:175], v[188:191], v[34:37]
	v_mfma_f32_16x16x32_bf16 v[22:25], v[164:167], v[212:215], v[22:25]
	v_mfma_f32_16x16x32_bf16 v[18:21], v[172:175], v[212:215], v[18:21]
	v_mfma_f32_16x16x32_bf16 v[6:9], v[164:167], v[220:223], v[6:9]
	v_mfma_f32_16x16x32_bf16 v[2:5], v[172:175], v[220:223], v[2:5]
	s_barrier
; #define PG8_STAGE(bufoff, gbase, voff) do { _Pragma("unroll") for (int _i = 0; _i < 2; ++_i) \
;         __builtin_amdgcn_global_load_lds((const unsigned*)((const char*)(gbase) + (voff)[_i]), (PG8_LAS unsigned*)(lds + (bufoff) + ldsw + _i * 8192), 16, 0, 0); } while (0)
; #define PG8_LDA(dst, b, h) do { _Pragma("unroll") for (int m = 0; m < 4; ++m) _Pragma("unroll") for (int k = 0; k < 2; ++k) dst[m][k] = *(const PG8_LAS bf16x8*)(lds + PG8_SA(b, h) + aoff + m * 2048 + k * 1024); } while (0)
; #define PG8_LDB(dst, b, h) do { _Pragma("unroll") for (int n = 0; n < 2; ++n) _Pragma("unroll") for (int k = 0; k < 2; ++k) dst[n][k] = *(const PG8_LAS bf16x8*)(lds + PG8_SB(b, h) + boff + n * 2048 + k * 1024); } while (0)
; #define PG8_MMA(ai, bj, At, Bt) do { __builtin_amdgcn_s_setprio(1); _Pragma("unroll") for (int m = 0; m < 4; ++m) _Pragma("unroll") for (int n = 0; n < 2; ++n) _Pragma("unroll") for (int k = 0; k < 2; ++k) \
;         acc[ai][bj][m][n] = __builtin_amdgcn_mfma_f32_16x16x32_bf16(Bt[n][k], At[m][k], acc[ai][bj][m][n], 0, 0, 0); __builtin_amdgcn_s_setprio(0); } while (0)
; #define PG8_WAIT_V(n) asm volatile("s_waitcnt vmcnt(" #n ")" ::: "memory")
; #define PG8_WAIT_L(n) asm volatile("s_waitcnt lgkmcnt(" #n ")" ::: "memory")
; #define PG8_BAR __builtin_amdgcn_s_barrier()
; #define PG8_SCHED __builtin_amdgcn_sched_barrier(0)
; template <class Epi, class Sched, bool ALIGN_EPI = false, bool SP2 = false>
; __device__ __forceinline__ void gemm_phase(PG8_LAS unsigned char* lds, const Gemm g, const Sched& S, const Epi& E, int wid_in) {
;     ...
;             PG8_LDB(B0, 1, 0); PG8_LDB(B1, 1, 1); PG8_SCHED; PG8_LDA(At, 1, 0); PG8_STAGE(PG8_SA(0, 1), a2 + hstep, voffA);
;             PG8_WAIT_V(8); PG8_WAIT_L(0); PG8_BAR; PG8_MMA(0, 0, At, B0); PG8_MMA(0, 1, At, B1); PG8_BAR; PG8_SCHED;
	s_setprio 1
	s_add_i32 s40, 0, 0x18000
	s_add_i32 s41, 0, 0x1c000
	v_add_u32_e32 v156, s40, v142
	v_add_u32_e32 v172, s41, v142
	ds_read_b128 v[144:147], v156
	ds_read_b128 v[148:151], v156 offset:1024
	ds_read_b128 v[152:155], v156 offset:2048
	ds_read_b128 v[156:159], v156 offset:3072
	ds_read_b128 v[160:163], v172
	ds_read_b128 v[164:167], v172 offset:1024
	ds_read_b128 v[168:171], v172 offset:2048
	ds_read_b128 v[172:175], v172 offset:3072
	s_add_u32 s28, s28, 0x80000
	s_addc_u32 s29, s29, 0
	s_mov_b32 m0, s36
	v_lshl_add_u64 v[228:229], s[28:29], 0, v[134:135]
	ds_read_b128 v[176:179], v143 offset:32768
	ds_read_b128 v[180:183], v143 offset:33792
	ds_read_b128 v[184:187], v143 offset:34816
	ds_read_b128 v[188:191], v143 offset:35840
	ds_read_b128 v[208:211], v143 offset:36864
	ds_read_b128 v[212:215], v143 offset:37888
	ds_read_b128 v[216:219], v143 offset:38912
	ds_read_b128 v[220:223], v143 offset:39936
	global_load_lds_dwordx4 v[228:229], off
	v_lshl_add_u64 v[228:229], s[28:29], 0, v[132:133]
	s_mov_b32 m0, s37
	s_nop 0
	global_load_lds_dwordx4 v[228:229], off
	s_waitcnt vmcnt(8)
	s_waitcnt lgkmcnt(0)
	s_barrier
	s_setprio 0
	s_waitcnt lgkmcnt(0)
	v_mfma_f32_16x16x32_bf16 v[126:129], v[144:147], v[176:179], v[126:129]
	v_mfma_f32_16x16x32_bf16 v[122:125], v[152:155], v[176:179], v[122:125]
	v_mfma_f32_16x16x32_bf16 v[110:113], v[144:147], v[184:187], v[110:113]
	v_mfma_f32_16x16x32_bf16 v[106:109], v[152:155], v[184:187], v[106:109]
	v_mfma_f32_16x16x32_bf16 v[94:97], v[144:147], v[208:211], v[94:97]
	v_mfma_f32_16x16x32_bf16 v[90:93], v[152:155], v[208:211], v[90:93]
	v_mfma_f32_16x16x32_bf16 v[78:81], v[144:147], v[216:219], v[78:81]
	v_mfma_f32_16x16x32_bf16 v[74:77], v[152:155], v[216:219], v[74:77]
	v_mfma_f32_16x16x32_bf16 v[126:129], v[148:151], v[180:183], v[126:129]
	v_mfma_f32_16x16x32_bf16 v[122:125], v[156:159], v[180:183], v[122:125]
	v_mfma_f32_16x16x32_bf16 v[110:113], v[148:151], v[188:191], v[110:113]
	v_mfma_f32_16x16x32_bf16 v[106:109], v[156:159], v[188:191], v[106:109]
	v_mfma_f32_16x16x32_bf16 v[94:97], v[148:151], v[212:215], v[94:97]
	v_mfma_f32_16x16x32_bf16 v[90:93], v[156:159], v[212:215], v[90:93]
	v_mfma_f32_16x16x32_bf16 v[78:81], v[148:151], v[220:223], v[78:81]
	v_mfma_f32_16x16x32_bf16 v[74:77], v[156:159], v[220:223], v[74:77]
	v_mfma_f32_16x16x32_bf16 v[118:121], v[160:163], v[176:179], v[118:121]
	v_mfma_f32_16x16x32_bf16 v[114:117], v[168:171], v[176:179], v[114:117]
	v_mfma_f32_16x16x32_bf16 v[102:105], v[160:163], v[184:187], v[102:105]
	v_mfma_f32_16x16x32_bf16 v[98:101], v[168:171], v[184:187], v[98:101]
	v_mfma_f32_16x16x32_bf16 v[86:89], v[160:163], v[208:211], v[86:89]
	v_mfma_f32_16x16x32_bf16 v[82:85], v[168:171], v[208:211], v[82:85]
	v_mfma_f32_16x16x32_bf16 v[70:73], v[160:163], v[216:219], v[70:73]
	v_mfma_f32_16x16x32_bf16 v[66:69], v[168:171], v[216:219], v[66:69]
	v_mfma_f32_16x16x32_bf16 v[118:121], v[164:167], v[180:183], v[118:121]
	v_mfma_f32_16x16x32_bf16 v[114:117], v[172:175], v[180:183], v[114:117]
	v_mfma_f32_16x16x32_bf16 v[102:105], v[164:167], v[188:191], v[102:105]
	v_mfma_f32_16x16x32_bf16 v[98:101], v[172:175], v[188:191], v[98:101]
	v_mfma_f32_16x16x32_bf16 v[86:89], v[164:167], v[212:215], v[86:89]
	v_mfma_f32_16x16x32_bf16 v[82:85], v[172:175], v[212:215], v[82:85]
	v_mfma_f32_16x16x32_bf16 v[70:73], v[164:167], v[220:223], v[70:73]
	v_mfma_f32_16x16x32_bf16 v[66:69], v[172:175], v[220:223], v[66:69]
	s_barrier
; #define PG8_STAGE(bufoff, gbase, voff) do { _Pragma("unroll") for (int _i = 0; _i < 2; ++_i) \
;         __builtin_amdgcn_global_load_lds((const unsigned*)((const char*)(gbase) + (voff)[_i]), (PG8_LAS unsigned*)(lds + (bufoff) + ldsw + _i * 8192), 16, 0, 0); } while (0)
; #define PG8_LDA(dst, b, h) do { _Pragma("unroll") for (int m = 0; m < 4; ++m) _Pragma("unroll") for (int k = 0; k < 2; ++k) dst[m][k] = *(const PG8_LAS bf16x8*)(lds + PG8_SA(b, h) + aoff + m * 2048 + k * 1024); } while (0)
; #define PG8_MMA(ai, bj, At, Bt) do { __builtin_amdgcn_s_setprio(1); _Pragma("unroll") for (int m = 0; m < 4; ++m) _Pragma("unroll") for (int n = 0; n < 2; ++n) _Pragma("unroll") for (int k = 0; k < 2; ++k) \
;         acc[ai][bj][m][n] = __builtin_amdgcn_mfma_f32_16x16x32_bf16(Bt[n][k], At[m][k], acc[ai][bj][m][n], 0, 0, 0); __builtin_amdgcn_s_setprio(0); } while (0)
; #define PG8_WAIT_V(n) asm volatile("s_waitcnt vmcnt(" #n ")" ::: "memory")
; #define PG8_WAIT_L(n) asm volatile("s_waitcnt lgkmcnt(" #n ")" ::: "memory")
; #define PG8_BAR __builtin_amdgcn_s_barrier()
; #define PG8_SCHED __builtin_amdgcn_sched_barrier(0)
; template <class Epi, class Sched, bool ALIGN_EPI = false, bool SP2 = false>
; __device__ __forceinline__ void gemm_phase(PG8_LAS unsigned char* lds, const Gemm g, const Sched& S, const Epi& E, int wid_in) {
;     ...
;             PG8_LDA(At, 1, 1); PG8_STAGE(PG8_SB(1, 0), b3, voffB); PG8_STAGE(PG8_SB(1, 1), b3 + hstep, voffB); PG8_STAGE(PG8_SA(1, 0), a3, voffA);
;             PG8_WAIT_V(8); PG8_WAIT_L(0); PG8_BAR; PG8_MMA(1, 0, At, B0); PG8_MMA(1, 1, At, B1); PG8_BAR; PG8_SCHED;
;     ...
;         if constexpr (ALIGN_EPI) { if (wr == 0) PG8_BAR; }
	s_setprio 1
	s_add_i32 s28, s40, s59
	v_lshl_add_u64 v[140:141], v[140:141], 0, s[94:95]
	s_mov_b32 m0, s28
	ds_read_b128 v[176:179], v143 offset:49152
	ds_read_b128 v[180:183], v143 offset:50176
	ds_read_b128 v[184:187], v143 offset:51200
	ds_read_b128 v[188:191], v143 offset:52224
	ds_read_b128 v[208:211], v143 offset:53248
	ds_read_b128 v[212:215], v143 offset:54272
	ds_read_b128 v[216:219], v143 offset:55296
	ds_read_b128 v[220:223], v143 offset:56320
	global_load_lds_dwordx4 v[140:141], off
	s_add_i32 m0, s28, 0x2000
	s_add_u32 s26, s26, 0x80080
	v_lshl_add_u64 v[140:141], v[192:193], 0, s[94:95]
	s_addc_u32 s27, s27, 0
	s_add_i32 s28, s41, s59
	global_load_lds_dwordx4 v[140:141], off
	v_lshl_add_u64 v[140:141], s[26:27], 0, v[0:1]
	s_mov_b32 m0, s28
	s_nop 0
	global_load_lds_dwordx4 v[140:141], off
	v_lshl_add_u64 v[140:141], s[26:27], 0, v[130:131]
	s_add_i32 m0, s28, 0x2000
	s_nop 0
	global_load_lds_dwordx4 v[140:141], off
	v_lshl_add_u64 v[140:141], v[224:225], 0, s[94:95]
	s_mov_b32 m0, s48
	s_nop 0
	global_load_lds_dwordx4 v[140:141], off
	v_lshl_add_u64 v[140:141], v[226:227], 0, s[94:95]
	s_mov_b32 m0, s52
	s_nop 0
	global_load_lds_dwordx4 v[140:141], off
	s_waitcnt vmcnt(8)
	s_waitcnt lgkmcnt(0)
	s_barrier
	s_setprio 0
	s_waitcnt lgkmcnt(0)
	v_mfma_f32_16x16x32_bf16 v[62:65], v[144:147], v[176:179], v[62:65]
	v_mfma_f32_16x16x32_bf16 v[58:61], v[152:155], v[176:179], v[58:61]
	v_mfma_f32_16x16x32_bf16 v[46:49], v[144:147], v[184:187], v[46:49]
	v_mfma_f32_16x16x32_bf16 v[42:45], v[152:155], v[184:187], v[42:45]
	v_mfma_f32_16x16x32_bf16 v[30:33], v[144:147], v[208:211], v[30:33]
	v_mfma_f32_16x16x32_bf16 v[26:29], v[152:155], v[208:211], v[26:29]
	v_mfma_f32_16x16x32_bf16 v[14:17], v[144:147], v[216:219], v[14:17]
	v_mfma_f32_16x16x32_bf16 v[10:13], v[152:155], v[216:219], v[10:13]
	v_mfma_f32_16x16x32_bf16 v[62:65], v[148:151], v[180:183], v[62:65]
	v_mfma_f32_16x16x32_bf16 v[58:61], v[156:159], v[180:183], v[58:61]
	v_mfma_f32_16x16x32_bf16 v[46:49], v[148:151], v[188:191], v[46:49]
	v_mfma_f32_16x16x32_bf16 v[42:45], v[156:159], v[188:191], v[42:45]
	v_mfma_f32_16x16x32_bf16 v[30:33], v[148:151], v[212:215], v[30:33]
	v_mfma_f32_16x16x32_bf16 v[26:29], v[156:159], v[212:215], v[26:29]
	v_mfma_f32_16x16x32_bf16 v[14:17], v[148:151], v[220:223], v[14:17]
	v_mfma_f32_16x16x32_bf16 v[10:13], v[156:159], v[220:223], v[10:13]
	v_mfma_f32_16x16x32_bf16 v[54:57], v[160:163], v[176:179], v[54:57]
	v_mfma_f32_16x16x32_bf16 v[50:53], v[168:171], v[176:179], v[50:53]
	v_mfma_f32_16x16x32_bf16 v[38:41], v[160:163], v[184:187], v[38:41]
	v_mfma_f32_16x16x32_bf16 v[34:37], v[168:171], v[184:187], v[34:37]
	v_mfma_f32_16x16x32_bf16 v[22:25], v[160:163], v[208:211], v[22:25]
	v_mfma_f32_16x16x32_bf16 v[18:21], v[168:171], v[208:211], v[18:21]
	v_mfma_f32_16x16x32_bf16 v[6:9], v[160:163], v[216:219], v[6:9]
	v_mfma_f32_16x16x32_bf16 v[2:5], v[168:171], v[216:219], v[2:5]
	v_mfma_f32_16x16x32_bf16 v[54:57], v[164:167], v[180:183], v[54:57]
	v_mfma_f32_16x16x32_bf16 v[50:53], v[172:175], v[180:183], v[50:53]
	v_mfma_f32_16x16x32_bf16 v[38:41], v[164:167], v[188:191], v[38:41]
	v_mfma_f32_16x16x32_bf16 v[34:37], v[172:175], v[188:191], v[34:37]
	v_mfma_f32_16x16x32_bf16 v[22:25], v[164:167], v[212:215], v[22:25]
	v_mfma_f32_16x16x32_bf16 v[18:21], v[172:175], v[212:215], v[18:21]
	v_mfma_f32_16x16x32_bf16 v[6:9], v[164:167], v[220:223], v[6:9]
	v_mfma_f32_16x16x32_bf16 v[2:5], v[172:175], v[220:223], v[2:5]
	s_barrier
	s_setprio 1
	s_add_i32 s73, s73, 2
	s_add_u32 s72, s72, 0x100
	s_addc_u32 s63, s63, 0
	s_add_u32 s24, s24, 0x100
	s_addc_u32 s25, s25, 0
	s_cmp_gt_u32 s73, 29
	s_cbranch_scc0 .LBB0_1153
	s_setprio 0
	s_and_b64 vcc, exec, s[14:15]
	s_cbranch_vccz .LBB0_1156
	s_barrier

; #define PG8_STAGE(bufoff, gbase, voff) do { _Pragma("unroll") for (int _i = 0; _i < 2; ++_i) \
;         __builtin_amdgcn_global_load_lds((const unsigned*)((const char*)(gbase) + (voff)[_i]), (PG8_LAS unsigned*)(lds + (bufoff) + ldsw + _i * 8192), 16, 0, 0); } while (0)
; #define PG8_LDA(dst, b, h) do { _Pragma("unroll") for (int m = 0; m < 4; ++m) _Pragma("unroll") for (int k = 0; k < 2; ++k) dst[m][k] = *(const PG8_LAS bf16x8*)(lds + PG8_SA(b, h) + aoff + m * 2048 + k * 1024); } while (0)
; #define PG8_LDB(dst, b, h) do { _Pragma("unroll") for (int n = 0; n < 2; ++n) _Pragma("unroll") for (int k = 0; k < 2; ++k) dst[n][k] = *(const PG8_LAS bf16x8*)(lds + PG8_SB(b, h) + boff + n * 2048 + k * 1024); } while (0)
; #define PG8_WAIT_V(n) asm volatile("s_waitcnt vmcnt(" #n ")" ::: "memory")
; #define PG8_WAIT_L(n) asm volatile("s_waitcnt lgkmcnt(" #n ")" ::: "memory")
; template <class Epi, class Sched, bool ALIGN_EPI = false, bool SP2 = false>
; __device__ __forceinline__ void gemm_phase(PG8_LAS unsigned char* lds, const Gemm g, const Sched& S, const Epi& E, int wid_in) {
;     ...
;     for (;;) {
;         const bool has_next = S.next(ui + 1, nxt);
;         const char* nA = has_next ? (const char*)g.A + (size_t)nxt.pm * tstep + (size_t)nxt.kt0 * kstep : cA; const char* nB = has_next ? (const char*)g.Bt + (size_t)nxt.pn * tstep + (size_t)nxt.kt0 * kstep : cB;
;         const int nt = cur.nkt;
;         for (int t = 0; t < nt; t += 2) {
;             const bool last = (t == nt - 2);
;             const char* a1 = cA + (size_t)(t + 1) * kstep;
;             const char* a2 = last ? nA : cA + (size_t)(t + 2) * kstep; const char* b2 = last ? nB : cB + (size_t)(t + 2) * kstep;
;             const char* a3 = a2 + kstep; const char* b3 = b2 + kstep;
;             if (last && has_next) S.a_ready(nxt);
;             if constexpr (SP2) {
;             PG8_LDB(B0, 0, 0); PG8_LDB(B1, 0, 1); PG8_SCHED; PG8_LDA(At, 0, 0); PG8_STAGE(PG8_SA(1, 1), a1 + hstep, voffA);
;             PG8_WAIT_V(8); PG8_WAIT_L(0); PG8_BAR; PG8_MMA(0, 0, At, B0); PG8_MMA(0, 1, At, B1); PG8_BAR; PG8_SCHED;
;     ...
; #pragma unroll
;         for (int a = 0; a < 2; ++a)
; #pragma unroll
;             for (int b = 0; b < 2; ++b)
; #pragma unroll
;                 for (int m = 0; m < 4; ++m)
; #pragma unroll
;                     for (int n = 0; n < 2; ++n) acc[a][b][m][n] = (f32x4){0.f, 0.f, 0.f, 0.f};
.LBB0_1232:
	s_add_i32 s17, s90, -2
	s_add_u32 s19, s30, 0x100
	s_addc_u32 s21, s31, 0
	s_add_u32 s30, s34, 0x200080
	v_mov_b32_e32 v2, 0
	s_addc_u32 s31, s35, 0
	s_mov_b32 s27, 0
	v_mov_b32_e32 v3, v2
	v_mov_b32_e32 v4, v2
	v_mov_b32_e32 v5, v2
	v_mov_b32_e32 v6, v2
	v_mov_b32_e32 v7, v2
	v_mov_b32_e32 v8, v2
	v_mov_b32_e32 v9, v2
	v_mov_b32_e32 v10, v2
	v_mov_b32_e32 v11, v2
	v_mov_b32_e32 v12, v2
	v_mov_b32_e32 v13, v2
	v_mov_b32_e32 v14, v2
	v_mov_b32_e32 v15, v2
	v_mov_b32_e32 v16, v2
	v_mov_b32_e32 v17, v2
	v_mov_b32_e32 v26, v2
	v_mov_b32_e32 v27, v2
	v_mov_b32_e32 v28, v2
	v_mov_b32_e32 v29, v2
	v_mov_b32_e32 v30, v2
	v_mov_b32_e32 v31, v2
	v_mov_b32_e32 v32, v2
	v_mov_b32_e32 v33, v2
	v_mov_b32_e32 v42, v2
	v_mov_b32_e32 v43, v2
	v_mov_b32_e32 v44, v2
	v_mov_b32_e32 v45, v2
	v_mov_b32_e32 v46, v2
	v_mov_b32_e32 v47, v2
	v_mov_b32_e32 v48, v2
	v_mov_b32_e32 v49, v2
	v_mov_b32_e32 v18, v2
	v_mov_b32_e32 v19, v2
	v_mov_b32_e32 v20, v2
	v_mov_b32_e32 v21, v2
	v_mov_b32_e32 v22, v2
	v_mov_b32_e32 v23, v2
	v_mov_b32_e32 v24, v2
	v_mov_b32_e32 v25, v2
	v_mov_b32_e32 v34, v2
	v_mov_b32_e32 v35, v2
	v_mov_b32_e32 v36, v2
	v_mov_b32_e32 v37, v2
	v_mov_b32_e32 v38, v2
	v_mov_b32_e32 v39, v2
	v_mov_b32_e32 v40, v2
	v_mov_b32_e32 v41, v2
	v_mov_b32_e32 v50, v2
	v_mov_b32_e32 v51, v2
	v_mov_b32_e32 v52, v2
	v_mov_b32_e32 v53, v2
	v_mov_b32_e32 v54, v2
	v_mov_b32_e32 v55, v2
	v_mov_b32_e32 v56, v2
	v_mov_b32_e32 v57, v2
	v_mov_b32_e32 v58, v2
	v_mov_b32_e32 v59, v2
	v_mov_b32_e32 v60, v2
	v_mov_b32_e32 v61, v2
	v_mov_b32_e32 v62, v2
	v_mov_b32_e32 v63, v2
	v_mov_b32_e32 v64, v2
	v_mov_b32_e32 v65, v2
	v_mov_b32_e32 v66, v2
	v_mov_b32_e32 v67, v2
	v_mov_b32_e32 v68, v2
	v_mov_b32_e32 v69, v2
	v_mov_b32_e32 v70, v2
	v_mov_b32_e32 v71, v2
	v_mov_b32_e32 v72, v2
	v_mov_b32_e32 v73, v2
	v_mov_b32_e32 v74, v2
	v_mov_b32_e32 v75, v2
	v_mov_b32_e32 v76, v2
	v_mov_b32_e32 v77, v2
	v_mov_b32_e32 v78, v2
	v_mov_b32_e32 v79, v2
	v_mov_b32_e32 v80, v2
	v_mov_b32_e32 v81, v2
	v_mov_b32_e32 v90, v2
	v_mov_b32_e32 v91, v2
	v_mov_b32_e32 v92, v2
	v_mov_b32_e32 v93, v2
	v_mov_b32_e32 v94, v2
	v_mov_b32_e32 v95, v2
	v_mov_b32_e32 v96, v2
	v_mov_b32_e32 v97, v2
	v_mov_b32_e32 v106, v2
	v_mov_b32_e32 v107, v2
	v_mov_b32_e32 v108, v2
	v_mov_b32_e32 v109, v2
	v_mov_b32_e32 v110, v2
	v_mov_b32_e32 v111, v2
	v_mov_b32_e32 v112, v2
	v_mov_b32_e32 v113, v2
	v_mov_b32_e32 v82, v2
	v_mov_b32_e32 v83, v2
	v_mov_b32_e32 v84, v2
	v_mov_b32_e32 v85, v2
	v_mov_b32_e32 v86, v2
	v_mov_b32_e32 v87, v2
	v_mov_b32_e32 v88, v2
	v_mov_b32_e32 v89, v2
	v_mov_b32_e32 v98, v2
	v_mov_b32_e32 v99, v2
	v_mov_b32_e32 v100, v2
	v_mov_b32_e32 v101, v2
	v_mov_b32_e32 v102, v2
	v_mov_b32_e32 v103, v2
	v_mov_b32_e32 v104, v2
	v_mov_b32_e32 v105, v2
	v_mov_b32_e32 v114, v2
	v_mov_b32_e32 v115, v2
	v_mov_b32_e32 v116, v2
	v_mov_b32_e32 v117, v2
	v_mov_b32_e32 v118, v2
	v_mov_b32_e32 v119, v2
	v_mov_b32_e32 v120, v2
	v_mov_b32_e32 v121, v2
	v_mov_b32_e32 v122, v2
	v_mov_b32_e32 v123, v2
	v_mov_b32_e32 v124, v2
	v_mov_b32_e32 v125, v2
	v_mov_b32_e32 v126, v2
	v_mov_b32_e32 v127, v2
	v_mov_b32_e32 v128, v2
	v_mov_b32_e32 v129, v2
	s_setprio 1
.Lprio_skip_5:
.LBB0_1233:
	s_add_i32 s56, s27, 2
	s_add_u32 s34, s30, 0xffe00080
	s_addc_u32 s35, s31, -1
	s_add_i32 s40, 0, 0x10000
	s_cmp_eq_u32 s17, s27
	s_cselect_b32 s37, s23, s35
	s_cselect_b32 s36, s22, s34
	s_cselect_b32 s35, s25, s21
	s_cselect_b32 s34, s24, s19
	s_add_i32 s27, 0, 0x14000
	v_add_u32_e32 v142, s40, v176
	v_add_u32_e32 v168, s27, v176
	ds_read_b128 v[130:133], v142
	ds_read_b128 v[134:137], v142 offset:1024
	ds_read_b128 v[138:141], v142 offset:2048
	ds_read_b128 v[142:145], v142 offset:3072
	ds_read_b128 v[146:149], v168
	ds_read_b128 v[160:163], v168 offset:1024
	ds_read_b128 v[164:167], v168 offset:2048
	ds_read_b128 v[168:171], v168 offset:3072
	v_lshl_add_u64 v[220:221], s[30:31], 0, v[158:159]
	s_add_i32 m0, s29, 0xc000
	ds_read_b128 v[172:175], v177
	ds_read_b128 v[178:181], v177 offset:1024
	ds_read_b128 v[182:185], v177 offset:2048
	ds_read_b128 v[186:189], v177 offset:3072
	ds_read_b128 v[190:193], v177 offset:4096
	ds_read_b128 v[208:211], v177 offset:5120
	ds_read_b128 v[212:215], v177 offset:6144
	ds_read_b128 v[216:219], v177 offset:7168
	global_load_lds_dwordx4 v[220:221], off
	v_lshl_add_u64 v[220:221], s[30:31], 0, v[156:157]
	s_add_i32 m0, s29, 0xe000
	s_nop 0
	global_load_lds_dwordx4 v[220:221], off
	s_waitcnt vmcnt(8)
	s_waitcnt lgkmcnt(0)
	s_barrier
	s_setprio 0
	s_waitcnt lgkmcnt(0)
	v_mfma_f32_16x16x32_bf16 v[126:129], v[130:133], v[172:175], v[126:129]
	v_mfma_f32_16x16x32_bf16 v[122:125], v[138:141], v[172:175], v[122:125]
	v_mfma_f32_16x16x32_bf16 v[118:121], v[130:133], v[182:185], v[118:121]
	v_mfma_f32_16x16x32_bf16 v[114:117], v[138:141], v[182:185], v[114:117]
	v_mfma_f32_16x16x32_bf16 v[102:105], v[130:133], v[190:193], v[102:105]
	v_mfma_f32_16x16x32_bf16 v[98:101], v[138:141], v[190:193], v[98:101]
	v_mfma_f32_16x16x32_bf16 v[86:89], v[130:133], v[212:215], v[86:89]
	v_mfma_f32_16x16x32_bf16 v[82:85], v[138:141], v[212:215], v[82:85]
	v_mfma_f32_16x16x32_bf16 v[126:129], v[134:137], v[178:181], v[126:129]
	v_mfma_f32_16x16x32_bf16 v[122:125], v[142:145], v[178:181], v[122:125]
	v_mfma_f32_16x16x32_bf16 v[118:121], v[134:137], v[186:189], v[118:121]
	v_mfma_f32_16x16x32_bf16 v[114:117], v[142:145], v[186:189], v[114:117]
	v_mfma_f32_16x16x32_bf16 v[102:105], v[134:137], v[208:211], v[102:105]
	v_mfma_f32_16x16x32_bf16 v[98:101], v[142:145], v[208:211], v[98:101]
	v_mfma_f32_16x16x32_bf16 v[86:89], v[134:137], v[216:219], v[86:89]
	v_mfma_f32_16x16x32_bf16 v[82:85], v[142:145], v[216:219], v[82:85]
	v_mfma_f32_16x16x32_bf16 v[110:113], v[146:149], v[172:175], v[110:113]
	v_mfma_f32_16x16x32_bf16 v[106:109], v[164:167], v[172:175], v[106:109]
	v_mfma_f32_16x16x32_bf16 v[94:97], v[146:149], v[182:185], v[94:97]
	v_mfma_f32_16x16x32_bf16 v[90:93], v[164:167], v[182:185], v[90:93]
	v_mfma_f32_16x16x32_bf16 v[78:81], v[146:149], v[190:193], v[78:81]
	v_mfma_f32_16x16x32_bf16 v[74:77], v[164:167], v[190:193], v[74:77]
	v_mfma_f32_16x16x32_bf16 v[70:73], v[146:149], v[212:215], v[70:73]
	v_mfma_f32_16x16x32_bf16 v[66:69], v[164:167], v[212:215], v[66:69]
	v_mfma_f32_16x16x32_bf16 v[110:113], v[160:163], v[178:181], v[110:113]
	v_mfma_f32_16x16x32_bf16 v[106:109], v[168:171], v[178:181], v[106:109]
	v_mfma_f32_16x16x32_bf16 v[94:97], v[160:163], v[186:189], v[94:97]
	v_mfma_f32_16x16x32_bf16 v[90:93], v[168:171], v[186:189], v[90:93]
	v_mfma_f32_16x16x32_bf16 v[78:81], v[160:163], v[208:211], v[78:81]
	v_mfma_f32_16x16x32_bf16 v[74:77], v[168:171], v[208:211], v[74:77]
	v_mfma_f32_16x16x32_bf16 v[70:73], v[160:163], v[216:219], v[70:73]
	v_mfma_f32_16x16x32_bf16 v[66:69], v[168:171], v[216:219], v[66:69]
	s_barrier
; #define PG8_STAGE(bufoff, gbase, voff) do { _Pragma("unroll") for (int _i = 0; _i < 2; ++_i) \
;         __builtin_amdgcn_global_load_lds((const unsigned*)((const char*)(gbase) + (voff)[_i]), (PG8_LAS unsigned*)(lds + (bufoff) + ldsw + _i * 8192), 16, 0, 0); } while (0)
; #define PG8_LDA(dst, b, h) do { _Pragma("unroll") for (int m = 0; m < 4; ++m) _Pragma("unroll") for (int k = 0; k < 2; ++k) dst[m][k] = *(const PG8_LAS bf16x8*)(lds + PG8_SA(b, h) + aoff + m * 2048 + k * 1024); } while (0)
; #define PG8_LDB(dst, b, h) do { _Pragma("unroll") for (int n = 0; n < 2; ++n) _Pragma("unroll") for (int k = 0; k < 2; ++k) dst[n][k] = *(const PG8_LAS bf16x8*)(lds + PG8_SB(b, h) + boff + n * 2048 + k * 1024); } while (0)
; #define PG8_MMA(ai, bj, At, Bt) do { __builtin_amdgcn_s_setprio(1); _Pragma("unroll") for (int m = 0; m < 4; ++m) _Pragma("unroll") for (int n = 0; n < 2; ++n) _Pragma("unroll") for (int k = 0; k < 2; ++k) \
;         acc[ai][bj][m][n] = __builtin_amdgcn_mfma_f32_16x16x32_bf16(Bt[n][k], At[m][k], acc[ai][bj][m][n], 0, 0, 0); __builtin_amdgcn_s_setprio(0); } while (0)
; #define PG8_WAIT_V(n) asm volatile("s_waitcnt vmcnt(" #n ")" ::: "memory")
; #define PG8_WAIT_L(n) asm volatile("s_waitcnt lgkmcnt(" #n ")" ::: "memory")
; #define PG8_BAR __builtin_amdgcn_s_barrier()
; #define PG8_SCHED __builtin_amdgcn_sched_barrier(0)
; template <class Epi, class Sched, bool ALIGN_EPI = false, bool SP2 = false>
; __device__ __forceinline__ void gemm_phase(PG8_LAS unsigned char* lds, const Gemm g, const Sched& S, const Epi& E, int wid_in) {
;     ...
;             PG8_LDA(At, 0, 1); PG8_STAGE(PG8_SB(0, 0), b2, voffB); PG8_STAGE(PG8_SB(0, 1), b2 + hstep, voffB); PG8_STAGE(PG8_SA(0, 0), a2, voffA);
;             PG8_WAIT_V(8); PG8_WAIT_L(0); PG8_BAR; PG8_MMA(1, 0, At, B0); PG8_MMA(1, 1, At, B1); PG8_BAR; PG8_SCHED;
;             PG8_LDB(B0, 1, 0); PG8_LDB(B1, 1, 1); PG8_SCHED; PG8_LDA(At, 1, 0); PG8_STAGE(PG8_SA(0, 1), a2 + hstep, voffA);
	s_setprio 1
	s_add_i32 s40, s40, s59
	v_lshl_add_u64 v[220:221], s[34:35], 0, v[0:1]
	s_mov_b32 m0, s40
	ds_read_b128 v[172:175], v177 offset:16384
	ds_read_b128 v[178:181], v177 offset:17408
	ds_read_b128 v[182:185], v177 offset:18432
	ds_read_b128 v[186:189], v177 offset:19456
	ds_read_b128 v[190:193], v177 offset:20480
	ds_read_b128 v[208:211], v177 offset:21504
	ds_read_b128 v[212:215], v177 offset:22528
	ds_read_b128 v[216:219], v177 offset:23552
	global_load_lds_dwordx4 v[220:221], off
	s_add_i32 m0, s40, 0x2000
	s_add_u32 s40, s34, 0x200000
	v_lshl_add_u64 v[222:223], s[34:35], 0, v[154:155]
	s_addc_u32 s41, s35, 0
	s_add_i32 s27, s27, s59
	global_load_lds_dwordx4 v[222:223], off
	v_lshl_add_u64 v[224:225], s[40:41], 0, v[0:1]
	s_mov_b32 m0, s27
	v_lshl_add_u64 v[226:227], s[36:37], 0, v[152:153]
	global_load_lds_dwordx4 v[224:225], off
	v_lshl_add_u64 v[224:225], s[40:41], 0, v[154:155]
	s_add_i32 m0, s27, 0x2000
	s_nop 0
	global_load_lds_dwordx4 v[224:225], off
	v_lshl_add_u64 v[224:225], s[36:37], 0, v[150:151]
	s_mov_b32 m0, s29
	s_nop 0
	global_load_lds_dwordx4 v[224:225], off
	s_mov_b32 m0, s52
	s_nop 0
	global_load_lds_dwordx4 v[226:227], off
	s_waitcnt vmcnt(8)
	s_waitcnt lgkmcnt(0)
	s_barrier
	s_setprio 0
	s_waitcnt lgkmcnt(0)
	v_mfma_f32_16x16x32_bf16 v[62:65], v[130:133], v[172:175], v[62:65]
	v_mfma_f32_16x16x32_bf16 v[58:61], v[138:141], v[172:175], v[58:61]
	v_mfma_f32_16x16x32_bf16 v[54:57], v[130:133], v[182:185], v[54:57]
	v_mfma_f32_16x16x32_bf16 v[50:53], v[138:141], v[182:185], v[50:53]
	v_mfma_f32_16x16x32_bf16 v[38:41], v[130:133], v[190:193], v[38:41]
	v_mfma_f32_16x16x32_bf16 v[34:37], v[138:141], v[190:193], v[34:37]
	v_mfma_f32_16x16x32_bf16 v[22:25], v[130:133], v[212:215], v[22:25]
	v_mfma_f32_16x16x32_bf16 v[18:21], v[138:141], v[212:215], v[18:21]
	v_mfma_f32_16x16x32_bf16 v[62:65], v[134:137], v[178:181], v[62:65]
	v_mfma_f32_16x16x32_bf16 v[58:61], v[142:145], v[178:181], v[58:61]
	v_mfma_f32_16x16x32_bf16 v[54:57], v[134:137], v[186:189], v[54:57]
	v_mfma_f32_16x16x32_bf16 v[50:53], v[142:145], v[186:189], v[50:53]
	v_mfma_f32_16x16x32_bf16 v[38:41], v[134:137], v[208:211], v[38:41]
	v_mfma_f32_16x16x32_bf16 v[34:37], v[142:145], v[208:211], v[34:37]
	v_mfma_f32_16x16x32_bf16 v[22:25], v[134:137], v[216:219], v[22:25]
	v_mfma_f32_16x16x32_bf16 v[18:21], v[142:145], v[216:219], v[18:21]
	v_mfma_f32_16x16x32_bf16 v[46:49], v[146:149], v[172:175], v[46:49]
	v_mfma_f32_16x16x32_bf16 v[42:45], v[164:167], v[172:175], v[42:45]
	v_mfma_f32_16x16x32_bf16 v[30:33], v[146:149], v[182:185], v[30:33]
	v_mfma_f32_16x16x32_bf16 v[26:29], v[164:167], v[182:185], v[26:29]
	v_mfma_f32_16x16x32_bf16 v[14:17], v[146:149], v[190:193], v[14:17]
	v_mfma_f32_16x16x32_bf16 v[10:13], v[164:167], v[190:193], v[10:13]
	v_mfma_f32_16x16x32_bf16 v[6:9], v[146:149], v[212:215], v[6:9]
	v_mfma_f32_16x16x32_bf16 v[2:5], v[164:167], v[212:215], v[2:5]
	v_mfma_f32_16x16x32_bf16 v[46:49], v[160:163], v[178:181], v[46:49]
	v_mfma_f32_16x16x32_bf16 v[42:45], v[168:171], v[178:181], v[42:45]
	v_mfma_f32_16x16x32_bf16 v[30:33], v[160:163], v[186:189], v[30:33]
	v_mfma_f32_16x16x32_bf16 v[26:29], v[168:171], v[186:189], v[26:29]
	v_mfma_f32_16x16x32_bf16 v[14:17], v[160:163], v[208:211], v[14:17]
	v_mfma_f32_16x16x32_bf16 v[10:13], v[168:171], v[208:211], v[10:13]
	v_mfma_f32_16x16x32_bf16 v[6:9], v[160:163], v[216:219], v[6:9]
	v_mfma_f32_16x16x32_bf16 v[2:5], v[168:171], v[216:219], v[2:5]
	s_barrier
	s_setprio 1
	s_add_i32 s27, 0, 0x18000
	s_add_i32 s40, 0, 0x1c000
	v_add_u32_e32 v142, s27, v176
	v_add_u32_e32 v168, s40, v176
	ds_read_b128 v[130:133], v142
	ds_read_b128 v[134:137], v142 offset:1024
	ds_read_b128 v[138:141], v142 offset:2048
	ds_read_b128 v[142:145], v142 offset:3072
	ds_read_b128 v[146:149], v168
	ds_read_b128 v[160:163], v168 offset:1024
	ds_read_b128 v[164:167], v168 offset:2048
	ds_read_b128 v[168:171], v168 offset:3072
	s_add_u32 s36, s36, 0x200000
	s_addc_u32 s37, s37, 0
	s_mov_b32 m0, s53
	v_lshl_add_u64 v[228:229], s[36:37], 0, v[150:151]
	ds_read_b128 v[172:175], v177 offset:32768
	ds_read_b128 v[178:181], v177 offset:33792
	ds_read_b128 v[182:185], v177 offset:34816
	ds_read_b128 v[186:189], v177 offset:35840
	ds_read_b128 v[190:193], v177 offset:36864
	ds_read_b128 v[208:211], v177 offset:37888
	ds_read_b128 v[212:215], v177 offset:38912
	ds_read_b128 v[216:219], v177 offset:39936
	global_load_lds_dwordx4 v[228:229], off
	v_lshl_add_u64 v[228:229], s[36:37], 0, v[152:153]
	s_mov_b32 m0, s61
	s_nop 0
	global_load_lds_dwordx4 v[228:229], off
	s_waitcnt vmcnt(8)
	s_waitcnt lgkmcnt(0)
	s_barrier
; #define PG8_STAGE(bufoff, gbase, voff) do { _Pragma("unroll") for (int _i = 0; _i < 2; ++_i) \
;         __builtin_amdgcn_global_load_lds((const unsigned*)((const char*)(gbase) + (voff)[_i]), (PG8_LAS unsigned*)(lds + (bufoff) + ldsw + _i * 8192), 16, 0, 0); } while (0)
; #define PG8_LDA(dst, b, h) do { _Pragma("unroll") for (int m = 0; m < 4; ++m) _Pragma("unroll") for (int k = 0; k < 2; ++k) dst[m][k] = *(const PG8_LAS bf16x8*)(lds + PG8_SA(b, h) + aoff + m * 2048 + k * 1024); } while (0)
; #define PG8_MMA(ai, bj, At, Bt) do { __builtin_amdgcn_s_setprio(1); _Pragma("unroll") for (int m = 0; m < 4; ++m) _Pragma("unroll") for (int n = 0; n < 2; ++n) _Pragma("unroll") for (int k = 0; k < 2; ++k) \
;         acc[ai][bj][m][n] = __builtin_amdgcn_mfma_f32_16x16x32_bf16(Bt[n][k], At[m][k], acc[ai][bj][m][n], 0, 0, 0); __builtin_amdgcn_s_setprio(0); } while (0)
; #define PG8_WAIT_V(n) asm volatile("s_waitcnt vmcnt(" #n ")" ::: "memory")
; #define PG8_WAIT_L(n) asm volatile("s_waitcnt lgkmcnt(" #n ")" ::: "memory")
; #define PG8_BAR __builtin_amdgcn_s_barrier()
; #define PG8_SCHED __builtin_amdgcn_sched_barrier(0)
; template <class Epi, class Sched, bool ALIGN_EPI = false, bool SP2 = false>
; __device__ __forceinline__ void gemm_phase(PG8_LAS unsigned char* lds, const Gemm g, const Sched& S, const Epi& E, int wid_in) {
;     ...
;             PG8_WAIT_V(8); PG8_WAIT_L(0); PG8_BAR; PG8_MMA(0, 0, At, B0); PG8_MMA(0, 1, At, B1); PG8_BAR; PG8_SCHED;
;             PG8_LDA(At, 1, 1); PG8_STAGE(PG8_SB(1, 0), b3, voffB); PG8_STAGE(PG8_SB(1, 1), b3 + hstep, voffB); PG8_STAGE(PG8_SA(1, 0), a3, voffA);
;             PG8_WAIT_V(8); PG8_WAIT_L(0); PG8_BAR; PG8_MMA(1, 0, At, B0); PG8_MMA(1, 1, At, B1); PG8_BAR; PG8_SCHED;
;     ...
;         if constexpr (ALIGN_EPI) { if (wr == 0) PG8_BAR; }
	s_setprio 0
	s_waitcnt lgkmcnt(0)
	v_mfma_f32_16x16x32_bf16 v[126:129], v[130:133], v[172:175], v[126:129]
	v_mfma_f32_16x16x32_bf16 v[122:125], v[138:141], v[172:175], v[122:125]
	v_mfma_f32_16x16x32_bf16 v[118:121], v[130:133], v[182:185], v[118:121]
	v_mfma_f32_16x16x32_bf16 v[114:117], v[138:141], v[182:185], v[114:117]
	v_mfma_f32_16x16x32_bf16 v[102:105], v[130:133], v[190:193], v[102:105]
	v_mfma_f32_16x16x32_bf16 v[98:101], v[138:141], v[190:193], v[98:101]
	v_mfma_f32_16x16x32_bf16 v[86:89], v[130:133], v[212:215], v[86:89]
	v_mfma_f32_16x16x32_bf16 v[82:85], v[138:141], v[212:215], v[82:85]
	v_mfma_f32_16x16x32_bf16 v[126:129], v[134:137], v[178:181], v[126:129]
	v_mfma_f32_16x16x32_bf16 v[122:125], v[142:145], v[178:181], v[122:125]
	v_mfma_f32_16x16x32_bf16 v[118:121], v[134:137], v[186:189], v[118:121]
	v_mfma_f32_16x16x32_bf16 v[114:117], v[142:145], v[186:189], v[114:117]
	v_mfma_f32_16x16x32_bf16 v[102:105], v[134:137], v[208:211], v[102:105]
	v_mfma_f32_16x16x32_bf16 v[98:101], v[142:145], v[208:211], v[98:101]
	v_mfma_f32_16x16x32_bf16 v[86:89], v[134:137], v[216:219], v[86:89]
	v_mfma_f32_16x16x32_bf16 v[82:85], v[142:145], v[216:219], v[82:85]
	v_mfma_f32_16x16x32_bf16 v[110:113], v[146:149], v[172:175], v[110:113]
	v_mfma_f32_16x16x32_bf16 v[106:109], v[164:167], v[172:175], v[106:109]
	v_mfma_f32_16x16x32_bf16 v[94:97], v[146:149], v[182:185], v[94:97]
	v_mfma_f32_16x16x32_bf16 v[90:93], v[164:167], v[182:185], v[90:93]
	v_mfma_f32_16x16x32_bf16 v[78:81], v[146:149], v[190:193], v[78:81]
	v_mfma_f32_16x16x32_bf16 v[74:77], v[164:167], v[190:193], v[74:77]
	v_mfma_f32_16x16x32_bf16 v[70:73], v[146:149], v[212:215], v[70:73]
	v_mfma_f32_16x16x32_bf16 v[66:69], v[164:167], v[212:215], v[66:69]
	v_mfma_f32_16x16x32_bf16 v[110:113], v[160:163], v[178:181], v[110:113]
	v_mfma_f32_16x16x32_bf16 v[106:109], v[168:171], v[178:181], v[106:109]
	v_mfma_f32_16x16x32_bf16 v[94:97], v[160:163], v[186:189], v[94:97]
	v_mfma_f32_16x16x32_bf16 v[90:93], v[168:171], v[186:189], v[90:93]
	v_mfma_f32_16x16x32_bf16 v[78:81], v[160:163], v[208:211], v[78:81]
	v_mfma_f32_16x16x32_bf16 v[74:77], v[168:171], v[208:211], v[74:77]
	v_mfma_f32_16x16x32_bf16 v[70:73], v[160:163], v[216:219], v[70:73]
	v_mfma_f32_16x16x32_bf16 v[66:69], v[168:171], v[216:219], v[66:69]
	s_barrier
	s_setprio 1
	s_add_i32 s27, s27, s59
	v_lshl_add_u64 v[220:221], v[220:221], 0, s[94:95]
	s_mov_b32 m0, s27
	ds_read_b128 v[172:175], v177 offset:49152
	ds_read_b128 v[178:181], v177 offset:50176
	ds_read_b128 v[182:185], v177 offset:51200
	ds_read_b128 v[186:189], v177 offset:52224
	ds_read_b128 v[190:193], v177 offset:53248
	ds_read_b128 v[208:211], v177 offset:54272
	ds_read_b128 v[212:215], v177 offset:55296
	ds_read_b128 v[216:219], v177 offset:56320
	global_load_lds_dwordx4 v[220:221], off
	s_add_i32 m0, s27, 0x2000
	s_add_u32 s34, s34, 0x200080
	v_lshl_add_u64 v[220:221], v[222:223], 0, s[94:95]
	s_addc_u32 s35, s35, 0
	s_add_i32 s27, s40, s59
	global_load_lds_dwordx4 v[220:221], off
	v_lshl_add_u64 v[220:221], s[34:35], 0, v[0:1]
	s_mov_b32 m0, s27
	s_nop 0
	global_load_lds_dwordx4 v[220:221], off
	v_lshl_add_u64 v[220:221], s[34:35], 0, v[154:155]
	s_add_i32 m0, s27, 0x2000
	s_nop 0
	global_load_lds_dwordx4 v[220:221], off
	v_lshl_add_u64 v[220:221], v[224:225], 0, s[94:95]
	s_mov_b32 m0, s73
	s_nop 0
	global_load_lds_dwordx4 v[220:221], off
	v_lshl_add_u64 v[220:221], v[226:227], 0, s[94:95]
	s_mov_b32 m0, s80
	s_nop 0
	global_load_lds_dwordx4 v[220:221], off
	s_waitcnt vmcnt(8)
	s_waitcnt lgkmcnt(0)
	s_barrier
	s_setprio 0
	s_waitcnt lgkmcnt(0)
	v_mfma_f32_16x16x32_bf16 v[62:65], v[130:133], v[172:175], v[62:65]
	v_mfma_f32_16x16x32_bf16 v[58:61], v[138:141], v[172:175], v[58:61]
	v_mfma_f32_16x16x32_bf16 v[54:57], v[130:133], v[182:185], v[54:57]
	v_mfma_f32_16x16x32_bf16 v[50:53], v[138:141], v[182:185], v[50:53]
	v_mfma_f32_16x16x32_bf16 v[38:41], v[130:133], v[190:193], v[38:41]
	v_mfma_f32_16x16x32_bf16 v[34:37], v[138:141], v[190:193], v[34:37]
	v_mfma_f32_16x16x32_bf16 v[22:25], v[130:133], v[212:215], v[22:25]
	v_mfma_f32_16x16x32_bf16 v[18:21], v[138:141], v[212:215], v[18:21]
	v_mfma_f32_16x16x32_bf16 v[62:65], v[134:137], v[178:181], v[62:65]
	v_mfma_f32_16x16x32_bf16 v[58:61], v[142:145], v[178:181], v[58:61]
	v_mfma_f32_16x16x32_bf16 v[54:57], v[134:137], v[186:189], v[54:57]
	v_mfma_f32_16x16x32_bf16 v[50:53], v[142:145], v[186:189], v[50:53]
	v_mfma_f32_16x16x32_bf16 v[38:41], v[134:137], v[208:211], v[38:41]
	v_mfma_f32_16x16x32_bf16 v[34:37], v[142:145], v[208:211], v[34:37]
	v_mfma_f32_16x16x32_bf16 v[22:25], v[134:137], v[216:219], v[22:25]
	v_mfma_f32_16x16x32_bf16 v[18:21], v[142:145], v[216:219], v[18:21]
	v_mfma_f32_16x16x32_bf16 v[46:49], v[146:149], v[172:175], v[46:49]
	v_mfma_f32_16x16x32_bf16 v[42:45], v[164:167], v[172:175], v[42:45]
	v_mfma_f32_16x16x32_bf16 v[30:33], v[146:149], v[182:185], v[30:33]
	v_mfma_f32_16x16x32_bf16 v[26:29], v[164:167], v[182:185], v[26:29]
	v_mfma_f32_16x16x32_bf16 v[14:17], v[146:149], v[190:193], v[14:17]
	v_mfma_f32_16x16x32_bf16 v[10:13], v[164:167], v[190:193], v[10:13]
	v_mfma_f32_16x16x32_bf16 v[6:9], v[146:149], v[212:215], v[6:9]
	v_mfma_f32_16x16x32_bf16 v[2:5], v[164:167], v[212:215], v[2:5]
	v_mfma_f32_16x16x32_bf16 v[46:49], v[160:163], v[178:181], v[46:49]
	v_mfma_f32_16x16x32_bf16 v[42:45], v[168:171], v[178:181], v[42:45]
	v_mfma_f32_16x16x32_bf16 v[30:33], v[160:163], v[186:189], v[30:33]
	v_mfma_f32_16x16x32_bf16 v[26:29], v[168:171], v[186:189], v[26:29]
	v_mfma_f32_16x16x32_bf16 v[14:17], v[160:163], v[208:211], v[14:17]
	v_mfma_f32_16x16x32_bf16 v[10:13], v[168:171], v[208:211], v[10:13]
	v_mfma_f32_16x16x32_bf16 v[6:9], v[160:163], v[216:219], v[6:9]
	v_mfma_f32_16x16x32_bf16 v[2:5], v[168:171], v[216:219], v[2:5]
	s_barrier
	s_setprio 1
	s_add_u32 s19, s19, 0x100
	s_addc_u32 s21, s21, 0
	s_add_u32 s30, s30, 0x100
	s_addc_u32 s31, s31, 0
	s_cmp_ge_i32 s56, s90
	s_mov_b32 s27, s56
	s_cbranch_scc0 .LBB0_1233
	s_setprio 0
	s_and_b64 vcc, exec, s[14:15]
	s_cbranch_vccz .LBB0_1236
	s_barrier
